# adds: K-loop LDS-DMA addressing in SGPR-base + VGPR-offset form (no VALU address arithmetic in the loader half), LDS read bases loop-invariant
# speedup vs baseline: 1.0209x; 1.0052x over previous
; #define PG8_STAGE(bufoff, gbase, voff) do { _Pragma("unroll") for (int _i = 0; _i < 2; ++_i) \
;         __builtin_amdgcn_global_load_lds((const unsigned*)((const char*)(gbase) + (voff)[_i]), (PG8_LAS unsigned*)(lds + (bufoff) + ldsw + _i * 8192), 16, 0, 0); } while (0)
; #define PG8_LDA(dst, b, h) do { _Pragma("unroll") for (int m = 0; m < 4; ++m) _Pragma("unroll") for (int k = 0; k < 2; ++k) dst[m][k] = *(const PG8_LAS bf16x8*)(lds + PG8_SA(b, h) + aoff + m * 2048 + k * 1024); } while (0)
; #define PG8_LDB(dst, b, h) do { _Pragma("unroll") for (int n = 0; n < 2; ++n) _Pragma("unroll") for (int k = 0; k < 2; ++k) dst[n][k] = *(const PG8_LAS bf16x8*)(lds + PG8_SB(b, h) + boff + n * 2048 + k * 1024); } while (0)
; #define PG8_WAIT_V(n) asm volatile("s_waitcnt vmcnt(" #n ")" ::: "memory")
; #define PG8_WAIT_L(n) asm volatile("s_waitcnt lgkmcnt(" #n ")" ::: "memory")
; #define PG8_BAR __builtin_amdgcn_s_barrier()
; #define PG8_SCHED __builtin_amdgcn_sched_barrier(0)
; template <class Epi, class Sched, bool ALIGN_EPI = false, bool SP2 = false>
; __device__ __forceinline__ void gemm_phase(PG8_LAS unsigned char* lds, const Gemm g, const Sched& S, const Epi& E) {
;     ...
;         const char* nA = has_next ? (const char*)g.A + (size_t)nxt.pm * tstep : cA; const char* nB = has_next ? (const char*)g.Bt + (size_t)nxt.pn * tstep : cB;
;         for (int t = 0; t < nt; t += 2) {
;             const bool last = (t == nt - 2);
;             const char* a1 = cA + (size_t)(t + 1) * kstep;
;             const char* a2 = last ? nA : cA + (size_t)(t + 2) * kstep; const char* b2 = last ? nB : cB + (size_t)(t + 2) * kstep;
;             const char* a3 = a2 + kstep; const char* b3 = b2 + kstep;
;             if (last && has_next) S.a_ready(nxt);
;             if constexpr (SP2) {
;             PG8_LDB(B0, 0, 0); PG8_LDB(B1, 0, 1); PG8_SCHED; PG8_LDA(At, 0, 0); PG8_STAGE(PG8_SA(1, 1), a1 + hstep, voffA);
;             PG8_WAIT_V(8); PG8_WAIT_L(0); PG8_BAR; PG8_MMA(0, 0, At, B0); PG8_MMA(0, 1, At, B1); PG8_BAR; PG8_SCHED;
;     ...
;         for (int a = 0; a < 2; ++a)
; #pragma unroll
;             for (int b = 0; b < 2; ++b)
; #pragma unroll
;                 for (int m = 0; m < 4; ++m)
; #pragma unroll
;                     for (int n = 0; n < 2; ++n) acc[a][b][m][n] = (f32x4){0.f, 0.f, 0.f, 0.f};
.LBB0_135:
	s_ashr_i32 s55, s54, 31
	s_lshl_b64 s[26:27], s[54:55], 19
	s_add_u32 s56, s96, s26
	s_addc_u32 s57, s97, s27
	s_and_b64 s[26:27], s[0:1], exec
	s_cselect_b32 s5, s57, s63
	s_cselect_b32 s26, s56, s62
	s_ashr_i32 s53, s52, 31
	s_lshl_b64 s[58:59], s[52:53], 19
	s_add_u32 s58, s24, s58
	s_addc_u32 s59, s25, s59
	s_and_b64 s[70:71], s[0:1], exec
	s_cselect_b32 s27, s59, s65
	s_cselect_b32 s53, s58, s64
	s_add_u32 s62, s62, 0x40080
	s_addc_u32 s63, s63, 0
	s_add_u32 s55, s64, 0x100
	v_mov_b32_e32 v0, 0
	s_addc_u32 s75, s65, 0
	s_mov_b32 s76, -2
	v_mov_b32_e32 v1, v0
	v_mov_b32_e32 v2, v0
	v_mov_b32_e32 v3, v0
	v_mov_b32_e32 v4, v0
	v_mov_b32_e32 v5, v0
	v_mov_b32_e32 v6, v0
	v_mov_b32_e32 v7, v0
	v_mov_b32_e32 v16, v0
	v_mov_b32_e32 v17, v0
	v_mov_b32_e32 v18, v0
	v_mov_b32_e32 v19, v0
	v_mov_b32_e32 v20, v0
	v_mov_b32_e32 v21, v0
	v_mov_b32_e32 v22, v0
	v_mov_b32_e32 v23, v0
	v_mov_b32_e32 v32, v0
	v_mov_b32_e32 v33, v0
	v_mov_b32_e32 v34, v0
	v_mov_b32_e32 v35, v0
	v_mov_b32_e32 v36, v0
	v_mov_b32_e32 v37, v0
	v_mov_b32_e32 v38, v0
	v_mov_b32_e32 v39, v0
	v_mov_b32_e32 v48, v0
	v_mov_b32_e32 v49, v0
	v_mov_b32_e32 v50, v0
	v_mov_b32_e32 v51, v0
	v_mov_b32_e32 v52, v0
	v_mov_b32_e32 v53, v0
	v_mov_b32_e32 v54, v0
	v_mov_b32_e32 v55, v0
	v_mov_b32_e32 v8, v0
	v_mov_b32_e32 v9, v0
	v_mov_b32_e32 v10, v0
	v_mov_b32_e32 v11, v0
	v_mov_b32_e32 v12, v0
	v_mov_b32_e32 v13, v0
	v_mov_b32_e32 v14, v0
	v_mov_b32_e32 v15, v0
	v_mov_b32_e32 v24, v0
	v_mov_b32_e32 v25, v0
	v_mov_b32_e32 v26, v0
	v_mov_b32_e32 v27, v0
	v_mov_b32_e32 v28, v0
	v_mov_b32_e32 v29, v0
	v_mov_b32_e32 v30, v0
	v_mov_b32_e32 v31, v0
	v_mov_b32_e32 v40, v0
	v_mov_b32_e32 v41, v0
	v_mov_b32_e32 v42, v0
	v_mov_b32_e32 v43, v0
	v_mov_b32_e32 v44, v0
	v_mov_b32_e32 v45, v0
	v_mov_b32_e32 v46, v0
	v_mov_b32_e32 v47, v0
	v_mov_b32_e32 v56, v0
	v_mov_b32_e32 v57, v0
	v_mov_b32_e32 v58, v0
	v_mov_b32_e32 v59, v0
	v_mov_b32_e32 v60, v0
	v_mov_b32_e32 v61, v0
	v_mov_b32_e32 v62, v0
	v_mov_b32_e32 v63, v0
	v_mov_b32_e32 v64, v0
	v_mov_b32_e32 v65, v0
	v_mov_b32_e32 v66, v0
	v_mov_b32_e32 v67, v0
	v_mov_b32_e32 v68, v0
	v_mov_b32_e32 v69, v0
	v_mov_b32_e32 v70, v0
	v_mov_b32_e32 v71, v0
	v_mov_b32_e32 v80, v0
	v_mov_b32_e32 v81, v0
	v_mov_b32_e32 v82, v0
	v_mov_b32_e32 v83, v0
	v_mov_b32_e32 v84, v0
	v_mov_b32_e32 v85, v0
	v_mov_b32_e32 v86, v0
	v_mov_b32_e32 v87, v0
	v_mov_b32_e32 v96, v0
	v_mov_b32_e32 v97, v0
	v_mov_b32_e32 v98, v0
	v_mov_b32_e32 v99, v0
	v_mov_b32_e32 v100, v0
	v_mov_b32_e32 v101, v0
	v_mov_b32_e32 v102, v0
	v_mov_b32_e32 v103, v0
	v_mov_b32_e32 v112, v0
	v_mov_b32_e32 v113, v0
	v_mov_b32_e32 v114, v0
	v_mov_b32_e32 v115, v0
	v_mov_b32_e32 v116, v0
	v_mov_b32_e32 v117, v0
	v_mov_b32_e32 v118, v0
	v_mov_b32_e32 v119, v0
	v_mov_b32_e32 v72, v0
	v_mov_b32_e32 v73, v0
	v_mov_b32_e32 v74, v0
	v_mov_b32_e32 v75, v0
	v_mov_b32_e32 v76, v0
	v_mov_b32_e32 v77, v0
	v_mov_b32_e32 v78, v0
	v_mov_b32_e32 v79, v0
	v_mov_b32_e32 v88, v0
	v_mov_b32_e32 v89, v0
	v_mov_b32_e32 v90, v0
	v_mov_b32_e32 v91, v0
	v_mov_b32_e32 v92, v0
	v_mov_b32_e32 v93, v0
	v_mov_b32_e32 v94, v0
	v_mov_b32_e32 v95, v0
	v_mov_b32_e32 v104, v0
	v_mov_b32_e32 v105, v0
	v_mov_b32_e32 v106, v0
	v_mov_b32_e32 v107, v0
	v_mov_b32_e32 v108, v0
	v_mov_b32_e32 v109, v0
	v_mov_b32_e32 v110, v0
	v_mov_b32_e32 v111, v0
	v_mov_b32_e32 v120, v0
	v_mov_b32_e32 v121, v0
	v_mov_b32_e32 v122, v0
	v_mov_b32_e32 v123, v0
	v_mov_b32_e32 v124, v0
	v_mov_b32_e32 v125, v0
	v_mov_b32_e32 v126, v0
	v_mov_b32_e32 v127, v0
	v_add_u32_e32 v240, 0x18000, v149
	v_add_u32_e32 v241, 0x1c000, v149
.LBB0_136:
	ds_read_b128 v[158:161], v152
	ds_read_b128 v[162:165], v152 offset:1024
	ds_read_b128 v[166:169], v152 offset:2048
	ds_read_b128 v[170:173], v152 offset:3072
	ds_read_b128 v[174:177], v153
	ds_read_b128 v[178:181], v153 offset:1024
	ds_read_b128 v[182:185], v153 offset:2048
	ds_read_b128 v[186:189], v153 offset:3072
	s_add_u32 s64, s62, 0xfffc0080
	s_addc_u32 s65, s63, -1
	s_cmp_eq_u32 s76, 12
	s_cselect_b32 s71, s5, s65
	s_cselect_b32 s70, s26, s64
	s_cselect_b32 s65, s27, s75
	s_cselect_b32 s64, s53, s55
	s_add_i32 m0, s61, 0xc000
	ds_read_b128 v[190:193], v154
	ds_read_b128 v[194:197], v154 offset:1024
	ds_read_b128 v[198:201], v154 offset:2048
	ds_read_b128 v[206:209], v154 offset:3072
	ds_read_b128 v[210:213], v154 offset:4096
	ds_read_b128 v[214:217], v154 offset:5120
	ds_read_b128 v[218:221], v154 offset:6144
	ds_read_b128 v[222:225], v154 offset:7168
	global_load_lds_dwordx4 v138, s[62:63]
	s_add_i32 m0, s61, 0xe000
	s_nop 0
	global_load_lds_dwordx4 v140, s[62:63]
	s_waitcnt vmcnt(8)
	s_waitcnt lgkmcnt(0)
	s_setprio 1
	s_barrier
; #define PG8_STAGE(bufoff, gbase, voff) do { _Pragma("unroll") for (int _i = 0; _i < 2; ++_i) \
;         __builtin_amdgcn_global_load_lds((const unsigned*)((const char*)(gbase) + (voff)[_i]), (PG8_LAS unsigned*)(lds + (bufoff) + ldsw + _i * 8192), 16, 0, 0); } while (0)
; #define PG8_LDA(dst, b, h) do { _Pragma("unroll") for (int m = 0; m < 4; ++m) _Pragma("unroll") for (int k = 0; k < 2; ++k) dst[m][k] = *(const PG8_LAS bf16x8*)(lds + PG8_SA(b, h) + aoff + m * 2048 + k * 1024); } while (0)
; #define PG8_MMA(ai, bj, At, Bt) do { __builtin_amdgcn_s_setprio(1); _Pragma("unroll") for (int m = 0; m < 4; ++m) _Pragma("unroll") for (int n = 0; n < 2; ++n) _Pragma("unroll") for (int k = 0; k < 2; ++k) \
;         acc[ai][bj][m][n] = __builtin_amdgcn_mfma_f32_16x16x32_bf16(Bt[n][k], At[m][k], acc[ai][bj][m][n], 0, 0, 0); __builtin_amdgcn_s_setprio(0); } while (0)
; #define PG8_WAIT_V(n) asm volatile("s_waitcnt vmcnt(" #n ")" ::: "memory")
; #define PG8_WAIT_L(n) asm volatile("s_waitcnt lgkmcnt(" #n ")" ::: "memory")
; #define PG8_BAR __builtin_amdgcn_s_barrier()
; #define PG8_SCHED __builtin_amdgcn_sched_barrier(0)
; template <class Epi, class Sched, bool ALIGN_EPI = false, bool SP2 = false>
; __device__ __forceinline__ void gemm_phase(PG8_LAS unsigned char* lds, const Gemm g, const Sched& S, const Epi& E) {
;     ...
;             PG8_WAIT_V(8); PG8_WAIT_L(0); PG8_BAR; PG8_MMA(0, 0, At, B0); PG8_MMA(0, 1, At, B1); PG8_BAR; PG8_SCHED;
;             PG8_LDA(At, 0, 1); PG8_STAGE(PG8_SB(0, 0), b2, voffB); PG8_STAGE(PG8_SB(0, 1), b2 + hstep, voffB); PG8_STAGE(PG8_SA(0, 0), a2, voffA);
;             PG8_WAIT_V(8); PG8_WAIT_L(0); PG8_BAR; PG8_MMA(1, 0, At, B0); PG8_MMA(1, 1, At, B1); PG8_BAR; PG8_SCHED;
	v_mfma_f32_16x16x32_bf16 v[124:127], v[158:161], v[190:193], v[124:127]
	v_mfma_f32_16x16x32_bf16 v[120:123], v[166:169], v[190:193], v[120:123]
	v_mfma_f32_16x16x32_bf16 v[108:111], v[158:161], v[198:201], v[108:111]
	v_mfma_f32_16x16x32_bf16 v[104:107], v[166:169], v[198:201], v[104:107]
	v_mfma_f32_16x16x32_bf16 v[92:95], v[158:161], v[210:213], v[92:95]
	v_mfma_f32_16x16x32_bf16 v[88:91], v[166:169], v[210:213], v[88:91]
	v_mfma_f32_16x16x32_bf16 v[76:79], v[158:161], v[218:221], v[76:79]
	v_mfma_f32_16x16x32_bf16 v[72:75], v[166:169], v[218:221], v[72:75]
	v_mfma_f32_16x16x32_bf16 v[124:127], v[162:165], v[194:197], v[124:127]
	v_mfma_f32_16x16x32_bf16 v[120:123], v[170:173], v[194:197], v[120:123]
	v_mfma_f32_16x16x32_bf16 v[108:111], v[162:165], v[206:209], v[108:111]
	v_mfma_f32_16x16x32_bf16 v[104:107], v[170:173], v[206:209], v[104:107]
	v_mfma_f32_16x16x32_bf16 v[92:95], v[162:165], v[214:217], v[92:95]
	v_mfma_f32_16x16x32_bf16 v[88:91], v[170:173], v[214:217], v[88:91]
	v_mfma_f32_16x16x32_bf16 v[76:79], v[162:165], v[222:225], v[76:79]
	v_mfma_f32_16x16x32_bf16 v[72:75], v[170:173], v[222:225], v[72:75]
	v_mfma_f32_16x16x32_bf16 v[116:119], v[174:177], v[190:193], v[116:119]
	v_mfma_f32_16x16x32_bf16 v[112:115], v[182:185], v[190:193], v[112:115]
	v_mfma_f32_16x16x32_bf16 v[100:103], v[174:177], v[198:201], v[100:103]
	v_mfma_f32_16x16x32_bf16 v[96:99], v[182:185], v[198:201], v[96:99]
	v_mfma_f32_16x16x32_bf16 v[84:87], v[174:177], v[210:213], v[84:87]
	v_mfma_f32_16x16x32_bf16 v[80:83], v[182:185], v[210:213], v[80:83]
	v_mfma_f32_16x16x32_bf16 v[68:71], v[174:177], v[218:221], v[68:71]
	v_mfma_f32_16x16x32_bf16 v[64:67], v[182:185], v[218:221], v[64:67]
	v_mfma_f32_16x16x32_bf16 v[116:119], v[178:181], v[194:197], v[116:119]
	v_mfma_f32_16x16x32_bf16 v[112:115], v[186:189], v[194:197], v[112:115]
	v_mfma_f32_16x16x32_bf16 v[100:103], v[178:181], v[206:209], v[100:103]
	v_mfma_f32_16x16x32_bf16 v[96:99], v[186:189], v[206:209], v[96:99]
	v_mfma_f32_16x16x32_bf16 v[84:87], v[178:181], v[214:217], v[84:87]
	v_mfma_f32_16x16x32_bf16 v[80:83], v[186:189], v[214:217], v[80:83]
	v_mfma_f32_16x16x32_bf16 v[68:71], v[178:181], v[222:225], v[68:71]
	v_mfma_f32_16x16x32_bf16 v[64:67], v[186:189], v[222:225], v[64:67]
	s_setprio 0
	s_barrier
	s_add_i32 s77, s72, s33
	s_mov_b32 m0, s77
	ds_read_b128 v[190:193], v154 offset:16384
	ds_read_b128 v[194:197], v154 offset:17408
	ds_read_b128 v[198:201], v154 offset:18432
	ds_read_b128 v[206:209], v154 offset:19456
	ds_read_b128 v[210:213], v154 offset:20480
	ds_read_b128 v[214:217], v154 offset:21504
	ds_read_b128 v[218:221], v154 offset:22528
	ds_read_b128 v[222:225], v154 offset:23552
	global_load_lds_dwordx4 v132, s[64:65]
	s_add_i32 m0, s77, 0x2000
	s_add_u32 s98, s64, 0x80
	s_addc_u32 s99, s65, 0
	s_add_u32 s78, s64, 0x40000
	s_addc_u32 s79, s65, 0
	s_add_i32 s77, s73, s33
	global_load_lds_dwordx4 v136, s[64:65]
	s_mov_b32 m0, s77
	s_nop 0
	global_load_lds_dwordx4 v132, s[78:79]
	s_add_i32 m0, s77, 0x2000
	s_nop 0
	global_load_lds_dwordx4 v136, s[78:79]
	s_mov_b32 m0, s61
	s_nop 0
	global_load_lds_dwordx4 v130, s[70:71]
	s_mov_b32 m0, s66
	s_nop 0
	global_load_lds_dwordx4 v134, s[70:71]
	s_waitcnt vmcnt(8)
	s_waitcnt lgkmcnt(0)
	s_setprio 1
	s_barrier
	v_mfma_f32_16x16x32_bf16 v[60:63], v[158:161], v[190:193], v[60:63]
	v_mfma_f32_16x16x32_bf16 v[56:59], v[166:169], v[190:193], v[56:59]
	v_mfma_f32_16x16x32_bf16 v[44:47], v[158:161], v[198:201], v[44:47]
	v_mfma_f32_16x16x32_bf16 v[40:43], v[166:169], v[198:201], v[40:43]
	v_mfma_f32_16x16x32_bf16 v[28:31], v[158:161], v[210:213], v[28:31]
	v_mfma_f32_16x16x32_bf16 v[24:27], v[166:169], v[210:213], v[24:27]
	v_mfma_f32_16x16x32_bf16 v[12:15], v[158:161], v[218:221], v[12:15]
	v_mfma_f32_16x16x32_bf16 v[8:11], v[166:169], v[218:221], v[8:11]
	v_mfma_f32_16x16x32_bf16 v[60:63], v[162:165], v[194:197], v[60:63]
	v_mfma_f32_16x16x32_bf16 v[56:59], v[170:173], v[194:197], v[56:59]
	v_mfma_f32_16x16x32_bf16 v[44:47], v[162:165], v[206:209], v[44:47]
	v_mfma_f32_16x16x32_bf16 v[40:43], v[170:173], v[206:209], v[40:43]
	v_mfma_f32_16x16x32_bf16 v[28:31], v[162:165], v[214:217], v[28:31]
	v_mfma_f32_16x16x32_bf16 v[24:27], v[170:173], v[214:217], v[24:27]
	v_mfma_f32_16x16x32_bf16 v[12:15], v[162:165], v[222:225], v[12:15]
	v_mfma_f32_16x16x32_bf16 v[8:11], v[170:173], v[222:225], v[8:11]
	v_mfma_f32_16x16x32_bf16 v[52:55], v[174:177], v[190:193], v[52:55]
	v_mfma_f32_16x16x32_bf16 v[48:51], v[182:185], v[190:193], v[48:51]
	v_mfma_f32_16x16x32_bf16 v[36:39], v[174:177], v[198:201], v[36:39]
	v_mfma_f32_16x16x32_bf16 v[32:35], v[182:185], v[198:201], v[32:35]
	v_mfma_f32_16x16x32_bf16 v[20:23], v[174:177], v[210:213], v[20:23]
	v_mfma_f32_16x16x32_bf16 v[16:19], v[182:185], v[210:213], v[16:19]
	v_mfma_f32_16x16x32_bf16 v[4:7], v[174:177], v[218:221], v[4:7]
	v_mfma_f32_16x16x32_bf16 v[0:3], v[182:185], v[218:221], v[0:3]
	v_mfma_f32_16x16x32_bf16 v[52:55], v[178:181], v[194:197], v[52:55]
	v_mfma_f32_16x16x32_bf16 v[48:51], v[186:189], v[194:197], v[48:51]
	v_mfma_f32_16x16x32_bf16 v[36:39], v[178:181], v[206:209], v[36:39]
	v_mfma_f32_16x16x32_bf16 v[32:35], v[186:189], v[206:209], v[32:35]
	v_mfma_f32_16x16x32_bf16 v[20:23], v[178:181], v[214:217], v[20:23]
	v_mfma_f32_16x16x32_bf16 v[16:19], v[186:189], v[214:217], v[16:19]
	v_mfma_f32_16x16x32_bf16 v[4:7], v[178:181], v[222:225], v[4:7]
	v_mfma_f32_16x16x32_bf16 v[0:3], v[186:189], v[222:225], v[0:3]
	s_setprio 0
	s_barrier
; #define PG8_STAGE(bufoff, gbase, voff) do { _Pragma("unroll") for (int _i = 0; _i < 2; ++_i) \
;         __builtin_amdgcn_global_load_lds((const unsigned*)((const char*)(gbase) + (voff)[_i]), (PG8_LAS unsigned*)(lds + (bufoff) + ldsw + _i * 8192), 16, 0, 0); } while (0)
; #define PG8_LDA(dst, b, h) do { _Pragma("unroll") for (int m = 0; m < 4; ++m) _Pragma("unroll") for (int k = 0; k < 2; ++k) dst[m][k] = *(const PG8_LAS bf16x8*)(lds + PG8_SA(b, h) + aoff + m * 2048 + k * 1024); } while (0)
; #define PG8_LDB(dst, b, h) do { _Pragma("unroll") for (int n = 0; n < 2; ++n) _Pragma("unroll") for (int k = 0; k < 2; ++k) dst[n][k] = *(const PG8_LAS bf16x8*)(lds + PG8_SB(b, h) + boff + n * 2048 + k * 1024); } while (0)
; #define PG8_MMA(ai, bj, At, Bt) do { __builtin_amdgcn_s_setprio(1); _Pragma("unroll") for (int m = 0; m < 4; ++m) _Pragma("unroll") for (int n = 0; n < 2; ++n) _Pragma("unroll") for (int k = 0; k < 2; ++k) \
;         acc[ai][bj][m][n] = __builtin_amdgcn_mfma_f32_16x16x32_bf16(Bt[n][k], At[m][k], acc[ai][bj][m][n], 0, 0, 0); __builtin_amdgcn_s_setprio(0); } while (0)
; #define PG8_WAIT_V(n) asm volatile("s_waitcnt vmcnt(" #n ")" ::: "memory")
; #define PG8_WAIT_L(n) asm volatile("s_waitcnt lgkmcnt(" #n ")" ::: "memory")
; #define PG8_BAR __builtin_amdgcn_s_barrier()
; #define PG8_SCHED __builtin_amdgcn_sched_barrier(0)
; template <class Epi, class Sched, bool ALIGN_EPI = false, bool SP2 = false>
; __device__ __forceinline__ void gemm_phase(PG8_LAS unsigned char* lds, const Gemm g, const Sched& S, const Epi& E) {
;     ...
;             PG8_LDB(B0, 1, 0); PG8_LDB(B1, 1, 1); PG8_SCHED; PG8_LDA(At, 1, 0); PG8_STAGE(PG8_SA(0, 1), a2 + hstep, voffA);
;             PG8_WAIT_V(8); PG8_WAIT_L(0); PG8_BAR; PG8_MMA(0, 0, At, B0); PG8_MMA(0, 1, At, B1); PG8_BAR; PG8_SCHED;
;             PG8_LDA(At, 1, 1); PG8_STAGE(PG8_SB(1, 0), b3, voffB); PG8_STAGE(PG8_SB(1, 1), b3 + hstep, voffB); PG8_STAGE(PG8_SA(1, 0), a3, voffA);
;             PG8_WAIT_V(8); PG8_WAIT_L(0); PG8_BAR; PG8_MMA(1, 0, At, B0); PG8_MMA(1, 1, At, B1); PG8_BAR; PG8_SCHED;
	s_add_i32 s77, 0, 0x18000
	s_add_i32 s78, 0, 0x1c000
	ds_read_b128 v[158:161], v240
	ds_read_b128 v[162:165], v240 offset:1024
	ds_read_b128 v[166:169], v240 offset:2048
	ds_read_b128 v[170:173], v240 offset:3072
	ds_read_b128 v[174:177], v241
	ds_read_b128 v[178:181], v241 offset:1024
	ds_read_b128 v[182:185], v241 offset:2048
	ds_read_b128 v[186:189], v241 offset:3072
	s_add_u32 s100, s70, 0x80
	s_addc_u32 s101, s71, 0
	s_add_u32 s70, s70, 0x40000
	s_addc_u32 s71, s71, 0
	s_mov_b32 m0, s67
	ds_read_b128 v[190:193], v154 offset:32768
	ds_read_b128 v[194:197], v154 offset:33792
	ds_read_b128 v[198:201], v154 offset:34816
	ds_read_b128 v[206:209], v154 offset:35840
	ds_read_b128 v[210:213], v154 offset:36864
	ds_read_b128 v[214:217], v154 offset:37888
	ds_read_b128 v[218:221], v154 offset:38912
	ds_read_b128 v[222:225], v154 offset:39936
	global_load_lds_dwordx4 v130, s[70:71]
	s_mov_b32 m0, s88
	s_nop 0
	global_load_lds_dwordx4 v134, s[70:71]
	s_waitcnt vmcnt(8)
	s_waitcnt lgkmcnt(0)
	s_setprio 1
	s_barrier
	v_mfma_f32_16x16x32_bf16 v[124:127], v[158:161], v[190:193], v[124:127]
	v_mfma_f32_16x16x32_bf16 v[120:123], v[166:169], v[190:193], v[120:123]
	v_mfma_f32_16x16x32_bf16 v[108:111], v[158:161], v[198:201], v[108:111]
	v_mfma_f32_16x16x32_bf16 v[104:107], v[166:169], v[198:201], v[104:107]
	v_mfma_f32_16x16x32_bf16 v[92:95], v[158:161], v[210:213], v[92:95]
	v_mfma_f32_16x16x32_bf16 v[88:91], v[166:169], v[210:213], v[88:91]
	v_mfma_f32_16x16x32_bf16 v[76:79], v[158:161], v[218:221], v[76:79]
	v_mfma_f32_16x16x32_bf16 v[72:75], v[166:169], v[218:221], v[72:75]
	v_mfma_f32_16x16x32_bf16 v[124:127], v[162:165], v[194:197], v[124:127]
	v_mfma_f32_16x16x32_bf16 v[120:123], v[170:173], v[194:197], v[120:123]
	v_mfma_f32_16x16x32_bf16 v[108:111], v[162:165], v[206:209], v[108:111]
	v_mfma_f32_16x16x32_bf16 v[104:107], v[170:173], v[206:209], v[104:107]
	v_mfma_f32_16x16x32_bf16 v[92:95], v[162:165], v[214:217], v[92:95]
	v_mfma_f32_16x16x32_bf16 v[88:91], v[170:173], v[214:217], v[88:91]
	v_mfma_f32_16x16x32_bf16 v[76:79], v[162:165], v[222:225], v[76:79]
	v_mfma_f32_16x16x32_bf16 v[72:75], v[170:173], v[222:225], v[72:75]
	v_mfma_f32_16x16x32_bf16 v[116:119], v[174:177], v[190:193], v[116:119]
	v_mfma_f32_16x16x32_bf16 v[112:115], v[182:185], v[190:193], v[112:115]
	v_mfma_f32_16x16x32_bf16 v[100:103], v[174:177], v[198:201], v[100:103]
	v_mfma_f32_16x16x32_bf16 v[96:99], v[182:185], v[198:201], v[96:99]
	v_mfma_f32_16x16x32_bf16 v[84:87], v[174:177], v[210:213], v[84:87]
	v_mfma_f32_16x16x32_bf16 v[80:83], v[182:185], v[210:213], v[80:83]
	v_mfma_f32_16x16x32_bf16 v[68:71], v[174:177], v[218:221], v[68:71]
	v_mfma_f32_16x16x32_bf16 v[64:67], v[182:185], v[218:221], v[64:67]
	v_mfma_f32_16x16x32_bf16 v[116:119], v[178:181], v[194:197], v[116:119]
	v_mfma_f32_16x16x32_bf16 v[112:115], v[186:189], v[194:197], v[112:115]
	v_mfma_f32_16x16x32_bf16 v[100:103], v[178:181], v[206:209], v[100:103]
	v_mfma_f32_16x16x32_bf16 v[96:99], v[186:189], v[206:209], v[96:99]
	v_mfma_f32_16x16x32_bf16 v[84:87], v[178:181], v[214:217], v[84:87]
	v_mfma_f32_16x16x32_bf16 v[80:83], v[186:189], v[214:217], v[80:83]
	v_mfma_f32_16x16x32_bf16 v[68:71], v[178:181], v[222:225], v[68:71]
	v_mfma_f32_16x16x32_bf16 v[64:67], v[186:189], v[222:225], v[64:67]
	s_setprio 0
	s_barrier
	s_add_i32 s70, s77, s33
	s_mov_b32 m0, s70
	ds_read_b128 v[190:193], v154 offset:49152
	ds_read_b128 v[194:197], v154 offset:50176
	ds_read_b128 v[198:201], v154 offset:51200
	ds_read_b128 v[206:209], v154 offset:52224
	ds_read_b128 v[210:213], v154 offset:53248
	ds_read_b128 v[214:217], v154 offset:54272
	ds_read_b128 v[218:221], v154 offset:55296
	ds_read_b128 v[222:225], v154 offset:56320
	global_load_lds_dwordx4 v132, s[98:99]
	s_add_i32 m0, s70, 0x2000
	s_add_u32 s64, s64, 0x40080
	s_addc_u32 s65, s65, 0
	s_add_i32 s70, s78, s33
	global_load_lds_dwordx4 v136, s[98:99]
	s_mov_b32 m0, s70
	s_nop 0
	global_load_lds_dwordx4 v132, s[64:65]
	s_add_i32 m0, s70, 0x2000
	s_nop 0
	global_load_lds_dwordx4 v136, s[64:65]
	s_mov_b32 m0, s3
	s_nop 0
	global_load_lds_dwordx4 v130, s[100:101]
	s_mov_b32 m0, s68
	s_nop 0
	global_load_lds_dwordx4 v134, s[100:101]
	s_waitcnt vmcnt(8)
	s_waitcnt lgkmcnt(0)
	s_setprio 1
	s_barrier
	v_mfma_f32_16x16x32_bf16 v[60:63], v[158:161], v[190:193], v[60:63]
	v_mfma_f32_16x16x32_bf16 v[56:59], v[166:169], v[190:193], v[56:59]
	v_mfma_f32_16x16x32_bf16 v[44:47], v[158:161], v[198:201], v[44:47]
	v_mfma_f32_16x16x32_bf16 v[40:43], v[166:169], v[198:201], v[40:43]
	v_mfma_f32_16x16x32_bf16 v[28:31], v[158:161], v[210:213], v[28:31]
	v_mfma_f32_16x16x32_bf16 v[24:27], v[166:169], v[210:213], v[24:27]
	v_mfma_f32_16x16x32_bf16 v[12:15], v[158:161], v[218:221], v[12:15]
	v_mfma_f32_16x16x32_bf16 v[8:11], v[166:169], v[218:221], v[8:11]
	v_mfma_f32_16x16x32_bf16 v[60:63], v[162:165], v[194:197], v[60:63]
	v_mfma_f32_16x16x32_bf16 v[56:59], v[170:173], v[194:197], v[56:59]
	v_mfma_f32_16x16x32_bf16 v[44:47], v[162:165], v[206:209], v[44:47]
	v_mfma_f32_16x16x32_bf16 v[40:43], v[170:173], v[206:209], v[40:43]
	v_mfma_f32_16x16x32_bf16 v[28:31], v[162:165], v[214:217], v[28:31]
	v_mfma_f32_16x16x32_bf16 v[24:27], v[170:173], v[214:217], v[24:27]
	v_mfma_f32_16x16x32_bf16 v[12:15], v[162:165], v[222:225], v[12:15]
	v_mfma_f32_16x16x32_bf16 v[8:11], v[170:173], v[222:225], v[8:11]
	v_mfma_f32_16x16x32_bf16 v[52:55], v[174:177], v[190:193], v[52:55]
	v_mfma_f32_16x16x32_bf16 v[48:51], v[182:185], v[190:193], v[48:51]
	v_mfma_f32_16x16x32_bf16 v[36:39], v[174:177], v[198:201], v[36:39]
	v_mfma_f32_16x16x32_bf16 v[32:35], v[182:185], v[198:201], v[32:35]
	v_mfma_f32_16x16x32_bf16 v[20:23], v[174:177], v[210:213], v[20:23]
	v_mfma_f32_16x16x32_bf16 v[16:19], v[182:185], v[210:213], v[16:19]
	v_mfma_f32_16x16x32_bf16 v[4:7], v[174:177], v[218:221], v[4:7]
	v_mfma_f32_16x16x32_bf16 v[0:3], v[182:185], v[218:221], v[0:3]
	v_mfma_f32_16x16x32_bf16 v[52:55], v[178:181], v[194:197], v[52:55]
	v_mfma_f32_16x16x32_bf16 v[48:51], v[186:189], v[194:197], v[48:51]
	v_mfma_f32_16x16x32_bf16 v[36:39], v[178:181], v[206:209], v[36:39]
	v_mfma_f32_16x16x32_bf16 v[32:35], v[186:189], v[206:209], v[32:35]
	v_mfma_f32_16x16x32_bf16 v[20:23], v[178:181], v[214:217], v[20:23]
	v_mfma_f32_16x16x32_bf16 v[16:19], v[186:189], v[214:217], v[16:19]
	v_mfma_f32_16x16x32_bf16 v[4:7], v[178:181], v[222:225], v[4:7]
	v_mfma_f32_16x16x32_bf16 v[0:3], v[186:189], v[222:225], v[0:3]
	s_setprio 0
	s_barrier
	s_add_i32 s76, s76, 2
	s_add_u32 s62, s62, 0x100
	s_addc_u32 s63, s63, 0
	s_add_u32 s55, s55, 0x100
	s_addc_u32 s75, s75, 0
	s_cmp_gt_u32 s76, 13
	s_cbranch_scc0 .LBB0_136
	s_and_b64 vcc, exec, s[50:51]
	s_cbranch_vccz .LBB0_139
	s_barrier

; #define PG8_STAGE(bufoff, gbase, voff) do { _Pragma("unroll") for (int _i = 0; _i < 2; ++_i) \
;         __builtin_amdgcn_global_load_lds((const unsigned*)((const char*)(gbase) + (voff)[_i]), (PG8_LAS unsigned*)(lds + (bufoff) + ldsw + _i * 8192), 16, 0, 0); } while (0)
; #define PG8_LDA(dst, b, h) do { _Pragma("unroll") for (int m = 0; m < 4; ++m) _Pragma("unroll") for (int k = 0; k < 2; ++k) dst[m][k] = *(const PG8_LAS bf16x8*)(lds + PG8_SA(b, h) + aoff + m * 2048 + k * 1024); } while (0)
; #define PG8_LDB(dst, b, h) do { _Pragma("unroll") for (int n = 0; n < 2; ++n) _Pragma("unroll") for (int k = 0; k < 2; ++k) dst[n][k] = *(const PG8_LAS bf16x8*)(lds + PG8_SB(b, h) + boff + n * 2048 + k * 1024); } while (0)
; #define PG8_WAIT_V(n) asm volatile("s_waitcnt vmcnt(" #n ")" ::: "memory")
; #define PG8_WAIT_L(n) asm volatile("s_waitcnt lgkmcnt(" #n ")" ::: "memory")
; #define PG8_BAR __builtin_amdgcn_s_barrier()
; #define PG8_SCHED __builtin_amdgcn_sched_barrier(0)
; template <class Epi, class Sched, bool ALIGN_EPI = false, bool SP2 = false>
; __device__ __forceinline__ void gemm_phase(PG8_LAS unsigned char* lds, const Gemm g, const Sched& S, const Epi& E) {
;     ...
;         const char* nA = has_next ? (const char*)g.A + (size_t)nxt.pm * tstep : cA; const char* nB = has_next ? (const char*)g.Bt + (size_t)nxt.pn * tstep : cB;
;         for (int t = 0; t < nt; t += 2) {
;             const bool last = (t == nt - 2);
;             const char* a1 = cA + (size_t)(t + 1) * kstep;
;             const char* a2 = last ? nA : cA + (size_t)(t + 2) * kstep; const char* b2 = last ? nB : cB + (size_t)(t + 2) * kstep;
;             const char* a3 = a2 + kstep; const char* b3 = b2 + kstep;
;             if (last && has_next) S.a_ready(nxt);
;             if constexpr (SP2) {
;             PG8_LDB(B0, 0, 0); PG8_LDB(B1, 0, 1); PG8_SCHED; PG8_LDA(At, 0, 0); PG8_STAGE(PG8_SA(1, 1), a1 + hstep, voffA);
;             PG8_WAIT_V(8); PG8_WAIT_L(0); PG8_BAR; PG8_MMA(0, 0, At, B0); PG8_MMA(0, 1, At, B1); PG8_BAR; PG8_SCHED;
;     ...
;         for (int a = 0; a < 2; ++a)
; #pragma unroll
;             for (int b = 0; b < 2; ++b)
; #pragma unroll
;                 for (int m = 0; m < 4; ++m)
; #pragma unroll
;                     for (int n = 0; n < 2; ++n) acc[a][b][m][n] = (f32x4){0.f, 0.f, 0.f, 0.f};
.LBB0_519:
	s_ashr_i32 s35, s34, 31
	s_lshl_b64 s[36:37], s[34:35], 19
	s_add_u32 s36, s70, s36
	s_addc_u32 s37, s71, s37
	s_and_b64 s[38:39], s[6:7], exec
	s_cselect_b32 s35, s37, s45
	s_cselect_b32 s41, s36, s44
	s_ashr_i32 s31, s30, 31
	s_lshl_b64 s[38:39], s[30:31], 19
	v_readlane_b32 s14, v255, 28
	v_readlane_b32 s15, v255, 29
	s_add_u32 s38, s14, s38
	s_addc_u32 s39, s15, s39
	s_and_b64 s[48:49], s[6:7], exec
	s_cselect_b32 s31, s39, s47
	s_cselect_b32 s60, s38, s46
	s_add_u32 s44, s44, 0x40080
	s_addc_u32 s45, s45, 0
	s_add_u32 s61, s46, 0x100
	v_mov_b32_e32 v0, 0
	s_addc_u32 s62, s47, 0
	s_mov_b32 s63, -2
	s_waitcnt lgkmcnt(0)
	v_mov_b32_e32 v1, v0
	v_mov_b32_e32 v2, v0
	v_mov_b32_e32 v3, v0
	v_mov_b32_e32 v4, v0
	v_mov_b32_e32 v5, v0
	v_mov_b32_e32 v6, v0
	v_mov_b32_e32 v7, v0
	v_mov_b32_e32 v16, v0
	v_mov_b32_e32 v17, v0
	v_mov_b32_e32 v18, v0
	v_mov_b32_e32 v19, v0
	v_mov_b32_e32 v20, v0
	v_mov_b32_e32 v21, v0
	v_mov_b32_e32 v22, v0
	v_mov_b32_e32 v23, v0
	v_mov_b32_e32 v32, v0
	v_mov_b32_e32 v33, v0
	v_mov_b32_e32 v34, v0
	v_mov_b32_e32 v35, v0
	v_mov_b32_e32 v36, v0
	v_mov_b32_e32 v37, v0
	v_mov_b32_e32 v38, v0
	v_mov_b32_e32 v39, v0
	v_mov_b32_e32 v48, v0
	v_mov_b32_e32 v49, v0
	v_mov_b32_e32 v50, v0
	v_mov_b32_e32 v51, v0
	v_mov_b32_e32 v52, v0
	v_mov_b32_e32 v53, v0
	v_mov_b32_e32 v54, v0
	v_mov_b32_e32 v55, v0
	v_mov_b32_e32 v8, v0
	v_mov_b32_e32 v9, v0
	v_mov_b32_e32 v10, v0
	v_mov_b32_e32 v11, v0
	v_mov_b32_e32 v12, v0
	v_mov_b32_e32 v13, v0
	v_mov_b32_e32 v14, v0
	v_mov_b32_e32 v15, v0
	v_mov_b32_e32 v24, v0
	v_mov_b32_e32 v25, v0
	v_mov_b32_e32 v26, v0
	v_mov_b32_e32 v27, v0
	v_mov_b32_e32 v28, v0
	v_mov_b32_e32 v29, v0
	v_mov_b32_e32 v30, v0
	v_mov_b32_e32 v31, v0
	v_mov_b32_e32 v40, v0
	v_mov_b32_e32 v41, v0
	v_mov_b32_e32 v42, v0
	v_mov_b32_e32 v43, v0
	v_mov_b32_e32 v44, v0
	v_mov_b32_e32 v45, v0
	v_mov_b32_e32 v46, v0
	v_mov_b32_e32 v47, v0
	v_mov_b32_e32 v56, v0
	v_mov_b32_e32 v57, v0
	v_mov_b32_e32 v58, v0
	v_mov_b32_e32 v59, v0
	v_mov_b32_e32 v60, v0
	v_mov_b32_e32 v61, v0
	v_mov_b32_e32 v62, v0
	v_mov_b32_e32 v63, v0
	v_mov_b32_e32 v64, v0
	v_mov_b32_e32 v65, v0
	v_mov_b32_e32 v66, v0
	v_mov_b32_e32 v67, v0
	v_mov_b32_e32 v68, v0
	v_mov_b32_e32 v69, v0
	v_mov_b32_e32 v70, v0
	v_mov_b32_e32 v71, v0
	v_mov_b32_e32 v80, v0
	v_mov_b32_e32 v81, v0
	v_mov_b32_e32 v82, v0
	v_mov_b32_e32 v83, v0
	v_mov_b32_e32 v84, v0
	v_mov_b32_e32 v85, v0
	v_mov_b32_e32 v86, v0
	v_mov_b32_e32 v87, v0
	v_mov_b32_e32 v96, v0
	v_mov_b32_e32 v97, v0
	v_mov_b32_e32 v98, v0
	v_mov_b32_e32 v99, v0
	v_mov_b32_e32 v100, v0
	v_mov_b32_e32 v101, v0
	v_mov_b32_e32 v102, v0
	v_mov_b32_e32 v103, v0
	v_mov_b32_e32 v112, v0
	v_mov_b32_e32 v113, v0
	v_mov_b32_e32 v114, v0
	v_mov_b32_e32 v115, v0
	v_mov_b32_e32 v116, v0
	v_mov_b32_e32 v117, v0
	v_mov_b32_e32 v118, v0
	v_mov_b32_e32 v119, v0
	v_mov_b32_e32 v72, v0
	v_mov_b32_e32 v73, v0
	v_mov_b32_e32 v74, v0
	v_mov_b32_e32 v75, v0
	v_mov_b32_e32 v76, v0
	v_mov_b32_e32 v77, v0
	v_mov_b32_e32 v78, v0
	v_mov_b32_e32 v79, v0
	v_mov_b32_e32 v88, v0
	v_mov_b32_e32 v89, v0
	v_mov_b32_e32 v90, v0
	v_mov_b32_e32 v91, v0
	v_mov_b32_e32 v92, v0
	v_mov_b32_e32 v93, v0
	v_mov_b32_e32 v94, v0
	v_mov_b32_e32 v95, v0
	v_mov_b32_e32 v104, v0
	v_mov_b32_e32 v105, v0
	v_mov_b32_e32 v106, v0
	v_mov_b32_e32 v107, v0
	v_mov_b32_e32 v108, v0
	v_mov_b32_e32 v109, v0
	v_mov_b32_e32 v110, v0
	v_mov_b32_e32 v111, v0
	v_mov_b32_e32 v120, v0
	v_mov_b32_e32 v121, v0
	v_mov_b32_e32 v122, v0
	v_mov_b32_e32 v123, v0
	v_mov_b32_e32 v124, v0
	v_mov_b32_e32 v125, v0
	v_mov_b32_e32 v126, v0
	v_mov_b32_e32 v127, v0
	v_add_u32_e32 v240, 0x18000, v150
	v_add_u32_e32 v241, 0x1c000, v150
.LBB0_520:
	ds_read_b128 v[146:149], v152
	ds_read_b128 v[156:159], v152 offset:1024
	ds_read_b128 v[160:163], v152 offset:2048
	ds_read_b128 v[164:167], v152 offset:3072
	ds_read_b128 v[168:171], v153
	ds_read_b128 v[172:175], v153 offset:1024
	ds_read_b128 v[176:179], v153 offset:2048
	ds_read_b128 v[180:183], v153 offset:3072
	s_add_u32 s46, s44, 0xfffc0080
	s_addc_u32 s47, s45, -1
	s_cmp_eq_u32 s63, 12
	s_cselect_b32 s49, s35, s47
	s_cselect_b32 s48, s41, s46
	s_cselect_b32 s47, s31, s62
	s_cselect_b32 s46, s60, s61
	s_add_i32 m0, s43, 0xc000
	ds_read_b128 v[184:187], v154
	ds_read_b128 v[188:191], v154 offset:1024
	ds_read_b128 v[192:195], v154 offset:2048
	ds_read_b128 v[196:199], v154 offset:3072
	ds_read_b128 v[200:203], v154 offset:4096
	ds_read_b128 v[206:209], v154 offset:5120
	ds_read_b128 v[210:213], v154 offset:6144
	ds_read_b128 v[214:217], v154 offset:7168
	global_load_lds_dwordx4 v138, s[44:45]
	s_add_i32 m0, s43, 0xe000
	s_nop 0
	global_load_lds_dwordx4 v140, s[44:45]
	s_waitcnt vmcnt(8)
	s_waitcnt lgkmcnt(0)
	s_setprio 1
	s_barrier
; #define PG8_STAGE(bufoff, gbase, voff) do { _Pragma("unroll") for (int _i = 0; _i < 2; ++_i) \
;         __builtin_amdgcn_global_load_lds((const unsigned*)((const char*)(gbase) + (voff)[_i]), (PG8_LAS unsigned*)(lds + (bufoff) + ldsw + _i * 8192), 16, 0, 0); } while (0)
; #define PG8_LDA(dst, b, h) do { _Pragma("unroll") for (int m = 0; m < 4; ++m) _Pragma("unroll") for (int k = 0; k < 2; ++k) dst[m][k] = *(const PG8_LAS bf16x8*)(lds + PG8_SA(b, h) + aoff + m * 2048 + k * 1024); } while (0)
; #define PG8_MMA(ai, bj, At, Bt) do { __builtin_amdgcn_s_setprio(1); _Pragma("unroll") for (int m = 0; m < 4; ++m) _Pragma("unroll") for (int n = 0; n < 2; ++n) _Pragma("unroll") for (int k = 0; k < 2; ++k) \
;         acc[ai][bj][m][n] = __builtin_amdgcn_mfma_f32_16x16x32_bf16(Bt[n][k], At[m][k], acc[ai][bj][m][n], 0, 0, 0); __builtin_amdgcn_s_setprio(0); } while (0)
; #define PG8_WAIT_V(n) asm volatile("s_waitcnt vmcnt(" #n ")" ::: "memory")
; #define PG8_WAIT_L(n) asm volatile("s_waitcnt lgkmcnt(" #n ")" ::: "memory")
; #define PG8_BAR __builtin_amdgcn_s_barrier()
; #define PG8_SCHED __builtin_amdgcn_sched_barrier(0)
; template <class Epi, class Sched, bool ALIGN_EPI = false, bool SP2 = false>
; __device__ __forceinline__ void gemm_phase(PG8_LAS unsigned char* lds, const Gemm g, const Sched& S, const Epi& E) {
;     ...
;             PG8_WAIT_V(8); PG8_WAIT_L(0); PG8_BAR; PG8_MMA(0, 0, At, B0); PG8_MMA(0, 1, At, B1); PG8_BAR; PG8_SCHED;
;             PG8_LDA(At, 0, 1); PG8_STAGE(PG8_SB(0, 0), b2, voffB); PG8_STAGE(PG8_SB(0, 1), b2 + hstep, voffB); PG8_STAGE(PG8_SA(0, 0), a2, voffA);
;             PG8_WAIT_V(8); PG8_WAIT_L(0); PG8_BAR; PG8_MMA(1, 0, At, B0); PG8_MMA(1, 1, At, B1); PG8_BAR; PG8_SCHED;
	v_mfma_f32_16x16x32_bf16 v[124:127], v[146:149], v[184:187], v[124:127]
	v_mfma_f32_16x16x32_bf16 v[120:123], v[160:163], v[184:187], v[120:123]
	v_mfma_f32_16x16x32_bf16 v[108:111], v[146:149], v[192:195], v[108:111]
	v_mfma_f32_16x16x32_bf16 v[104:107], v[160:163], v[192:195], v[104:107]
	v_mfma_f32_16x16x32_bf16 v[92:95], v[146:149], v[200:203], v[92:95]
	v_mfma_f32_16x16x32_bf16 v[88:91], v[160:163], v[200:203], v[88:91]
	v_mfma_f32_16x16x32_bf16 v[76:79], v[146:149], v[210:213], v[76:79]
	v_mfma_f32_16x16x32_bf16 v[72:75], v[160:163], v[210:213], v[72:75]
	v_mfma_f32_16x16x32_bf16 v[124:127], v[156:159], v[188:191], v[124:127]
	v_mfma_f32_16x16x32_bf16 v[120:123], v[164:167], v[188:191], v[120:123]
	v_mfma_f32_16x16x32_bf16 v[108:111], v[156:159], v[196:199], v[108:111]
	v_mfma_f32_16x16x32_bf16 v[104:107], v[164:167], v[196:199], v[104:107]
	v_mfma_f32_16x16x32_bf16 v[92:95], v[156:159], v[206:209], v[92:95]
	v_mfma_f32_16x16x32_bf16 v[88:91], v[164:167], v[206:209], v[88:91]
	v_mfma_f32_16x16x32_bf16 v[76:79], v[156:159], v[214:217], v[76:79]
	v_mfma_f32_16x16x32_bf16 v[72:75], v[164:167], v[214:217], v[72:75]
	v_mfma_f32_16x16x32_bf16 v[116:119], v[168:171], v[184:187], v[116:119]
	v_mfma_f32_16x16x32_bf16 v[112:115], v[176:179], v[184:187], v[112:115]
	v_mfma_f32_16x16x32_bf16 v[100:103], v[168:171], v[192:195], v[100:103]
	v_mfma_f32_16x16x32_bf16 v[96:99], v[176:179], v[192:195], v[96:99]
	v_mfma_f32_16x16x32_bf16 v[84:87], v[168:171], v[200:203], v[84:87]
	v_mfma_f32_16x16x32_bf16 v[80:83], v[176:179], v[200:203], v[80:83]
	v_mfma_f32_16x16x32_bf16 v[68:71], v[168:171], v[210:213], v[68:71]
	v_mfma_f32_16x16x32_bf16 v[64:67], v[176:179], v[210:213], v[64:67]
	v_mfma_f32_16x16x32_bf16 v[116:119], v[172:175], v[188:191], v[116:119]
	v_mfma_f32_16x16x32_bf16 v[112:115], v[180:183], v[188:191], v[112:115]
	v_mfma_f32_16x16x32_bf16 v[100:103], v[172:175], v[196:199], v[100:103]
	v_mfma_f32_16x16x32_bf16 v[96:99], v[180:183], v[196:199], v[96:99]
	v_mfma_f32_16x16x32_bf16 v[84:87], v[172:175], v[206:209], v[84:87]
	v_mfma_f32_16x16x32_bf16 v[80:83], v[180:183], v[206:209], v[80:83]
	v_mfma_f32_16x16x32_bf16 v[68:71], v[172:175], v[214:217], v[68:71]
	v_mfma_f32_16x16x32_bf16 v[64:67], v[180:183], v[214:217], v[64:67]
	s_setprio 0
	s_barrier
	s_add_i32 s64, s58, s13
	s_mov_b32 m0, s64
	ds_read_b128 v[184:187], v154 offset:16384
	ds_read_b128 v[188:191], v154 offset:17408
	ds_read_b128 v[192:195], v154 offset:18432
	ds_read_b128 v[196:199], v154 offset:19456
	ds_read_b128 v[200:203], v154 offset:20480
	ds_read_b128 v[206:209], v154 offset:21504
	ds_read_b128 v[210:213], v154 offset:22528
	ds_read_b128 v[214:217], v154 offset:23552
	global_load_lds_dwordx4 v132, s[46:47]
	s_add_i32 m0, s64, 0x2000
	s_add_u32 s98, s46, 0x80
	s_addc_u32 s99, s47, 0
	s_add_u32 s64, s46, 0x40000
	s_addc_u32 s65, s47, 0
	s_add_i32 s66, s59, s13
	global_load_lds_dwordx4 v136, s[46:47]
	s_mov_b32 m0, s66
	s_nop 0
	global_load_lds_dwordx4 v132, s[64:65]
	s_add_i32 m0, s66, 0x2000
	s_nop 0
	global_load_lds_dwordx4 v136, s[64:65]
	s_mov_b32 m0, s43
	s_nop 0
	global_load_lds_dwordx4 v130, s[48:49]
	s_mov_b32 m0, s50
	s_nop 0
	global_load_lds_dwordx4 v134, s[48:49]
	s_waitcnt vmcnt(8)
	s_waitcnt lgkmcnt(0)
	s_setprio 1
	s_barrier
	v_mfma_f32_16x16x32_bf16 v[60:63], v[146:149], v[184:187], v[60:63]
	v_mfma_f32_16x16x32_bf16 v[56:59], v[160:163], v[184:187], v[56:59]
	v_mfma_f32_16x16x32_bf16 v[44:47], v[146:149], v[192:195], v[44:47]
	v_mfma_f32_16x16x32_bf16 v[40:43], v[160:163], v[192:195], v[40:43]
	v_mfma_f32_16x16x32_bf16 v[28:31], v[146:149], v[200:203], v[28:31]
	v_mfma_f32_16x16x32_bf16 v[24:27], v[160:163], v[200:203], v[24:27]
	v_mfma_f32_16x16x32_bf16 v[12:15], v[146:149], v[210:213], v[12:15]
	v_mfma_f32_16x16x32_bf16 v[8:11], v[160:163], v[210:213], v[8:11]
	v_mfma_f32_16x16x32_bf16 v[60:63], v[156:159], v[188:191], v[60:63]
	v_mfma_f32_16x16x32_bf16 v[56:59], v[164:167], v[188:191], v[56:59]
	v_mfma_f32_16x16x32_bf16 v[44:47], v[156:159], v[196:199], v[44:47]
	v_mfma_f32_16x16x32_bf16 v[40:43], v[164:167], v[196:199], v[40:43]
	v_mfma_f32_16x16x32_bf16 v[28:31], v[156:159], v[206:209], v[28:31]
	v_mfma_f32_16x16x32_bf16 v[24:27], v[164:167], v[206:209], v[24:27]
	v_mfma_f32_16x16x32_bf16 v[12:15], v[156:159], v[214:217], v[12:15]
	v_mfma_f32_16x16x32_bf16 v[8:11], v[164:167], v[214:217], v[8:11]
	v_mfma_f32_16x16x32_bf16 v[52:55], v[168:171], v[184:187], v[52:55]
	v_mfma_f32_16x16x32_bf16 v[48:51], v[176:179], v[184:187], v[48:51]
	v_mfma_f32_16x16x32_bf16 v[36:39], v[168:171], v[192:195], v[36:39]
	v_mfma_f32_16x16x32_bf16 v[32:35], v[176:179], v[192:195], v[32:35]
	v_mfma_f32_16x16x32_bf16 v[20:23], v[168:171], v[200:203], v[20:23]
	v_mfma_f32_16x16x32_bf16 v[16:19], v[176:179], v[200:203], v[16:19]
	v_mfma_f32_16x16x32_bf16 v[4:7], v[168:171], v[210:213], v[4:7]
	v_mfma_f32_16x16x32_bf16 v[0:3], v[176:179], v[210:213], v[0:3]
	v_mfma_f32_16x16x32_bf16 v[52:55], v[172:175], v[188:191], v[52:55]
	v_mfma_f32_16x16x32_bf16 v[48:51], v[180:183], v[188:191], v[48:51]
	v_mfma_f32_16x16x32_bf16 v[36:39], v[172:175], v[196:199], v[36:39]
	v_mfma_f32_16x16x32_bf16 v[32:35], v[180:183], v[196:199], v[32:35]
	v_mfma_f32_16x16x32_bf16 v[20:23], v[172:175], v[206:209], v[20:23]
	v_mfma_f32_16x16x32_bf16 v[16:19], v[180:183], v[206:209], v[16:19]
	v_mfma_f32_16x16x32_bf16 v[4:7], v[172:175], v[214:217], v[4:7]
	v_mfma_f32_16x16x32_bf16 v[0:3], v[180:183], v[214:217], v[0:3]
	s_setprio 0
	s_barrier
; #define PG8_STAGE(bufoff, gbase, voff) do { _Pragma("unroll") for (int _i = 0; _i < 2; ++_i) \
;         __builtin_amdgcn_global_load_lds((const unsigned*)((const char*)(gbase) + (voff)[_i]), (PG8_LAS unsigned*)(lds + (bufoff) + ldsw + _i * 8192), 16, 0, 0); } while (0)
; #define PG8_LDA(dst, b, h) do { _Pragma("unroll") for (int m = 0; m < 4; ++m) _Pragma("unroll") for (int k = 0; k < 2; ++k) dst[m][k] = *(const PG8_LAS bf16x8*)(lds + PG8_SA(b, h) + aoff + m * 2048 + k * 1024); } while (0)
; #define PG8_LDB(dst, b, h) do { _Pragma("unroll") for (int n = 0; n < 2; ++n) _Pragma("unroll") for (int k = 0; k < 2; ++k) dst[n][k] = *(const PG8_LAS bf16x8*)(lds + PG8_SB(b, h) + boff + n * 2048 + k * 1024); } while (0)
; #define PG8_MMA(ai, bj, At, Bt) do { __builtin_amdgcn_s_setprio(1); _Pragma("unroll") for (int m = 0; m < 4; ++m) _Pragma("unroll") for (int n = 0; n < 2; ++n) _Pragma("unroll") for (int k = 0; k < 2; ++k) \
;         acc[ai][bj][m][n] = __builtin_amdgcn_mfma_f32_16x16x32_bf16(Bt[n][k], At[m][k], acc[ai][bj][m][n], 0, 0, 0); __builtin_amdgcn_s_setprio(0); } while (0)
; #define PG8_WAIT_V(n) asm volatile("s_waitcnt vmcnt(" #n ")" ::: "memory")
; #define PG8_WAIT_L(n) asm volatile("s_waitcnt lgkmcnt(" #n ")" ::: "memory")
; #define PG8_BAR __builtin_amdgcn_s_barrier()
; #define PG8_SCHED __builtin_amdgcn_sched_barrier(0)
; template <class Epi, class Sched, bool ALIGN_EPI = false, bool SP2 = false>
; __device__ __forceinline__ void gemm_phase(PG8_LAS unsigned char* lds, const Gemm g, const Sched& S, const Epi& E) {
;     ...
;             PG8_LDB(B0, 1, 0); PG8_LDB(B1, 1, 1); PG8_SCHED; PG8_LDA(At, 1, 0); PG8_STAGE(PG8_SA(0, 1), a2 + hstep, voffA);
;             PG8_WAIT_V(8); PG8_WAIT_L(0); PG8_BAR; PG8_MMA(0, 0, At, B0); PG8_MMA(0, 1, At, B1); PG8_BAR; PG8_SCHED;
;             PG8_LDA(At, 1, 1); PG8_STAGE(PG8_SB(1, 0), b3, voffB); PG8_STAGE(PG8_SB(1, 1), b3 + hstep, voffB); PG8_STAGE(PG8_SA(1, 0), a3, voffA);
;             PG8_WAIT_V(8); PG8_WAIT_L(0); PG8_BAR; PG8_MMA(1, 0, At, B0); PG8_MMA(1, 1, At, B1); PG8_BAR; PG8_SCHED;
	s_add_i32 s64, 0, 0x18000
	s_add_i32 s65, 0, 0x1c000
	ds_read_b128 v[146:149], v240
	ds_read_b128 v[156:159], v240 offset:1024
	ds_read_b128 v[160:163], v240 offset:2048
	ds_read_b128 v[164:167], v240 offset:3072
	ds_read_b128 v[168:171], v241
	ds_read_b128 v[172:175], v241 offset:1024
	ds_read_b128 v[176:179], v241 offset:2048
	ds_read_b128 v[180:183], v241 offset:3072
	s_add_u32 s100, s48, 0x80
	s_addc_u32 s101, s49, 0
	s_add_u32 s48, s48, 0x40000
	s_addc_u32 s49, s49, 0
	s_mov_b32 m0, s51
	ds_read_b128 v[184:187], v154 offset:32768
	ds_read_b128 v[188:191], v154 offset:33792
	ds_read_b128 v[192:195], v154 offset:34816
	ds_read_b128 v[196:199], v154 offset:35840
	ds_read_b128 v[200:203], v154 offset:36864
	ds_read_b128 v[206:209], v154 offset:37888
	ds_read_b128 v[210:213], v154 offset:38912
	ds_read_b128 v[214:217], v154 offset:39936
	global_load_lds_dwordx4 v130, s[48:49]
	s_mov_b32 m0, s52
	s_nop 0
	global_load_lds_dwordx4 v134, s[48:49]
	s_waitcnt vmcnt(8)
	s_waitcnt lgkmcnt(0)
	s_setprio 1
	s_barrier
	v_mfma_f32_16x16x32_bf16 v[124:127], v[146:149], v[184:187], v[124:127]
	v_mfma_f32_16x16x32_bf16 v[120:123], v[160:163], v[184:187], v[120:123]
	v_mfma_f32_16x16x32_bf16 v[108:111], v[146:149], v[192:195], v[108:111]
	v_mfma_f32_16x16x32_bf16 v[104:107], v[160:163], v[192:195], v[104:107]
	v_mfma_f32_16x16x32_bf16 v[92:95], v[146:149], v[200:203], v[92:95]
	v_mfma_f32_16x16x32_bf16 v[88:91], v[160:163], v[200:203], v[88:91]
	v_mfma_f32_16x16x32_bf16 v[76:79], v[146:149], v[210:213], v[76:79]
	v_mfma_f32_16x16x32_bf16 v[72:75], v[160:163], v[210:213], v[72:75]
	v_mfma_f32_16x16x32_bf16 v[124:127], v[156:159], v[188:191], v[124:127]
	v_mfma_f32_16x16x32_bf16 v[120:123], v[164:167], v[188:191], v[120:123]
	v_mfma_f32_16x16x32_bf16 v[108:111], v[156:159], v[196:199], v[108:111]
	v_mfma_f32_16x16x32_bf16 v[104:107], v[164:167], v[196:199], v[104:107]
	v_mfma_f32_16x16x32_bf16 v[92:95], v[156:159], v[206:209], v[92:95]
	v_mfma_f32_16x16x32_bf16 v[88:91], v[164:167], v[206:209], v[88:91]
	v_mfma_f32_16x16x32_bf16 v[76:79], v[156:159], v[214:217], v[76:79]
	v_mfma_f32_16x16x32_bf16 v[72:75], v[164:167], v[214:217], v[72:75]
	v_mfma_f32_16x16x32_bf16 v[116:119], v[168:171], v[184:187], v[116:119]
	v_mfma_f32_16x16x32_bf16 v[112:115], v[176:179], v[184:187], v[112:115]
	v_mfma_f32_16x16x32_bf16 v[100:103], v[168:171], v[192:195], v[100:103]
	v_mfma_f32_16x16x32_bf16 v[96:99], v[176:179], v[192:195], v[96:99]
	v_mfma_f32_16x16x32_bf16 v[84:87], v[168:171], v[200:203], v[84:87]
	v_mfma_f32_16x16x32_bf16 v[80:83], v[176:179], v[200:203], v[80:83]
	v_mfma_f32_16x16x32_bf16 v[68:71], v[168:171], v[210:213], v[68:71]
	v_mfma_f32_16x16x32_bf16 v[64:67], v[176:179], v[210:213], v[64:67]
	v_mfma_f32_16x16x32_bf16 v[116:119], v[172:175], v[188:191], v[116:119]
	v_mfma_f32_16x16x32_bf16 v[112:115], v[180:183], v[188:191], v[112:115]
	v_mfma_f32_16x16x32_bf16 v[100:103], v[172:175], v[196:199], v[100:103]
	v_mfma_f32_16x16x32_bf16 v[96:99], v[180:183], v[196:199], v[96:99]
	v_mfma_f32_16x16x32_bf16 v[84:87], v[172:175], v[206:209], v[84:87]
	v_mfma_f32_16x16x32_bf16 v[80:83], v[180:183], v[206:209], v[80:83]
	v_mfma_f32_16x16x32_bf16 v[68:71], v[172:175], v[214:217], v[68:71]
	v_mfma_f32_16x16x32_bf16 v[64:67], v[180:183], v[214:217], v[64:67]
	s_setprio 0
	s_barrier
	s_add_i32 s48, s64, s13
	s_mov_b32 m0, s48
	ds_read_b128 v[184:187], v154 offset:49152
	ds_read_b128 v[188:191], v154 offset:50176
	ds_read_b128 v[192:195], v154 offset:51200
	ds_read_b128 v[196:199], v154 offset:52224
	ds_read_b128 v[200:203], v154 offset:53248
	ds_read_b128 v[206:209], v154 offset:54272
	ds_read_b128 v[210:213], v154 offset:55296
	ds_read_b128 v[214:217], v154 offset:56320
	global_load_lds_dwordx4 v132, s[98:99]
	s_add_i32 m0, s48, 0x2000
	s_add_u32 s46, s46, 0x40080
	s_addc_u32 s47, s47, 0
	s_add_i32 s48, s65, s13
	global_load_lds_dwordx4 v136, s[98:99]
	s_mov_b32 m0, s48
	s_nop 0
	global_load_lds_dwordx4 v132, s[46:47]
	s_add_i32 m0, s48, 0x2000
	s_nop 0
	global_load_lds_dwordx4 v136, s[46:47]
	s_mov_b32 m0, s54
	s_nop 0
	global_load_lds_dwordx4 v130, s[100:101]
	s_mov_b32 m0, s55
	s_nop 0
	global_load_lds_dwordx4 v134, s[100:101]
	s_waitcnt vmcnt(8)
	s_waitcnt lgkmcnt(0)
	s_setprio 1
	s_barrier
	v_mfma_f32_16x16x32_bf16 v[60:63], v[146:149], v[184:187], v[60:63]
	v_mfma_f32_16x16x32_bf16 v[56:59], v[160:163], v[184:187], v[56:59]
	v_mfma_f32_16x16x32_bf16 v[44:47], v[146:149], v[192:195], v[44:47]
	v_mfma_f32_16x16x32_bf16 v[40:43], v[160:163], v[192:195], v[40:43]
	v_mfma_f32_16x16x32_bf16 v[28:31], v[146:149], v[200:203], v[28:31]
	v_mfma_f32_16x16x32_bf16 v[24:27], v[160:163], v[200:203], v[24:27]
	v_mfma_f32_16x16x32_bf16 v[12:15], v[146:149], v[210:213], v[12:15]
	v_mfma_f32_16x16x32_bf16 v[8:11], v[160:163], v[210:213], v[8:11]
	v_mfma_f32_16x16x32_bf16 v[60:63], v[156:159], v[188:191], v[60:63]
	v_mfma_f32_16x16x32_bf16 v[56:59], v[164:167], v[188:191], v[56:59]
	v_mfma_f32_16x16x32_bf16 v[44:47], v[156:159], v[196:199], v[44:47]
	v_mfma_f32_16x16x32_bf16 v[40:43], v[164:167], v[196:199], v[40:43]
	v_mfma_f32_16x16x32_bf16 v[28:31], v[156:159], v[206:209], v[28:31]
	v_mfma_f32_16x16x32_bf16 v[24:27], v[164:167], v[206:209], v[24:27]
	v_mfma_f32_16x16x32_bf16 v[12:15], v[156:159], v[214:217], v[12:15]
	v_mfma_f32_16x16x32_bf16 v[8:11], v[164:167], v[214:217], v[8:11]
	v_mfma_f32_16x16x32_bf16 v[52:55], v[168:171], v[184:187], v[52:55]
	v_mfma_f32_16x16x32_bf16 v[48:51], v[176:179], v[184:187], v[48:51]
	v_mfma_f32_16x16x32_bf16 v[36:39], v[168:171], v[192:195], v[36:39]
	v_mfma_f32_16x16x32_bf16 v[32:35], v[176:179], v[192:195], v[32:35]
	v_mfma_f32_16x16x32_bf16 v[20:23], v[168:171], v[200:203], v[20:23]
	v_mfma_f32_16x16x32_bf16 v[16:19], v[176:179], v[200:203], v[16:19]
	v_mfma_f32_16x16x32_bf16 v[4:7], v[168:171], v[210:213], v[4:7]
	v_mfma_f32_16x16x32_bf16 v[0:3], v[176:179], v[210:213], v[0:3]
	v_mfma_f32_16x16x32_bf16 v[52:55], v[172:175], v[188:191], v[52:55]
	v_mfma_f32_16x16x32_bf16 v[48:51], v[180:183], v[188:191], v[48:51]
	v_mfma_f32_16x16x32_bf16 v[36:39], v[172:175], v[196:199], v[36:39]
	v_mfma_f32_16x16x32_bf16 v[32:35], v[180:183], v[196:199], v[32:35]
	v_mfma_f32_16x16x32_bf16 v[20:23], v[172:175], v[206:209], v[20:23]
	v_mfma_f32_16x16x32_bf16 v[16:19], v[180:183], v[206:209], v[16:19]
	v_mfma_f32_16x16x32_bf16 v[4:7], v[172:175], v[214:217], v[4:7]
	v_mfma_f32_16x16x32_bf16 v[0:3], v[180:183], v[214:217], v[0:3]
	s_setprio 0
	s_barrier
	s_add_i32 s63, s63, 2
	s_add_u32 s44, s44, 0x100
	s_addc_u32 s45, s45, 0
	s_add_u32 s61, s61, 0x100
	s_addc_u32 s62, s62, 0
	s_cmp_gt_u32 s63, 13
	s_cbranch_scc0 .LBB0_520
	s_and_b64 vcc, exec, s[28:29]
	s_cbranch_vccz .LBB0_523
	s_barrier

; #define PG8_STAGE(bufoff, gbase, voff) do { _Pragma("unroll") for (int _i = 0; _i < 2; ++_i) \
;         __builtin_amdgcn_global_load_lds((const unsigned*)((const char*)(gbase) + (voff)[_i]), (PG8_LAS unsigned*)(lds + (bufoff) + ldsw + _i * 8192), 16, 0, 0); } while (0)
; #define PG8_LDA(dst, b, h) do { _Pragma("unroll") for (int m = 0; m < 4; ++m) _Pragma("unroll") for (int k = 0; k < 2; ++k) dst[m][k] = *(const PG8_LAS bf16x8*)(lds + PG8_SA(b, h) + aoff + m * 2048 + k * 1024); } while (0)
; #define PG8_LDB(dst, b, h) do { _Pragma("unroll") for (int n = 0; n < 2; ++n) _Pragma("unroll") for (int k = 0; k < 2; ++k) dst[n][k] = *(const PG8_LAS bf16x8*)(lds + PG8_SB(b, h) + boff + n * 2048 + k * 1024); } while (0)
; #define PG8_WAIT_V(n) asm volatile("s_waitcnt vmcnt(" #n ")" ::: "memory")
; #define PG8_WAIT_L(n) asm volatile("s_waitcnt lgkmcnt(" #n ")" ::: "memory")
; #define PG8_BAR __builtin_amdgcn_s_barrier()
; #define PG8_SCHED __builtin_amdgcn_sched_barrier(0)
; template <class Epi, class Sched, bool ALIGN_EPI = false, bool SP2 = false>
; __device__ __forceinline__ void gemm_phase(PG8_LAS unsigned char* lds, const Gemm g, const Sched& S, const Epi& E) {
;     ...
;         const char* nA = has_next ? (const char*)g.A + (size_t)nxt.pm * tstep : cA; const char* nB = has_next ? (const char*)g.Bt + (size_t)nxt.pn * tstep : cB;
;         for (int t = 0; t < nt; t += 2) {
;             const bool last = (t == nt - 2);
;             const char* a1 = cA + (size_t)(t + 1) * kstep;
;             const char* a2 = last ? nA : cA + (size_t)(t + 2) * kstep; const char* b2 = last ? nB : cB + (size_t)(t + 2) * kstep;
;             const char* a3 = a2 + kstep; const char* b3 = b2 + kstep;
;             if (last && has_next) S.a_ready(nxt);
;             if constexpr (SP2) {
;             PG8_LDB(B0, 0, 0); PG8_LDB(B1, 0, 1); PG8_SCHED; PG8_LDA(At, 0, 0); PG8_STAGE(PG8_SA(1, 1), a1 + hstep, voffA);
;             PG8_WAIT_V(8); PG8_WAIT_L(0); PG8_BAR; PG8_MMA(0, 0, At, B0); PG8_MMA(0, 1, At, B1); PG8_BAR; PG8_SCHED;
;     ...
;         for (int a = 0; a < 2; ++a)
; #pragma unroll
;             for (int b = 0; b < 2; ++b)
; #pragma unroll
;                 for (int m = 0; m < 4; ++m)
; #pragma unroll
;                     for (int n = 0; n < 2; ++n) acc[a][b][m][n] = (f32x4){0.f, 0.f, 0.f, 0.f};
.LBB0_626:
	s_ashr_i32 s37, s36, 31
	s_lshl_b64 s[38:39], s[36:37], 19
	s_add_u32 s38, s96, s38
	s_addc_u32 s39, s97, s39
	s_and_b64 s[40:41], s[4:5], exec
	s_cselect_b32 s37, s39, s43
	s_cselect_b32 s60, s38, s42
	s_ashr_i32 s35, s34, 31
	s_lshl_b64 s[40:41], s[34:35], 19
	v_readlane_b32 s14, v255, 30
	v_readlane_b32 s15, v255, 31
	s_add_u32 s40, s14, s40
	s_addc_u32 s41, s15, s41
	s_and_b64 s[46:47], s[4:5], exec
	s_cselect_b32 s35, s41, s45
	s_cselect_b32 s61, s40, s44
	s_add_u32 s42, s42, 0x40080
	s_addc_u32 s43, s43, 0
	s_add_u32 s62, s44, 0x100
	v_mov_b32_e32 v0, 0
	s_addc_u32 s63, s45, 0
	s_mov_b32 s64, -2
	v_mov_b32_e32 v1, v0
	v_mov_b32_e32 v2, v0
	v_mov_b32_e32 v3, v0
	v_mov_b32_e32 v4, v0
	v_mov_b32_e32 v5, v0
	v_mov_b32_e32 v6, v0
	v_mov_b32_e32 v7, v0
	v_mov_b32_e32 v16, v0
	v_mov_b32_e32 v17, v0
	v_mov_b32_e32 v18, v0
	v_mov_b32_e32 v19, v0
	v_mov_b32_e32 v20, v0
	v_mov_b32_e32 v21, v0
	v_mov_b32_e32 v22, v0
	v_mov_b32_e32 v23, v0
	v_mov_b32_e32 v32, v0
	v_mov_b32_e32 v33, v0
	v_mov_b32_e32 v34, v0
	v_mov_b32_e32 v35, v0
	v_mov_b32_e32 v36, v0
	v_mov_b32_e32 v37, v0
	v_mov_b32_e32 v38, v0
	v_mov_b32_e32 v39, v0
	v_mov_b32_e32 v48, v0
	v_mov_b32_e32 v49, v0
	v_mov_b32_e32 v50, v0
	v_mov_b32_e32 v51, v0
	v_mov_b32_e32 v52, v0
	v_mov_b32_e32 v53, v0
	v_mov_b32_e32 v54, v0
	v_mov_b32_e32 v55, v0
	v_mov_b32_e32 v8, v0
	v_mov_b32_e32 v9, v0
	v_mov_b32_e32 v10, v0
	v_mov_b32_e32 v11, v0
	v_mov_b32_e32 v12, v0
	v_mov_b32_e32 v13, v0
	v_mov_b32_e32 v14, v0
	v_mov_b32_e32 v15, v0
	v_mov_b32_e32 v24, v0
	v_mov_b32_e32 v25, v0
	v_mov_b32_e32 v26, v0
	v_mov_b32_e32 v27, v0
	v_mov_b32_e32 v28, v0
	v_mov_b32_e32 v29, v0
	v_mov_b32_e32 v30, v0
	v_mov_b32_e32 v31, v0
	v_mov_b32_e32 v40, v0
	v_mov_b32_e32 v41, v0
	v_mov_b32_e32 v42, v0
	v_mov_b32_e32 v43, v0
	v_mov_b32_e32 v44, v0
	v_mov_b32_e32 v45, v0
	v_mov_b32_e32 v46, v0
	v_mov_b32_e32 v47, v0
	v_mov_b32_e32 v56, v0
	v_mov_b32_e32 v57, v0
	v_mov_b32_e32 v58, v0
	v_mov_b32_e32 v59, v0
	v_mov_b32_e32 v60, v0
	v_mov_b32_e32 v61, v0
	v_mov_b32_e32 v62, v0
	v_mov_b32_e32 v63, v0
	v_mov_b32_e32 v64, v0
	v_mov_b32_e32 v65, v0
	v_mov_b32_e32 v66, v0
	v_mov_b32_e32 v67, v0
	v_mov_b32_e32 v68, v0
	v_mov_b32_e32 v69, v0
	v_mov_b32_e32 v70, v0
	v_mov_b32_e32 v71, v0
	v_mov_b32_e32 v80, v0
	v_mov_b32_e32 v81, v0
	v_mov_b32_e32 v82, v0
	v_mov_b32_e32 v83, v0
	v_mov_b32_e32 v84, v0
	v_mov_b32_e32 v85, v0
	v_mov_b32_e32 v86, v0
	v_mov_b32_e32 v87, v0
	v_mov_b32_e32 v96, v0
	v_mov_b32_e32 v97, v0
	v_mov_b32_e32 v98, v0
	v_mov_b32_e32 v99, v0
	v_mov_b32_e32 v100, v0
	v_mov_b32_e32 v101, v0
	v_mov_b32_e32 v102, v0
	v_mov_b32_e32 v103, v0
	v_mov_b32_e32 v112, v0
	v_mov_b32_e32 v113, v0
	v_mov_b32_e32 v114, v0
	v_mov_b32_e32 v115, v0
	v_mov_b32_e32 v116, v0
	v_mov_b32_e32 v117, v0
	v_mov_b32_e32 v118, v0
	v_mov_b32_e32 v119, v0
	v_mov_b32_e32 v72, v0
	v_mov_b32_e32 v73, v0
	v_mov_b32_e32 v74, v0
	v_mov_b32_e32 v75, v0
	v_mov_b32_e32 v76, v0
	v_mov_b32_e32 v77, v0
	v_mov_b32_e32 v78, v0
	v_mov_b32_e32 v79, v0
	v_mov_b32_e32 v88, v0
	v_mov_b32_e32 v89, v0
	v_mov_b32_e32 v90, v0
	v_mov_b32_e32 v91, v0
	v_mov_b32_e32 v92, v0
	v_mov_b32_e32 v93, v0
	v_mov_b32_e32 v94, v0
	v_mov_b32_e32 v95, v0
	v_mov_b32_e32 v104, v0
	v_mov_b32_e32 v105, v0
	v_mov_b32_e32 v106, v0
	v_mov_b32_e32 v107, v0
	v_mov_b32_e32 v108, v0
	v_mov_b32_e32 v109, v0
	v_mov_b32_e32 v110, v0
	v_mov_b32_e32 v111, v0
	v_mov_b32_e32 v120, v0
	v_mov_b32_e32 v121, v0
	v_mov_b32_e32 v122, v0
	v_mov_b32_e32 v123, v0
	v_mov_b32_e32 v124, v0
	v_mov_b32_e32 v125, v0
	v_mov_b32_e32 v126, v0
	v_mov_b32_e32 v127, v0
	v_add_u32_e32 v240, 0x18000, v148
	v_add_u32_e32 v241, 0x1c000, v148
.LBB0_627:
	ds_read_b128 v[154:157], v149
	ds_read_b128 v[158:161], v149 offset:1024
	ds_read_b128 v[162:165], v149 offset:2048
	ds_read_b128 v[166:169], v149 offset:3072
	ds_read_b128 v[170:173], v150
	ds_read_b128 v[174:177], v150 offset:1024
	ds_read_b128 v[178:181], v150 offset:2048
	ds_read_b128 v[182:185], v150 offset:3072
	s_add_u32 s44, s42, 0xfffc0080
	s_addc_u32 s45, s43, -1
	s_cmp_eq_u32 s64, 12
	s_cselect_b32 s47, s37, s45
	s_cselect_b32 s46, s60, s44
	s_cselect_b32 s45, s35, s63
	s_cselect_b32 s44, s61, s62
	s_add_i32 m0, s48, 0xc000
	ds_read_b128 v[186:189], v151
	ds_read_b128 v[190:193], v151 offset:1024
	ds_read_b128 v[194:197], v151 offset:2048
	ds_read_b128 v[198:201], v151 offset:3072
	ds_read_b128 v[206:209], v151 offset:4096
	ds_read_b128 v[210:213], v151 offset:5120
	ds_read_b128 v[214:217], v151 offset:6144
	ds_read_b128 v[218:221], v151 offset:7168
	global_load_lds_dwordx4 v138, s[42:43]
	s_add_i32 m0, s48, 0xe000
	s_nop 0
	global_load_lds_dwordx4 v140, s[42:43]
	s_waitcnt vmcnt(8)
	s_waitcnt lgkmcnt(0)
	s_setprio 1
	s_barrier
; #define PG8_STAGE(bufoff, gbase, voff) do { _Pragma("unroll") for (int _i = 0; _i < 2; ++_i) \
;         __builtin_amdgcn_global_load_lds((const unsigned*)((const char*)(gbase) + (voff)[_i]), (PG8_LAS unsigned*)(lds + (bufoff) + ldsw + _i * 8192), 16, 0, 0); } while (0)
; #define PG8_LDA(dst, b, h) do { _Pragma("unroll") for (int m = 0; m < 4; ++m) _Pragma("unroll") for (int k = 0; k < 2; ++k) dst[m][k] = *(const PG8_LAS bf16x8*)(lds + PG8_SA(b, h) + aoff + m * 2048 + k * 1024); } while (0)
; #define PG8_MMA(ai, bj, At, Bt) do { __builtin_amdgcn_s_setprio(1); _Pragma("unroll") for (int m = 0; m < 4; ++m) _Pragma("unroll") for (int n = 0; n < 2; ++n) _Pragma("unroll") for (int k = 0; k < 2; ++k) \
;         acc[ai][bj][m][n] = __builtin_amdgcn_mfma_f32_16x16x32_bf16(Bt[n][k], At[m][k], acc[ai][bj][m][n], 0, 0, 0); __builtin_amdgcn_s_setprio(0); } while (0)
; #define PG8_WAIT_V(n) asm volatile("s_waitcnt vmcnt(" #n ")" ::: "memory")
; #define PG8_WAIT_L(n) asm volatile("s_waitcnt lgkmcnt(" #n ")" ::: "memory")
; #define PG8_BAR __builtin_amdgcn_s_barrier()
; #define PG8_SCHED __builtin_amdgcn_sched_barrier(0)
; template <class Epi, class Sched, bool ALIGN_EPI = false, bool SP2 = false>
; __device__ __forceinline__ void gemm_phase(PG8_LAS unsigned char* lds, const Gemm g, const Sched& S, const Epi& E) {
;     ...
;             PG8_WAIT_V(8); PG8_WAIT_L(0); PG8_BAR; PG8_MMA(0, 0, At, B0); PG8_MMA(0, 1, At, B1); PG8_BAR; PG8_SCHED;
;             PG8_LDA(At, 0, 1); PG8_STAGE(PG8_SB(0, 0), b2, voffB); PG8_STAGE(PG8_SB(0, 1), b2 + hstep, voffB); PG8_STAGE(PG8_SA(0, 0), a2, voffA);
;             PG8_WAIT_V(8); PG8_WAIT_L(0); PG8_BAR; PG8_MMA(1, 0, At, B0); PG8_MMA(1, 1, At, B1); PG8_BAR; PG8_SCHED;
	v_mfma_f32_16x16x32_bf16 v[124:127], v[154:157], v[186:189], v[124:127]
	v_mfma_f32_16x16x32_bf16 v[120:123], v[162:165], v[186:189], v[120:123]
	v_mfma_f32_16x16x32_bf16 v[108:111], v[154:157], v[194:197], v[108:111]
	v_mfma_f32_16x16x32_bf16 v[104:107], v[162:165], v[194:197], v[104:107]
	v_mfma_f32_16x16x32_bf16 v[92:95], v[154:157], v[206:209], v[92:95]
	v_mfma_f32_16x16x32_bf16 v[88:91], v[162:165], v[206:209], v[88:91]
	v_mfma_f32_16x16x32_bf16 v[76:79], v[154:157], v[214:217], v[76:79]
	v_mfma_f32_16x16x32_bf16 v[72:75], v[162:165], v[214:217], v[72:75]
	v_mfma_f32_16x16x32_bf16 v[124:127], v[158:161], v[190:193], v[124:127]
	v_mfma_f32_16x16x32_bf16 v[120:123], v[166:169], v[190:193], v[120:123]
	v_mfma_f32_16x16x32_bf16 v[108:111], v[158:161], v[198:201], v[108:111]
	v_mfma_f32_16x16x32_bf16 v[104:107], v[166:169], v[198:201], v[104:107]
	v_mfma_f32_16x16x32_bf16 v[92:95], v[158:161], v[210:213], v[92:95]
	v_mfma_f32_16x16x32_bf16 v[88:91], v[166:169], v[210:213], v[88:91]
	v_mfma_f32_16x16x32_bf16 v[76:79], v[158:161], v[218:221], v[76:79]
	v_mfma_f32_16x16x32_bf16 v[72:75], v[166:169], v[218:221], v[72:75]
	v_mfma_f32_16x16x32_bf16 v[116:119], v[170:173], v[186:189], v[116:119]
	v_mfma_f32_16x16x32_bf16 v[112:115], v[178:181], v[186:189], v[112:115]
	v_mfma_f32_16x16x32_bf16 v[100:103], v[170:173], v[194:197], v[100:103]
	v_mfma_f32_16x16x32_bf16 v[96:99], v[178:181], v[194:197], v[96:99]
	v_mfma_f32_16x16x32_bf16 v[84:87], v[170:173], v[206:209], v[84:87]
	v_mfma_f32_16x16x32_bf16 v[80:83], v[178:181], v[206:209], v[80:83]
	v_mfma_f32_16x16x32_bf16 v[68:71], v[170:173], v[214:217], v[68:71]
	v_mfma_f32_16x16x32_bf16 v[64:67], v[178:181], v[214:217], v[64:67]
	v_mfma_f32_16x16x32_bf16 v[116:119], v[174:177], v[190:193], v[116:119]
	v_mfma_f32_16x16x32_bf16 v[112:115], v[182:185], v[190:193], v[112:115]
	v_mfma_f32_16x16x32_bf16 v[100:103], v[174:177], v[198:201], v[100:103]
	v_mfma_f32_16x16x32_bf16 v[96:99], v[182:185], v[198:201], v[96:99]
	v_mfma_f32_16x16x32_bf16 v[84:87], v[174:177], v[210:213], v[84:87]
	v_mfma_f32_16x16x32_bf16 v[80:83], v[182:185], v[210:213], v[80:83]
	v_mfma_f32_16x16x32_bf16 v[68:71], v[174:177], v[218:221], v[68:71]
	v_mfma_f32_16x16x32_bf16 v[64:67], v[182:185], v[218:221], v[64:67]
	s_setprio 0
	s_barrier
	s_add_i32 s65, s57, s13
	s_mov_b32 m0, s65
	ds_read_b128 v[186:189], v151 offset:16384
	ds_read_b128 v[190:193], v151 offset:17408
	ds_read_b128 v[194:197], v151 offset:18432
	ds_read_b128 v[198:201], v151 offset:19456
	ds_read_b128 v[206:209], v151 offset:20480
	ds_read_b128 v[210:213], v151 offset:21504
	ds_read_b128 v[214:217], v151 offset:22528
	ds_read_b128 v[218:221], v151 offset:23552
	global_load_lds_dwordx4 v132, s[44:45]
	s_add_i32 m0, s65, 0x2000
	s_add_u32 s98, s44, 0x80
	s_addc_u32 s99, s45, 0
	s_add_u32 s66, s44, 0x40000
	s_addc_u32 s67, s45, 0
	s_add_i32 s65, s58, s13
	global_load_lds_dwordx4 v136, s[44:45]
	s_mov_b32 m0, s65
	s_nop 0
	global_load_lds_dwordx4 v132, s[66:67]
	s_add_i32 m0, s65, 0x2000
	s_nop 0
	global_load_lds_dwordx4 v136, s[66:67]
	s_mov_b32 m0, s48
	s_nop 0
	global_load_lds_dwordx4 v130, s[46:47]
	s_mov_b32 m0, s49
	s_nop 0
	global_load_lds_dwordx4 v134, s[46:47]
	s_waitcnt vmcnt(8)
	s_waitcnt lgkmcnt(0)
	s_setprio 1
	s_barrier
	v_mfma_f32_16x16x32_bf16 v[60:63], v[154:157], v[186:189], v[60:63]
	v_mfma_f32_16x16x32_bf16 v[56:59], v[162:165], v[186:189], v[56:59]
	v_mfma_f32_16x16x32_bf16 v[44:47], v[154:157], v[194:197], v[44:47]
	v_mfma_f32_16x16x32_bf16 v[40:43], v[162:165], v[194:197], v[40:43]
	v_mfma_f32_16x16x32_bf16 v[28:31], v[154:157], v[206:209], v[28:31]
	v_mfma_f32_16x16x32_bf16 v[24:27], v[162:165], v[206:209], v[24:27]
	v_mfma_f32_16x16x32_bf16 v[12:15], v[154:157], v[214:217], v[12:15]
	v_mfma_f32_16x16x32_bf16 v[8:11], v[162:165], v[214:217], v[8:11]
	v_mfma_f32_16x16x32_bf16 v[60:63], v[158:161], v[190:193], v[60:63]
	v_mfma_f32_16x16x32_bf16 v[56:59], v[166:169], v[190:193], v[56:59]
	v_mfma_f32_16x16x32_bf16 v[44:47], v[158:161], v[198:201], v[44:47]
	v_mfma_f32_16x16x32_bf16 v[40:43], v[166:169], v[198:201], v[40:43]
	v_mfma_f32_16x16x32_bf16 v[28:31], v[158:161], v[210:213], v[28:31]
	v_mfma_f32_16x16x32_bf16 v[24:27], v[166:169], v[210:213], v[24:27]
	v_mfma_f32_16x16x32_bf16 v[12:15], v[158:161], v[218:221], v[12:15]
	v_mfma_f32_16x16x32_bf16 v[8:11], v[166:169], v[218:221], v[8:11]
	v_mfma_f32_16x16x32_bf16 v[52:55], v[170:173], v[186:189], v[52:55]
	v_mfma_f32_16x16x32_bf16 v[48:51], v[178:181], v[186:189], v[48:51]
	v_mfma_f32_16x16x32_bf16 v[36:39], v[170:173], v[194:197], v[36:39]
	v_mfma_f32_16x16x32_bf16 v[32:35], v[178:181], v[194:197], v[32:35]
	v_mfma_f32_16x16x32_bf16 v[20:23], v[170:173], v[206:209], v[20:23]
	v_mfma_f32_16x16x32_bf16 v[16:19], v[178:181], v[206:209], v[16:19]
	v_mfma_f32_16x16x32_bf16 v[4:7], v[170:173], v[214:217], v[4:7]
	v_mfma_f32_16x16x32_bf16 v[0:3], v[178:181], v[214:217], v[0:3]
	v_mfma_f32_16x16x32_bf16 v[52:55], v[174:177], v[190:193], v[52:55]
	v_mfma_f32_16x16x32_bf16 v[48:51], v[182:185], v[190:193], v[48:51]
	v_mfma_f32_16x16x32_bf16 v[36:39], v[174:177], v[198:201], v[36:39]
	v_mfma_f32_16x16x32_bf16 v[32:35], v[182:185], v[198:201], v[32:35]
	v_mfma_f32_16x16x32_bf16 v[20:23], v[174:177], v[210:213], v[20:23]
	v_mfma_f32_16x16x32_bf16 v[16:19], v[182:185], v[210:213], v[16:19]
	v_mfma_f32_16x16x32_bf16 v[4:7], v[174:177], v[218:221], v[4:7]
	v_mfma_f32_16x16x32_bf16 v[0:3], v[182:185], v[218:221], v[0:3]
	s_setprio 0
	s_barrier
; #define PG8_STAGE(bufoff, gbase, voff) do { _Pragma("unroll") for (int _i = 0; _i < 2; ++_i) \
;         __builtin_amdgcn_global_load_lds((const unsigned*)((const char*)(gbase) + (voff)[_i]), (PG8_LAS unsigned*)(lds + (bufoff) + ldsw + _i * 8192), 16, 0, 0); } while (0)
; #define PG8_LDA(dst, b, h) do { _Pragma("unroll") for (int m = 0; m < 4; ++m) _Pragma("unroll") for (int k = 0; k < 2; ++k) dst[m][k] = *(const PG8_LAS bf16x8*)(lds + PG8_SA(b, h) + aoff + m * 2048 + k * 1024); } while (0)
; #define PG8_LDB(dst, b, h) do { _Pragma("unroll") for (int n = 0; n < 2; ++n) _Pragma("unroll") for (int k = 0; k < 2; ++k) dst[n][k] = *(const PG8_LAS bf16x8*)(lds + PG8_SB(b, h) + boff + n * 2048 + k * 1024); } while (0)
; #define PG8_MMA(ai, bj, At, Bt) do { __builtin_amdgcn_s_setprio(1); _Pragma("unroll") for (int m = 0; m < 4; ++m) _Pragma("unroll") for (int n = 0; n < 2; ++n) _Pragma("unroll") for (int k = 0; k < 2; ++k) \
;         acc[ai][bj][m][n] = __builtin_amdgcn_mfma_f32_16x16x32_bf16(Bt[n][k], At[m][k], acc[ai][bj][m][n], 0, 0, 0); __builtin_amdgcn_s_setprio(0); } while (0)
; #define PG8_WAIT_V(n) asm volatile("s_waitcnt vmcnt(" #n ")" ::: "memory")
; #define PG8_WAIT_L(n) asm volatile("s_waitcnt lgkmcnt(" #n ")" ::: "memory")
; #define PG8_BAR __builtin_amdgcn_s_barrier()
; #define PG8_SCHED __builtin_amdgcn_sched_barrier(0)
; template <class Epi, class Sched, bool ALIGN_EPI = false, bool SP2 = false>
; __device__ __forceinline__ void gemm_phase(PG8_LAS unsigned char* lds, const Gemm g, const Sched& S, const Epi& E) {
;     ...
;         for (int t = 0; t < nt; t += 2) {
;     ...
;             PG8_LDB(B0, 1, 0); PG8_LDB(B1, 1, 1); PG8_SCHED; PG8_LDA(At, 1, 0); PG8_STAGE(PG8_SA(0, 1), a2 + hstep, voffA);
;             PG8_WAIT_V(8); PG8_WAIT_L(0); PG8_BAR; PG8_MMA(0, 0, At, B0); PG8_MMA(0, 1, At, B1); PG8_BAR; PG8_SCHED;
;             PG8_LDA(At, 1, 1); PG8_STAGE(PG8_SB(1, 0), b3, voffB); PG8_STAGE(PG8_SB(1, 1), b3 + hstep, voffB); PG8_STAGE(PG8_SA(1, 0), a3, voffA);
;             PG8_WAIT_V(8); PG8_WAIT_L(0); PG8_BAR; PG8_MMA(1, 0, At, B0); PG8_MMA(1, 1, At, B1); PG8_BAR; PG8_SCHED;
	s_add_i32 s65, 0, 0x18000
	s_add_i32 s66, 0, 0x1c000
	ds_read_b128 v[154:157], v240
	ds_read_b128 v[158:161], v240 offset:1024
	ds_read_b128 v[162:165], v240 offset:2048
	ds_read_b128 v[166:169], v240 offset:3072
	ds_read_b128 v[170:173], v241
	ds_read_b128 v[174:177], v241 offset:1024
	ds_read_b128 v[178:181], v241 offset:2048
	ds_read_b128 v[182:185], v241 offset:3072
	s_add_u32 s100, s46, 0x80
	s_addc_u32 s101, s47, 0
	s_add_u32 s46, s46, 0x40000
	s_addc_u32 s47, s47, 0
	s_mov_b32 m0, s50
	ds_read_b128 v[186:189], v151 offset:32768
	ds_read_b128 v[190:193], v151 offset:33792
	ds_read_b128 v[194:197], v151 offset:34816
	ds_read_b128 v[198:201], v151 offset:35840
	ds_read_b128 v[206:209], v151 offset:36864
	ds_read_b128 v[210:213], v151 offset:37888
	ds_read_b128 v[214:217], v151 offset:38912
	ds_read_b128 v[218:221], v151 offset:39936
	global_load_lds_dwordx4 v130, s[46:47]
	s_mov_b32 m0, s51
	s_nop 0
	global_load_lds_dwordx4 v134, s[46:47]
	s_waitcnt vmcnt(8)
	s_waitcnt lgkmcnt(0)
	s_setprio 1
	s_barrier
	v_mfma_f32_16x16x32_bf16 v[124:127], v[154:157], v[186:189], v[124:127]
	v_mfma_f32_16x16x32_bf16 v[120:123], v[162:165], v[186:189], v[120:123]
	v_mfma_f32_16x16x32_bf16 v[108:111], v[154:157], v[194:197], v[108:111]
	v_mfma_f32_16x16x32_bf16 v[104:107], v[162:165], v[194:197], v[104:107]
	v_mfma_f32_16x16x32_bf16 v[92:95], v[154:157], v[206:209], v[92:95]
	v_mfma_f32_16x16x32_bf16 v[88:91], v[162:165], v[206:209], v[88:91]
	v_mfma_f32_16x16x32_bf16 v[76:79], v[154:157], v[214:217], v[76:79]
	v_mfma_f32_16x16x32_bf16 v[72:75], v[162:165], v[214:217], v[72:75]
	v_mfma_f32_16x16x32_bf16 v[124:127], v[158:161], v[190:193], v[124:127]
	v_mfma_f32_16x16x32_bf16 v[120:123], v[166:169], v[190:193], v[120:123]
	v_mfma_f32_16x16x32_bf16 v[108:111], v[158:161], v[198:201], v[108:111]
	v_mfma_f32_16x16x32_bf16 v[104:107], v[166:169], v[198:201], v[104:107]
	v_mfma_f32_16x16x32_bf16 v[92:95], v[158:161], v[210:213], v[92:95]
	v_mfma_f32_16x16x32_bf16 v[88:91], v[166:169], v[210:213], v[88:91]
	v_mfma_f32_16x16x32_bf16 v[76:79], v[158:161], v[218:221], v[76:79]
	v_mfma_f32_16x16x32_bf16 v[72:75], v[166:169], v[218:221], v[72:75]
	v_mfma_f32_16x16x32_bf16 v[116:119], v[170:173], v[186:189], v[116:119]
	v_mfma_f32_16x16x32_bf16 v[112:115], v[178:181], v[186:189], v[112:115]
	v_mfma_f32_16x16x32_bf16 v[100:103], v[170:173], v[194:197], v[100:103]
	v_mfma_f32_16x16x32_bf16 v[96:99], v[178:181], v[194:197], v[96:99]
	v_mfma_f32_16x16x32_bf16 v[84:87], v[170:173], v[206:209], v[84:87]
	v_mfma_f32_16x16x32_bf16 v[80:83], v[178:181], v[206:209], v[80:83]
	v_mfma_f32_16x16x32_bf16 v[68:71], v[170:173], v[214:217], v[68:71]
	v_mfma_f32_16x16x32_bf16 v[64:67], v[178:181], v[214:217], v[64:67]
	v_mfma_f32_16x16x32_bf16 v[116:119], v[174:177], v[190:193], v[116:119]
	v_mfma_f32_16x16x32_bf16 v[112:115], v[182:185], v[190:193], v[112:115]
	v_mfma_f32_16x16x32_bf16 v[100:103], v[174:177], v[198:201], v[100:103]
	v_mfma_f32_16x16x32_bf16 v[96:99], v[182:185], v[198:201], v[96:99]
	v_mfma_f32_16x16x32_bf16 v[84:87], v[174:177], v[210:213], v[84:87]
	v_mfma_f32_16x16x32_bf16 v[80:83], v[182:185], v[210:213], v[80:83]
	v_mfma_f32_16x16x32_bf16 v[68:71], v[174:177], v[218:221], v[68:71]
	v_mfma_f32_16x16x32_bf16 v[64:67], v[182:185], v[218:221], v[64:67]
	s_setprio 0
	s_barrier
	s_add_i32 s46, s65, s13
	s_mov_b32 m0, s46
	ds_read_b128 v[186:189], v151 offset:49152
	ds_read_b128 v[190:193], v151 offset:50176
	ds_read_b128 v[194:197], v151 offset:51200
	ds_read_b128 v[198:201], v151 offset:52224
	ds_read_b128 v[206:209], v151 offset:53248
	ds_read_b128 v[210:213], v151 offset:54272
	ds_read_b128 v[214:217], v151 offset:55296
	ds_read_b128 v[218:221], v151 offset:56320
	global_load_lds_dwordx4 v132, s[98:99]
	s_add_i32 m0, s46, 0x2000
	s_add_u32 s44, s44, 0x40080
	s_addc_u32 s45, s45, 0
	s_add_i32 s46, s66, s13
	global_load_lds_dwordx4 v136, s[98:99]
	s_mov_b32 m0, s46
	s_nop 0
	global_load_lds_dwordx4 v132, s[44:45]
	s_add_i32 m0, s46, 0x2000
	s_nop 0
	global_load_lds_dwordx4 v136, s[44:45]
	s_mov_b32 m0, s54
	s_nop 0
	global_load_lds_dwordx4 v130, s[100:101]
	s_mov_b32 m0, s55
	s_nop 0
	global_load_lds_dwordx4 v134, s[100:101]
	s_waitcnt vmcnt(8)
	s_waitcnt lgkmcnt(0)
	s_setprio 1
	s_barrier
	v_mfma_f32_16x16x32_bf16 v[60:63], v[154:157], v[186:189], v[60:63]
	v_mfma_f32_16x16x32_bf16 v[56:59], v[162:165], v[186:189], v[56:59]
	v_mfma_f32_16x16x32_bf16 v[44:47], v[154:157], v[194:197], v[44:47]
	v_mfma_f32_16x16x32_bf16 v[40:43], v[162:165], v[194:197], v[40:43]
	v_mfma_f32_16x16x32_bf16 v[28:31], v[154:157], v[206:209], v[28:31]
	v_mfma_f32_16x16x32_bf16 v[24:27], v[162:165], v[206:209], v[24:27]
	v_mfma_f32_16x16x32_bf16 v[12:15], v[154:157], v[214:217], v[12:15]
	v_mfma_f32_16x16x32_bf16 v[8:11], v[162:165], v[214:217], v[8:11]
	v_mfma_f32_16x16x32_bf16 v[60:63], v[158:161], v[190:193], v[60:63]
	v_mfma_f32_16x16x32_bf16 v[56:59], v[166:169], v[190:193], v[56:59]
	v_mfma_f32_16x16x32_bf16 v[44:47], v[158:161], v[198:201], v[44:47]
	v_mfma_f32_16x16x32_bf16 v[40:43], v[166:169], v[198:201], v[40:43]
	v_mfma_f32_16x16x32_bf16 v[28:31], v[158:161], v[210:213], v[28:31]
	v_mfma_f32_16x16x32_bf16 v[24:27], v[166:169], v[210:213], v[24:27]
	v_mfma_f32_16x16x32_bf16 v[12:15], v[158:161], v[218:221], v[12:15]
	v_mfma_f32_16x16x32_bf16 v[8:11], v[166:169], v[218:221], v[8:11]
	v_mfma_f32_16x16x32_bf16 v[52:55], v[170:173], v[186:189], v[52:55]
	v_mfma_f32_16x16x32_bf16 v[48:51], v[178:181], v[186:189], v[48:51]
	v_mfma_f32_16x16x32_bf16 v[36:39], v[170:173], v[194:197], v[36:39]
	v_mfma_f32_16x16x32_bf16 v[32:35], v[178:181], v[194:197], v[32:35]
	v_mfma_f32_16x16x32_bf16 v[20:23], v[170:173], v[206:209], v[20:23]
	v_mfma_f32_16x16x32_bf16 v[16:19], v[178:181], v[206:209], v[16:19]
	v_mfma_f32_16x16x32_bf16 v[4:7], v[170:173], v[214:217], v[4:7]
	v_mfma_f32_16x16x32_bf16 v[0:3], v[178:181], v[214:217], v[0:3]
	v_mfma_f32_16x16x32_bf16 v[52:55], v[174:177], v[190:193], v[52:55]
	v_mfma_f32_16x16x32_bf16 v[48:51], v[182:185], v[190:193], v[48:51]
	v_mfma_f32_16x16x32_bf16 v[36:39], v[174:177], v[198:201], v[36:39]
	v_mfma_f32_16x16x32_bf16 v[32:35], v[182:185], v[198:201], v[32:35]
	v_mfma_f32_16x16x32_bf16 v[20:23], v[174:177], v[210:213], v[20:23]
	v_mfma_f32_16x16x32_bf16 v[16:19], v[182:185], v[210:213], v[16:19]
	v_mfma_f32_16x16x32_bf16 v[4:7], v[174:177], v[218:221], v[4:7]
	v_mfma_f32_16x16x32_bf16 v[0:3], v[182:185], v[218:221], v[0:3]
	s_setprio 0
	s_barrier
	s_add_i32 s64, s64, 2
	s_add_u32 s42, s42, 0x100
	s_addc_u32 s43, s43, 0
	s_add_u32 s62, s62, 0x100
	s_addc_u32 s63, s63, 0
	s_cmp_gt_u32 s64, 13
	s_cbranch_scc0 .LBB0_627
	s_and_b64 vcc, exec, s[30:31]
	s_cbranch_vccz .LBB0_630
	s_barrier

; #define PG8_STAGE(bufoff, gbase, voff) do { _Pragma("unroll") for (int _i = 0; _i < 2; ++_i) \
;         __builtin_amdgcn_global_load_lds((const unsigned*)((const char*)(gbase) + (voff)[_i]), (PG8_LAS unsigned*)(lds + (bufoff) + ldsw + _i * 8192), 16, 0, 0); } while (0)
; #define PG8_LDA(dst, b, h) do { _Pragma("unroll") for (int m = 0; m < 4; ++m) _Pragma("unroll") for (int k = 0; k < 2; ++k) dst[m][k] = *(const PG8_LAS bf16x8*)(lds + PG8_SA(b, h) + aoff + m * 2048 + k * 1024); } while (0)
; #define PG8_LDB(dst, b, h) do { _Pragma("unroll") for (int n = 0; n < 2; ++n) _Pragma("unroll") for (int k = 0; k < 2; ++k) dst[n][k] = *(const PG8_LAS bf16x8*)(lds + PG8_SB(b, h) + boff + n * 2048 + k * 1024); } while (0)
; #define PG8_WAIT_V(n) asm volatile("s_waitcnt vmcnt(" #n ")" ::: "memory")
; #define PG8_WAIT_L(n) asm volatile("s_waitcnt lgkmcnt(" #n ")" ::: "memory")
; #define PG8_BAR __builtin_amdgcn_s_barrier()
; template <class Epi, class Sched, bool ALIGN_EPI = false, bool SP2 = false>
; __device__ __forceinline__ void gemm_phase(PG8_LAS unsigned char* lds, const Gemm g, const Sched& S, const Epi& E) {
;     ...
;         const bool has_next = S.next(ui + 1, nxt);
;         const char* nA = has_next ? (const char*)g.A + (size_t)nxt.pm * tstep : cA; const char* nB = has_next ? (const char*)g.Bt + (size_t)nxt.pn * tstep : cB;
;         for (int t = 0; t < nt; t += 2) {
;             const bool last = (t == nt - 2);
;             const char* a1 = cA + (size_t)(t + 1) * kstep;
;             const char* a2 = last ? nA : cA + (size_t)(t + 2) * kstep; const char* b2 = last ? nB : cB + (size_t)(t + 2) * kstep;
;             const char* a3 = a2 + kstep; const char* b3 = b2 + kstep;
;             if (last && has_next) S.a_ready(nxt);
;             if constexpr (SP2) {
;             PG8_LDB(B0, 0, 0); PG8_LDB(B1, 0, 1); PG8_SCHED; PG8_LDA(At, 0, 0); PG8_STAGE(PG8_SA(1, 1), a1 + hstep, voffA);
;             PG8_WAIT_V(8); PG8_WAIT_L(0); PG8_BAR; PG8_MMA(0, 0, At, B0); PG8_MMA(0, 1, At, B1); PG8_BAR; PG8_SCHED;
;     ...
; #pragma unroll
;         for (int a = 0; a < 2; ++a)
; #pragma unroll
;             for (int b = 0; b < 2; ++b)
; #pragma unroll
;                 for (int m = 0; m < 4; ++m)
; #pragma unroll
;                     for (int n = 0; n < 2; ++n) acc[a][b][m][n] = (f32x4){0.f, 0.f, 0.f, 0.f};
;         cur = nxt; cA = nA; cB = nB; ++ui;
.LBB0_797:
	s_ashr_i32 s35, s34, 31
	s_lshl_b64 s[36:37], s[34:35], 19
	s_add_u32 s36, s70, s36
	s_addc_u32 s37, s71, s37
	s_and_b64 s[38:39], s[8:9], exec
	s_cselect_b32 s35, s37, s45
	s_cselect_b32 s41, s36, s44
	s_ashr_i32 s31, s30, 31
	s_lshl_b64 s[38:39], s[30:31], 19
	s_add_u32 s38, s68, s38
	s_addc_u32 s39, s69, s39
	s_and_b64 s[48:49], s[8:9], exec
	s_cselect_b32 s31, s39, s47
	s_cselect_b32 s60, s38, s46
	s_add_u32 s44, s44, 0x40080
	s_addc_u32 s45, s45, 0
	s_add_u32 s61, s46, 0x100
	v_mov_b32_e32 v0, 0
	s_addc_u32 s62, s47, 0
	s_mov_b32 s63, -2
	s_waitcnt lgkmcnt(0)
	v_mov_b32_e32 v1, v0
	v_mov_b32_e32 v2, v0
	v_mov_b32_e32 v3, v0
	v_mov_b32_e32 v4, v0
	v_mov_b32_e32 v5, v0
	v_mov_b32_e32 v6, v0
	v_mov_b32_e32 v7, v0
	v_mov_b32_e32 v16, v0
	v_mov_b32_e32 v17, v0
	v_mov_b32_e32 v18, v0
	v_mov_b32_e32 v19, v0
	v_mov_b32_e32 v20, v0
	v_mov_b32_e32 v21, v0
	v_mov_b32_e32 v22, v0
	v_mov_b32_e32 v23, v0
	v_mov_b32_e32 v32, v0
	v_mov_b32_e32 v33, v0
	v_mov_b32_e32 v34, v0
	v_mov_b32_e32 v35, v0
	v_mov_b32_e32 v36, v0
	v_mov_b32_e32 v37, v0
	v_mov_b32_e32 v38, v0
	v_mov_b32_e32 v39, v0
	v_mov_b32_e32 v48, v0
	v_mov_b32_e32 v49, v0
	v_mov_b32_e32 v50, v0
	v_mov_b32_e32 v51, v0
	v_mov_b32_e32 v52, v0
	v_mov_b32_e32 v53, v0
	v_mov_b32_e32 v54, v0
	v_mov_b32_e32 v55, v0
	v_mov_b32_e32 v8, v0
	v_mov_b32_e32 v9, v0
	v_mov_b32_e32 v10, v0
	v_mov_b32_e32 v11, v0
	v_mov_b32_e32 v12, v0
	v_mov_b32_e32 v13, v0
	v_mov_b32_e32 v14, v0
	v_mov_b32_e32 v15, v0
	v_mov_b32_e32 v24, v0
	v_mov_b32_e32 v25, v0
	v_mov_b32_e32 v26, v0
	v_mov_b32_e32 v27, v0
	v_mov_b32_e32 v28, v0
	v_mov_b32_e32 v29, v0
	v_mov_b32_e32 v30, v0
	v_mov_b32_e32 v31, v0
	v_mov_b32_e32 v40, v0
	v_mov_b32_e32 v41, v0
	v_mov_b32_e32 v42, v0
	v_mov_b32_e32 v43, v0
	v_mov_b32_e32 v44, v0
	v_mov_b32_e32 v45, v0
	v_mov_b32_e32 v46, v0
	v_mov_b32_e32 v47, v0
	v_mov_b32_e32 v56, v0
	v_mov_b32_e32 v57, v0
	v_mov_b32_e32 v58, v0
	v_mov_b32_e32 v59, v0
	v_mov_b32_e32 v60, v0
	v_mov_b32_e32 v61, v0
	v_mov_b32_e32 v62, v0
	v_mov_b32_e32 v63, v0
	v_mov_b32_e32 v64, v0
	v_mov_b32_e32 v65, v0
	v_mov_b32_e32 v66, v0
	v_mov_b32_e32 v67, v0
	v_mov_b32_e32 v68, v0
	v_mov_b32_e32 v69, v0
	v_mov_b32_e32 v70, v0
	v_mov_b32_e32 v71, v0
	v_mov_b32_e32 v80, v0
	v_mov_b32_e32 v81, v0
	v_mov_b32_e32 v82, v0
	v_mov_b32_e32 v83, v0
	v_mov_b32_e32 v84, v0
	v_mov_b32_e32 v85, v0
	v_mov_b32_e32 v86, v0
	v_mov_b32_e32 v87, v0
	v_mov_b32_e32 v96, v0
	v_mov_b32_e32 v97, v0
	v_mov_b32_e32 v98, v0
	v_mov_b32_e32 v99, v0
	v_mov_b32_e32 v100, v0
	v_mov_b32_e32 v101, v0
	v_mov_b32_e32 v102, v0
	v_mov_b32_e32 v103, v0
	v_mov_b32_e32 v112, v0
	v_mov_b32_e32 v113, v0
	v_mov_b32_e32 v114, v0
	v_mov_b32_e32 v115, v0
	v_mov_b32_e32 v116, v0
	v_mov_b32_e32 v117, v0
	v_mov_b32_e32 v118, v0
	v_mov_b32_e32 v119, v0
	v_mov_b32_e32 v72, v0
	v_mov_b32_e32 v73, v0
	v_mov_b32_e32 v74, v0
	v_mov_b32_e32 v75, v0
	v_mov_b32_e32 v76, v0
	v_mov_b32_e32 v77, v0
	v_mov_b32_e32 v78, v0
	v_mov_b32_e32 v79, v0
	v_mov_b32_e32 v88, v0
	v_mov_b32_e32 v89, v0
	v_mov_b32_e32 v90, v0
	v_mov_b32_e32 v91, v0
	v_mov_b32_e32 v92, v0
	v_mov_b32_e32 v93, v0
	v_mov_b32_e32 v94, v0
	v_mov_b32_e32 v95, v0
	v_mov_b32_e32 v104, v0
	v_mov_b32_e32 v105, v0
	v_mov_b32_e32 v106, v0
	v_mov_b32_e32 v107, v0
	v_mov_b32_e32 v108, v0
	v_mov_b32_e32 v109, v0
	v_mov_b32_e32 v110, v0
	v_mov_b32_e32 v111, v0
	v_mov_b32_e32 v120, v0
	v_mov_b32_e32 v121, v0
	v_mov_b32_e32 v122, v0
	v_mov_b32_e32 v123, v0
	v_mov_b32_e32 v124, v0
	v_mov_b32_e32 v125, v0
	v_mov_b32_e32 v126, v0
	v_mov_b32_e32 v127, v0
	v_add_u32_e32 v240, 0x18000, v150
	v_add_u32_e32 v241, 0x1c000, v150
.LBB0_798:
	ds_read_b128 v[146:149], v152
	ds_read_b128 v[156:159], v152 offset:1024
	ds_read_b128 v[160:163], v152 offset:2048
	ds_read_b128 v[164:167], v152 offset:3072
	ds_read_b128 v[168:171], v153
	ds_read_b128 v[172:175], v153 offset:1024
	ds_read_b128 v[176:179], v153 offset:2048
	ds_read_b128 v[180:183], v153 offset:3072
	s_add_u32 s46, s44, 0xfffc0080
	s_addc_u32 s47, s45, -1
	s_cmp_eq_u32 s63, 12
	s_cselect_b32 s49, s35, s47
	s_cselect_b32 s48, s41, s46
	s_cselect_b32 s47, s31, s62
	s_cselect_b32 s46, s60, s61
	s_add_i32 m0, s43, 0xc000
	ds_read_b128 v[184:187], v154
	ds_read_b128 v[188:191], v154 offset:1024
	ds_read_b128 v[192:195], v154 offset:2048
	ds_read_b128 v[196:199], v154 offset:3072
	ds_read_b128 v[200:203], v154 offset:4096
	ds_read_b128 v[206:209], v154 offset:5120
	ds_read_b128 v[210:213], v154 offset:6144
	ds_read_b128 v[214:217], v154 offset:7168
	global_load_lds_dwordx4 v138, s[44:45]
	s_add_i32 m0, s43, 0xe000
	s_nop 0
	global_load_lds_dwordx4 v140, s[44:45]
	s_waitcnt vmcnt(8)
	s_waitcnt lgkmcnt(0)
	s_setprio 1
	s_barrier
; #define PG8_STAGE(bufoff, gbase, voff) do { _Pragma("unroll") for (int _i = 0; _i < 2; ++_i) \
;         __builtin_amdgcn_global_load_lds((const unsigned*)((const char*)(gbase) + (voff)[_i]), (PG8_LAS unsigned*)(lds + (bufoff) + ldsw + _i * 8192), 16, 0, 0); } while (0)
; #define PG8_LDA(dst, b, h) do { _Pragma("unroll") for (int m = 0; m < 4; ++m) _Pragma("unroll") for (int k = 0; k < 2; ++k) dst[m][k] = *(const PG8_LAS bf16x8*)(lds + PG8_SA(b, h) + aoff + m * 2048 + k * 1024); } while (0)
; #define PG8_MMA(ai, bj, At, Bt) do { __builtin_amdgcn_s_setprio(1); _Pragma("unroll") for (int m = 0; m < 4; ++m) _Pragma("unroll") for (int n = 0; n < 2; ++n) _Pragma("unroll") for (int k = 0; k < 2; ++k) \
;         acc[ai][bj][m][n] = __builtin_amdgcn_mfma_f32_16x16x32_bf16(Bt[n][k], At[m][k], acc[ai][bj][m][n], 0, 0, 0); __builtin_amdgcn_s_setprio(0); } while (0)
; #define PG8_WAIT_V(n) asm volatile("s_waitcnt vmcnt(" #n ")" ::: "memory")
; #define PG8_WAIT_L(n) asm volatile("s_waitcnt lgkmcnt(" #n ")" ::: "memory")
; #define PG8_BAR __builtin_amdgcn_s_barrier()
; #define PG8_SCHED __builtin_amdgcn_sched_barrier(0)
; template <class Epi, class Sched, bool ALIGN_EPI = false, bool SP2 = false>
; __device__ __forceinline__ void gemm_phase(PG8_LAS unsigned char* lds, const Gemm g, const Sched& S, const Epi& E) {
;     ...
;             PG8_WAIT_V(8); PG8_WAIT_L(0); PG8_BAR; PG8_MMA(0, 0, At, B0); PG8_MMA(0, 1, At, B1); PG8_BAR; PG8_SCHED;
;             PG8_LDA(At, 0, 1); PG8_STAGE(PG8_SB(0, 0), b2, voffB); PG8_STAGE(PG8_SB(0, 1), b2 + hstep, voffB); PG8_STAGE(PG8_SA(0, 0), a2, voffA);
;             PG8_WAIT_V(8); PG8_WAIT_L(0); PG8_BAR; PG8_MMA(1, 0, At, B0); PG8_MMA(1, 1, At, B1); PG8_BAR; PG8_SCHED;
	v_mfma_f32_16x16x32_bf16 v[124:127], v[146:149], v[184:187], v[124:127]
	v_mfma_f32_16x16x32_bf16 v[120:123], v[160:163], v[184:187], v[120:123]
	v_mfma_f32_16x16x32_bf16 v[108:111], v[146:149], v[192:195], v[108:111]
	v_mfma_f32_16x16x32_bf16 v[104:107], v[160:163], v[192:195], v[104:107]
	v_mfma_f32_16x16x32_bf16 v[92:95], v[146:149], v[200:203], v[92:95]
	v_mfma_f32_16x16x32_bf16 v[88:91], v[160:163], v[200:203], v[88:91]
	v_mfma_f32_16x16x32_bf16 v[76:79], v[146:149], v[210:213], v[76:79]
	v_mfma_f32_16x16x32_bf16 v[72:75], v[160:163], v[210:213], v[72:75]
	v_mfma_f32_16x16x32_bf16 v[124:127], v[156:159], v[188:191], v[124:127]
	v_mfma_f32_16x16x32_bf16 v[120:123], v[164:167], v[188:191], v[120:123]
	v_mfma_f32_16x16x32_bf16 v[108:111], v[156:159], v[196:199], v[108:111]
	v_mfma_f32_16x16x32_bf16 v[104:107], v[164:167], v[196:199], v[104:107]
	v_mfma_f32_16x16x32_bf16 v[92:95], v[156:159], v[206:209], v[92:95]
	v_mfma_f32_16x16x32_bf16 v[88:91], v[164:167], v[206:209], v[88:91]
	v_mfma_f32_16x16x32_bf16 v[76:79], v[156:159], v[214:217], v[76:79]
	v_mfma_f32_16x16x32_bf16 v[72:75], v[164:167], v[214:217], v[72:75]
	v_mfma_f32_16x16x32_bf16 v[116:119], v[168:171], v[184:187], v[116:119]
	v_mfma_f32_16x16x32_bf16 v[112:115], v[176:179], v[184:187], v[112:115]
	v_mfma_f32_16x16x32_bf16 v[100:103], v[168:171], v[192:195], v[100:103]
	v_mfma_f32_16x16x32_bf16 v[96:99], v[176:179], v[192:195], v[96:99]
	v_mfma_f32_16x16x32_bf16 v[84:87], v[168:171], v[200:203], v[84:87]
	v_mfma_f32_16x16x32_bf16 v[80:83], v[176:179], v[200:203], v[80:83]
	v_mfma_f32_16x16x32_bf16 v[68:71], v[168:171], v[210:213], v[68:71]
	v_mfma_f32_16x16x32_bf16 v[64:67], v[176:179], v[210:213], v[64:67]
	v_mfma_f32_16x16x32_bf16 v[116:119], v[172:175], v[188:191], v[116:119]
	v_mfma_f32_16x16x32_bf16 v[112:115], v[180:183], v[188:191], v[112:115]
	v_mfma_f32_16x16x32_bf16 v[100:103], v[172:175], v[196:199], v[100:103]
	v_mfma_f32_16x16x32_bf16 v[96:99], v[180:183], v[196:199], v[96:99]
	v_mfma_f32_16x16x32_bf16 v[84:87], v[172:175], v[206:209], v[84:87]
	v_mfma_f32_16x16x32_bf16 v[80:83], v[180:183], v[206:209], v[80:83]
	v_mfma_f32_16x16x32_bf16 v[68:71], v[172:175], v[214:217], v[68:71]
	v_mfma_f32_16x16x32_bf16 v[64:67], v[180:183], v[214:217], v[64:67]
	s_setprio 0
	s_barrier
	s_add_i32 s64, s58, s33
	s_mov_b32 m0, s64
	ds_read_b128 v[184:187], v154 offset:16384
	ds_read_b128 v[188:191], v154 offset:17408
	ds_read_b128 v[192:195], v154 offset:18432
	ds_read_b128 v[196:199], v154 offset:19456
	ds_read_b128 v[200:203], v154 offset:20480
	ds_read_b128 v[206:209], v154 offset:21504
	ds_read_b128 v[210:213], v154 offset:22528
	ds_read_b128 v[214:217], v154 offset:23552
	global_load_lds_dwordx4 v132, s[46:47]
	s_add_i32 m0, s64, 0x2000
	s_add_u32 s98, s46, 0x80
	s_addc_u32 s99, s47, 0
	s_add_u32 s64, s46, 0x40000
	s_addc_u32 s65, s47, 0
	s_add_i32 s66, s59, s33
	global_load_lds_dwordx4 v136, s[46:47]
	s_mov_b32 m0, s66
	s_nop 0
	global_load_lds_dwordx4 v132, s[64:65]
	s_add_i32 m0, s66, 0x2000
	s_nop 0
	global_load_lds_dwordx4 v136, s[64:65]
	s_mov_b32 m0, s43
	s_nop 0
	global_load_lds_dwordx4 v130, s[48:49]
	s_mov_b32 m0, s50
	s_nop 0
	global_load_lds_dwordx4 v134, s[48:49]
	s_waitcnt vmcnt(8)
	s_waitcnt lgkmcnt(0)
	s_setprio 1
	s_barrier
	v_mfma_f32_16x16x32_bf16 v[60:63], v[146:149], v[184:187], v[60:63]
	v_mfma_f32_16x16x32_bf16 v[56:59], v[160:163], v[184:187], v[56:59]
	v_mfma_f32_16x16x32_bf16 v[44:47], v[146:149], v[192:195], v[44:47]
	v_mfma_f32_16x16x32_bf16 v[40:43], v[160:163], v[192:195], v[40:43]
	v_mfma_f32_16x16x32_bf16 v[28:31], v[146:149], v[200:203], v[28:31]
	v_mfma_f32_16x16x32_bf16 v[24:27], v[160:163], v[200:203], v[24:27]
	v_mfma_f32_16x16x32_bf16 v[12:15], v[146:149], v[210:213], v[12:15]
	v_mfma_f32_16x16x32_bf16 v[8:11], v[160:163], v[210:213], v[8:11]
	v_mfma_f32_16x16x32_bf16 v[60:63], v[156:159], v[188:191], v[60:63]
	v_mfma_f32_16x16x32_bf16 v[56:59], v[164:167], v[188:191], v[56:59]
	v_mfma_f32_16x16x32_bf16 v[44:47], v[156:159], v[196:199], v[44:47]
	v_mfma_f32_16x16x32_bf16 v[40:43], v[164:167], v[196:199], v[40:43]
	v_mfma_f32_16x16x32_bf16 v[28:31], v[156:159], v[206:209], v[28:31]
	v_mfma_f32_16x16x32_bf16 v[24:27], v[164:167], v[206:209], v[24:27]
	v_mfma_f32_16x16x32_bf16 v[12:15], v[156:159], v[214:217], v[12:15]
	v_mfma_f32_16x16x32_bf16 v[8:11], v[164:167], v[214:217], v[8:11]
	v_mfma_f32_16x16x32_bf16 v[52:55], v[168:171], v[184:187], v[52:55]
	v_mfma_f32_16x16x32_bf16 v[48:51], v[176:179], v[184:187], v[48:51]
	v_mfma_f32_16x16x32_bf16 v[36:39], v[168:171], v[192:195], v[36:39]
	v_mfma_f32_16x16x32_bf16 v[32:35], v[176:179], v[192:195], v[32:35]
	v_mfma_f32_16x16x32_bf16 v[20:23], v[168:171], v[200:203], v[20:23]
	v_mfma_f32_16x16x32_bf16 v[16:19], v[176:179], v[200:203], v[16:19]
	v_mfma_f32_16x16x32_bf16 v[4:7], v[168:171], v[210:213], v[4:7]
	v_mfma_f32_16x16x32_bf16 v[0:3], v[176:179], v[210:213], v[0:3]
	v_mfma_f32_16x16x32_bf16 v[52:55], v[172:175], v[188:191], v[52:55]
	v_mfma_f32_16x16x32_bf16 v[48:51], v[180:183], v[188:191], v[48:51]
	v_mfma_f32_16x16x32_bf16 v[36:39], v[172:175], v[196:199], v[36:39]
	v_mfma_f32_16x16x32_bf16 v[32:35], v[180:183], v[196:199], v[32:35]
	v_mfma_f32_16x16x32_bf16 v[20:23], v[172:175], v[206:209], v[20:23]
	v_mfma_f32_16x16x32_bf16 v[16:19], v[180:183], v[206:209], v[16:19]
	v_mfma_f32_16x16x32_bf16 v[4:7], v[172:175], v[214:217], v[4:7]
	v_mfma_f32_16x16x32_bf16 v[0:3], v[180:183], v[214:217], v[0:3]
	s_setprio 0
	s_barrier
; #define PG8_STAGE(bufoff, gbase, voff) do { _Pragma("unroll") for (int _i = 0; _i < 2; ++_i) \
;         __builtin_amdgcn_global_load_lds((const unsigned*)((const char*)(gbase) + (voff)[_i]), (PG8_LAS unsigned*)(lds + (bufoff) + ldsw + _i * 8192), 16, 0, 0); } while (0)
; #define PG8_LDA(dst, b, h) do { _Pragma("unroll") for (int m = 0; m < 4; ++m) _Pragma("unroll") for (int k = 0; k < 2; ++k) dst[m][k] = *(const PG8_LAS bf16x8*)(lds + PG8_SA(b, h) + aoff + m * 2048 + k * 1024); } while (0)
; #define PG8_LDB(dst, b, h) do { _Pragma("unroll") for (int n = 0; n < 2; ++n) _Pragma("unroll") for (int k = 0; k < 2; ++k) dst[n][k] = *(const PG8_LAS bf16x8*)(lds + PG8_SB(b, h) + boff + n * 2048 + k * 1024); } while (0)
; #define PG8_MMA(ai, bj, At, Bt) do { __builtin_amdgcn_s_setprio(1); _Pragma("unroll") for (int m = 0; m < 4; ++m) _Pragma("unroll") for (int n = 0; n < 2; ++n) _Pragma("unroll") for (int k = 0; k < 2; ++k) \
;         acc[ai][bj][m][n] = __builtin_amdgcn_mfma_f32_16x16x32_bf16(Bt[n][k], At[m][k], acc[ai][bj][m][n], 0, 0, 0); __builtin_amdgcn_s_setprio(0); } while (0)
; #define PG8_WAIT_V(n) asm volatile("s_waitcnt vmcnt(" #n ")" ::: "memory")
; #define PG8_WAIT_L(n) asm volatile("s_waitcnt lgkmcnt(" #n ")" ::: "memory")
; #define PG8_BAR __builtin_amdgcn_s_barrier()
; #define PG8_SCHED __builtin_amdgcn_sched_barrier(0)
; template <class Epi, class Sched, bool ALIGN_EPI = false, bool SP2 = false>
; __device__ __forceinline__ void gemm_phase(PG8_LAS unsigned char* lds, const Gemm g, const Sched& S, const Epi& E) {
;     ...
;         for (int t = 0; t < nt; t += 2) {
;     ...
;             PG8_LDB(B0, 1, 0); PG8_LDB(B1, 1, 1); PG8_SCHED; PG8_LDA(At, 1, 0); PG8_STAGE(PG8_SA(0, 1), a2 + hstep, voffA);
;             PG8_WAIT_V(8); PG8_WAIT_L(0); PG8_BAR; PG8_MMA(0, 0, At, B0); PG8_MMA(0, 1, At, B1); PG8_BAR; PG8_SCHED;
;             PG8_LDA(At, 1, 1); PG8_STAGE(PG8_SB(1, 0), b3, voffB); PG8_STAGE(PG8_SB(1, 1), b3 + hstep, voffB); PG8_STAGE(PG8_SA(1, 0), a3, voffA);
;             PG8_WAIT_V(8); PG8_WAIT_L(0); PG8_BAR; PG8_MMA(1, 0, At, B0); PG8_MMA(1, 1, At, B1); PG8_BAR; PG8_SCHED;
	s_add_i32 s64, 0, 0x18000
	s_add_i32 s65, 0, 0x1c000
	ds_read_b128 v[146:149], v240
	ds_read_b128 v[156:159], v240 offset:1024
	ds_read_b128 v[160:163], v240 offset:2048
	ds_read_b128 v[164:167], v240 offset:3072
	ds_read_b128 v[168:171], v241
	ds_read_b128 v[172:175], v241 offset:1024
	ds_read_b128 v[176:179], v241 offset:2048
	ds_read_b128 v[180:183], v241 offset:3072
	s_add_u32 s100, s48, 0x80
	s_addc_u32 s101, s49, 0
	s_add_u32 s48, s48, 0x40000
	s_addc_u32 s49, s49, 0
	s_mov_b32 m0, s51
	ds_read_b128 v[184:187], v154 offset:32768
	ds_read_b128 v[188:191], v154 offset:33792
	ds_read_b128 v[192:195], v154 offset:34816
	ds_read_b128 v[196:199], v154 offset:35840
	ds_read_b128 v[200:203], v154 offset:36864
	ds_read_b128 v[206:209], v154 offset:37888
	ds_read_b128 v[210:213], v154 offset:38912
	ds_read_b128 v[214:217], v154 offset:39936
	global_load_lds_dwordx4 v130, s[48:49]
	s_mov_b32 m0, s52
	s_nop 0
	global_load_lds_dwordx4 v134, s[48:49]
	s_waitcnt vmcnt(8)
	s_waitcnt lgkmcnt(0)
	s_setprio 1
	s_barrier
	v_mfma_f32_16x16x32_bf16 v[124:127], v[146:149], v[184:187], v[124:127]
	v_mfma_f32_16x16x32_bf16 v[120:123], v[160:163], v[184:187], v[120:123]
	v_mfma_f32_16x16x32_bf16 v[108:111], v[146:149], v[192:195], v[108:111]
	v_mfma_f32_16x16x32_bf16 v[104:107], v[160:163], v[192:195], v[104:107]
	v_mfma_f32_16x16x32_bf16 v[92:95], v[146:149], v[200:203], v[92:95]
	v_mfma_f32_16x16x32_bf16 v[88:91], v[160:163], v[200:203], v[88:91]
	v_mfma_f32_16x16x32_bf16 v[76:79], v[146:149], v[210:213], v[76:79]
	v_mfma_f32_16x16x32_bf16 v[72:75], v[160:163], v[210:213], v[72:75]
	v_mfma_f32_16x16x32_bf16 v[124:127], v[156:159], v[188:191], v[124:127]
	v_mfma_f32_16x16x32_bf16 v[120:123], v[164:167], v[188:191], v[120:123]
	v_mfma_f32_16x16x32_bf16 v[108:111], v[156:159], v[196:199], v[108:111]
	v_mfma_f32_16x16x32_bf16 v[104:107], v[164:167], v[196:199], v[104:107]
	v_mfma_f32_16x16x32_bf16 v[92:95], v[156:159], v[206:209], v[92:95]
	v_mfma_f32_16x16x32_bf16 v[88:91], v[164:167], v[206:209], v[88:91]
	v_mfma_f32_16x16x32_bf16 v[76:79], v[156:159], v[214:217], v[76:79]
	v_mfma_f32_16x16x32_bf16 v[72:75], v[164:167], v[214:217], v[72:75]
	v_mfma_f32_16x16x32_bf16 v[116:119], v[168:171], v[184:187], v[116:119]
	v_mfma_f32_16x16x32_bf16 v[112:115], v[176:179], v[184:187], v[112:115]
	v_mfma_f32_16x16x32_bf16 v[100:103], v[168:171], v[192:195], v[100:103]
	v_mfma_f32_16x16x32_bf16 v[96:99], v[176:179], v[192:195], v[96:99]
	v_mfma_f32_16x16x32_bf16 v[84:87], v[168:171], v[200:203], v[84:87]
	v_mfma_f32_16x16x32_bf16 v[80:83], v[176:179], v[200:203], v[80:83]
	v_mfma_f32_16x16x32_bf16 v[68:71], v[168:171], v[210:213], v[68:71]
	v_mfma_f32_16x16x32_bf16 v[64:67], v[176:179], v[210:213], v[64:67]
	v_mfma_f32_16x16x32_bf16 v[116:119], v[172:175], v[188:191], v[116:119]
	v_mfma_f32_16x16x32_bf16 v[112:115], v[180:183], v[188:191], v[112:115]
	v_mfma_f32_16x16x32_bf16 v[100:103], v[172:175], v[196:199], v[100:103]
	v_mfma_f32_16x16x32_bf16 v[96:99], v[180:183], v[196:199], v[96:99]
	v_mfma_f32_16x16x32_bf16 v[84:87], v[172:175], v[206:209], v[84:87]
	v_mfma_f32_16x16x32_bf16 v[80:83], v[180:183], v[206:209], v[80:83]
	v_mfma_f32_16x16x32_bf16 v[68:71], v[172:175], v[214:217], v[68:71]
	v_mfma_f32_16x16x32_bf16 v[64:67], v[180:183], v[214:217], v[64:67]
	s_setprio 0
	s_barrier
	s_add_i32 s48, s64, s33
	s_mov_b32 m0, s48
	ds_read_b128 v[184:187], v154 offset:49152
	ds_read_b128 v[188:191], v154 offset:50176
	ds_read_b128 v[192:195], v154 offset:51200
	ds_read_b128 v[196:199], v154 offset:52224
	ds_read_b128 v[200:203], v154 offset:53248
	ds_read_b128 v[206:209], v154 offset:54272
	ds_read_b128 v[210:213], v154 offset:55296
	ds_read_b128 v[214:217], v154 offset:56320
	global_load_lds_dwordx4 v132, s[98:99]
	s_add_i32 m0, s48, 0x2000
	s_add_u32 s46, s46, 0x40080
	s_addc_u32 s47, s47, 0
	s_add_i32 s48, s65, s33
	global_load_lds_dwordx4 v136, s[98:99]
	s_mov_b32 m0, s48
	s_nop 0
	global_load_lds_dwordx4 v132, s[46:47]
	s_add_i32 m0, s48, 0x2000
	s_nop 0
	global_load_lds_dwordx4 v136, s[46:47]
	s_mov_b32 m0, s54
	s_nop 0
	global_load_lds_dwordx4 v130, s[100:101]
	s_mov_b32 m0, s55
	s_nop 0
	global_load_lds_dwordx4 v134, s[100:101]
	s_waitcnt vmcnt(8)
	s_waitcnt lgkmcnt(0)
	s_setprio 1
	s_barrier
	v_mfma_f32_16x16x32_bf16 v[60:63], v[146:149], v[184:187], v[60:63]
	v_mfma_f32_16x16x32_bf16 v[56:59], v[160:163], v[184:187], v[56:59]
	v_mfma_f32_16x16x32_bf16 v[44:47], v[146:149], v[192:195], v[44:47]
	v_mfma_f32_16x16x32_bf16 v[40:43], v[160:163], v[192:195], v[40:43]
	v_mfma_f32_16x16x32_bf16 v[28:31], v[146:149], v[200:203], v[28:31]
	v_mfma_f32_16x16x32_bf16 v[24:27], v[160:163], v[200:203], v[24:27]
	v_mfma_f32_16x16x32_bf16 v[12:15], v[146:149], v[210:213], v[12:15]
	v_mfma_f32_16x16x32_bf16 v[8:11], v[160:163], v[210:213], v[8:11]
	v_mfma_f32_16x16x32_bf16 v[60:63], v[156:159], v[188:191], v[60:63]
	v_mfma_f32_16x16x32_bf16 v[56:59], v[164:167], v[188:191], v[56:59]
	v_mfma_f32_16x16x32_bf16 v[44:47], v[156:159], v[196:199], v[44:47]
	v_mfma_f32_16x16x32_bf16 v[40:43], v[164:167], v[196:199], v[40:43]
	v_mfma_f32_16x16x32_bf16 v[28:31], v[156:159], v[206:209], v[28:31]
	v_mfma_f32_16x16x32_bf16 v[24:27], v[164:167], v[206:209], v[24:27]
	v_mfma_f32_16x16x32_bf16 v[12:15], v[156:159], v[214:217], v[12:15]
	v_mfma_f32_16x16x32_bf16 v[8:11], v[164:167], v[214:217], v[8:11]
	v_mfma_f32_16x16x32_bf16 v[52:55], v[168:171], v[184:187], v[52:55]
	v_mfma_f32_16x16x32_bf16 v[48:51], v[176:179], v[184:187], v[48:51]
	v_mfma_f32_16x16x32_bf16 v[36:39], v[168:171], v[192:195], v[36:39]
	v_mfma_f32_16x16x32_bf16 v[32:35], v[176:179], v[192:195], v[32:35]
	v_mfma_f32_16x16x32_bf16 v[20:23], v[168:171], v[200:203], v[20:23]
	v_mfma_f32_16x16x32_bf16 v[16:19], v[176:179], v[200:203], v[16:19]
	v_mfma_f32_16x16x32_bf16 v[4:7], v[168:171], v[210:213], v[4:7]
	v_mfma_f32_16x16x32_bf16 v[0:3], v[176:179], v[210:213], v[0:3]
	v_mfma_f32_16x16x32_bf16 v[52:55], v[172:175], v[188:191], v[52:55]
	v_mfma_f32_16x16x32_bf16 v[48:51], v[180:183], v[188:191], v[48:51]
	v_mfma_f32_16x16x32_bf16 v[36:39], v[172:175], v[196:199], v[36:39]
	v_mfma_f32_16x16x32_bf16 v[32:35], v[180:183], v[196:199], v[32:35]
	v_mfma_f32_16x16x32_bf16 v[20:23], v[172:175], v[206:209], v[20:23]
	v_mfma_f32_16x16x32_bf16 v[16:19], v[180:183], v[206:209], v[16:19]
	v_mfma_f32_16x16x32_bf16 v[4:7], v[172:175], v[214:217], v[4:7]
	v_mfma_f32_16x16x32_bf16 v[0:3], v[180:183], v[214:217], v[0:3]
	s_setprio 0
	s_barrier
	s_add_i32 s63, s63, 2
	s_add_u32 s44, s44, 0x100
	s_addc_u32 s45, s45, 0
	s_add_u32 s61, s61, 0x100
	s_addc_u32 s62, s62, 0
	s_cmp_gt_u32 s63, 13
	s_cbranch_scc0 .LBB0_798
	s_and_b64 vcc, exec, s[28:29]
	s_cbranch_vccz .LBB0_801
	s_barrier

; #define PG8_STAGE(bufoff, gbase, voff) do { _Pragma("unroll") for (int _i = 0; _i < 2; ++_i) \
;         __builtin_amdgcn_global_load_lds((const unsigned*)((const char*)(gbase) + (voff)[_i]), (PG8_LAS unsigned*)(lds + (bufoff) + ldsw + _i * 8192), 16, 0, 0); } while (0)
; #define PG8_LDA(dst, b, h) do { _Pragma("unroll") for (int m = 0; m < 4; ++m) _Pragma("unroll") for (int k = 0; k < 2; ++k) dst[m][k] = *(const PG8_LAS bf16x8*)(lds + PG8_SA(b, h) + aoff + m * 2048 + k * 1024); } while (0)
; #define PG8_LDB(dst, b, h) do { _Pragma("unroll") for (int n = 0; n < 2; ++n) _Pragma("unroll") for (int k = 0; k < 2; ++k) dst[n][k] = *(const PG8_LAS bf16x8*)(lds + PG8_SB(b, h) + boff + n * 2048 + k * 1024); } while (0)
; #define PG8_WAIT_V(n) asm volatile("s_waitcnt vmcnt(" #n ")" ::: "memory")
; #define PG8_WAIT_L(n) asm volatile("s_waitcnt lgkmcnt(" #n ")" ::: "memory")
; #define PG8_BAR __builtin_amdgcn_s_barrier()
; template <class Epi, class Sched, bool ALIGN_EPI = false, bool SP2 = false>
; __device__ __forceinline__ void gemm_phase(PG8_LAS unsigned char* lds, const Gemm g, const Sched& S, const Epi& E) {
;     ...
;         const bool has_next = S.next(ui + 1, nxt);
;         const char* nA = has_next ? (const char*)g.A + (size_t)nxt.pm * tstep : cA; const char* nB = has_next ? (const char*)g.Bt + (size_t)nxt.pn * tstep : cB;
;         for (int t = 0; t < nt; t += 2) {
;             const bool last = (t == nt - 2);
;             const char* a1 = cA + (size_t)(t + 1) * kstep;
;             const char* a2 = last ? nA : cA + (size_t)(t + 2) * kstep; const char* b2 = last ? nB : cB + (size_t)(t + 2) * kstep;
;             const char* a3 = a2 + kstep; const char* b3 = b2 + kstep;
;             if (last && has_next) S.a_ready(nxt);
;             if constexpr (SP2) {
;             PG8_LDB(B0, 0, 0); PG8_LDB(B1, 0, 1); PG8_SCHED; PG8_LDA(At, 0, 0); PG8_STAGE(PG8_SA(1, 1), a1 + hstep, voffA);
;             PG8_WAIT_V(8); PG8_WAIT_L(0); PG8_BAR; PG8_MMA(0, 0, At, B0); PG8_MMA(0, 1, At, B1); PG8_BAR; PG8_SCHED;
;     ...
; #pragma unroll
;         for (int a = 0; a < 2; ++a)
; #pragma unroll
;             for (int b = 0; b < 2; ++b)
; #pragma unroll
;                 for (int m = 0; m < 4; ++m)
; #pragma unroll
;                     for (int n = 0; n < 2; ++n) acc[a][b][m][n] = (f32x4){0.f, 0.f, 0.f, 0.f};
;         cur = nxt; cA = nA; cB = nB; ++ui;
.LBB0_904:
	s_ashr_i32 s35, s34, 31
	s_lshl_b64 s[36:37], s[34:35], 19
	s_add_u32 s36, s96, s36
	s_addc_u32 s37, s97, s37
	s_and_b64 s[38:39], s[6:7], exec
	s_cselect_b32 s35, s37, s41
	s_cselect_b32 s58, s36, s40
	s_ashr_i32 s31, s30, 31
	s_lshl_b64 s[38:39], s[30:31], 19
	s_add_u32 s38, s68, s38
	s_addc_u32 s39, s69, s39
	s_and_b64 s[44:45], s[6:7], exec
	s_cselect_b32 s31, s39, s43
	s_cselect_b32 s59, s38, s42
	s_add_u32 s40, s40, 0x40080
	s_addc_u32 s41, s41, 0
	s_add_u32 s60, s42, 0x100
	v_mov_b32_e32 v0, 0
	s_addc_u32 s61, s43, 0
	s_mov_b32 s62, -2
	v_mov_b32_e32 v1, v0
	v_mov_b32_e32 v2, v0
	v_mov_b32_e32 v3, v0
	v_mov_b32_e32 v4, v0
	v_mov_b32_e32 v5, v0
	v_mov_b32_e32 v6, v0
	v_mov_b32_e32 v7, v0
	v_mov_b32_e32 v16, v0
	v_mov_b32_e32 v17, v0
	v_mov_b32_e32 v18, v0
	v_mov_b32_e32 v19, v0
	v_mov_b32_e32 v20, v0
	v_mov_b32_e32 v21, v0
	v_mov_b32_e32 v22, v0
	v_mov_b32_e32 v23, v0
	v_mov_b32_e32 v32, v0
	v_mov_b32_e32 v33, v0
	v_mov_b32_e32 v34, v0
	v_mov_b32_e32 v35, v0
	v_mov_b32_e32 v36, v0
	v_mov_b32_e32 v37, v0
	v_mov_b32_e32 v38, v0
	v_mov_b32_e32 v39, v0
	v_mov_b32_e32 v48, v0
	v_mov_b32_e32 v49, v0
	v_mov_b32_e32 v50, v0
	v_mov_b32_e32 v51, v0
	v_mov_b32_e32 v52, v0
	v_mov_b32_e32 v53, v0
	v_mov_b32_e32 v54, v0
	v_mov_b32_e32 v55, v0
	v_mov_b32_e32 v8, v0
	v_mov_b32_e32 v9, v0
	v_mov_b32_e32 v10, v0
	v_mov_b32_e32 v11, v0
	v_mov_b32_e32 v12, v0
	v_mov_b32_e32 v13, v0
	v_mov_b32_e32 v14, v0
	v_mov_b32_e32 v15, v0
	v_mov_b32_e32 v24, v0
	v_mov_b32_e32 v25, v0
	v_mov_b32_e32 v26, v0
	v_mov_b32_e32 v27, v0
	v_mov_b32_e32 v28, v0
	v_mov_b32_e32 v29, v0
	v_mov_b32_e32 v30, v0
	v_mov_b32_e32 v31, v0
	v_mov_b32_e32 v40, v0
	v_mov_b32_e32 v41, v0
	v_mov_b32_e32 v42, v0
	v_mov_b32_e32 v43, v0
	v_mov_b32_e32 v44, v0
	v_mov_b32_e32 v45, v0
	v_mov_b32_e32 v46, v0
	v_mov_b32_e32 v47, v0
	v_mov_b32_e32 v56, v0
	v_mov_b32_e32 v57, v0
	v_mov_b32_e32 v58, v0
	v_mov_b32_e32 v59, v0
	v_mov_b32_e32 v60, v0
	v_mov_b32_e32 v61, v0
	v_mov_b32_e32 v62, v0
	v_mov_b32_e32 v63, v0
	v_mov_b32_e32 v64, v0
	v_mov_b32_e32 v65, v0
	v_mov_b32_e32 v66, v0
	v_mov_b32_e32 v67, v0
	v_mov_b32_e32 v68, v0
	v_mov_b32_e32 v69, v0
	v_mov_b32_e32 v70, v0
	v_mov_b32_e32 v71, v0
	v_mov_b32_e32 v80, v0
	v_mov_b32_e32 v81, v0
	v_mov_b32_e32 v82, v0
	v_mov_b32_e32 v83, v0
	v_mov_b32_e32 v84, v0
	v_mov_b32_e32 v85, v0
	v_mov_b32_e32 v86, v0
	v_mov_b32_e32 v87, v0
	v_mov_b32_e32 v96, v0
	v_mov_b32_e32 v97, v0
	v_mov_b32_e32 v98, v0
	v_mov_b32_e32 v99, v0
	v_mov_b32_e32 v100, v0
	v_mov_b32_e32 v101, v0
	v_mov_b32_e32 v102, v0
	v_mov_b32_e32 v103, v0
	v_mov_b32_e32 v112, v0
	v_mov_b32_e32 v113, v0
	v_mov_b32_e32 v114, v0
	v_mov_b32_e32 v115, v0
	v_mov_b32_e32 v116, v0
	v_mov_b32_e32 v117, v0
	v_mov_b32_e32 v118, v0
	v_mov_b32_e32 v119, v0
	v_mov_b32_e32 v72, v0
	v_mov_b32_e32 v73, v0
	v_mov_b32_e32 v74, v0
	v_mov_b32_e32 v75, v0
	v_mov_b32_e32 v76, v0
	v_mov_b32_e32 v77, v0
	v_mov_b32_e32 v78, v0
	v_mov_b32_e32 v79, v0
	v_mov_b32_e32 v88, v0
	v_mov_b32_e32 v89, v0
	v_mov_b32_e32 v90, v0
	v_mov_b32_e32 v91, v0
	v_mov_b32_e32 v92, v0
	v_mov_b32_e32 v93, v0
	v_mov_b32_e32 v94, v0
	v_mov_b32_e32 v95, v0
	v_mov_b32_e32 v104, v0
	v_mov_b32_e32 v105, v0
	v_mov_b32_e32 v106, v0
	v_mov_b32_e32 v107, v0
	v_mov_b32_e32 v108, v0
	v_mov_b32_e32 v109, v0
	v_mov_b32_e32 v110, v0
	v_mov_b32_e32 v111, v0
	v_mov_b32_e32 v120, v0
	v_mov_b32_e32 v121, v0
	v_mov_b32_e32 v122, v0
	v_mov_b32_e32 v123, v0
	v_mov_b32_e32 v124, v0
	v_mov_b32_e32 v125, v0
	v_mov_b32_e32 v126, v0
	v_mov_b32_e32 v127, v0
	v_add_u32_e32 v240, 0x18000, v150
	v_add_u32_e32 v241, 0x1c000, v150
.LBB0_905:
	ds_read_b128 v[146:149], v151
	ds_read_b128 v[156:159], v151 offset:1024
	ds_read_b128 v[160:163], v151 offset:2048
	ds_read_b128 v[164:167], v151 offset:3072
	ds_read_b128 v[168:171], v152
	ds_read_b128 v[172:175], v152 offset:1024
	ds_read_b128 v[176:179], v152 offset:2048
	ds_read_b128 v[180:183], v152 offset:3072
	s_add_u32 s42, s40, 0xfffc0080
	s_addc_u32 s43, s41, -1
	s_cmp_eq_u32 s62, 12
	s_cselect_b32 s45, s35, s43
	s_cselect_b32 s44, s58, s42
	s_cselect_b32 s43, s31, s61
	s_cselect_b32 s42, s59, s60
	s_add_i32 m0, s46, 0xc000
	ds_read_b128 v[184:187], v153
	ds_read_b128 v[188:191], v153 offset:1024
	ds_read_b128 v[192:195], v153 offset:2048
	ds_read_b128 v[196:199], v153 offset:3072
	ds_read_b128 v[200:203], v153 offset:4096
	ds_read_b128 v[206:209], v153 offset:5120
	ds_read_b128 v[210:213], v153 offset:6144
	ds_read_b128 v[214:217], v153 offset:7168
	global_load_lds_dwordx4 v138, s[40:41]
	s_add_i32 m0, s46, 0xe000
	s_nop 0
	global_load_lds_dwordx4 v140, s[40:41]
	s_waitcnt vmcnt(8)
	s_waitcnt lgkmcnt(0)
	s_setprio 1
	s_barrier
; #define PG8_STAGE(bufoff, gbase, voff) do { _Pragma("unroll") for (int _i = 0; _i < 2; ++_i) \
;         __builtin_amdgcn_global_load_lds((const unsigned*)((const char*)(gbase) + (voff)[_i]), (PG8_LAS unsigned*)(lds + (bufoff) + ldsw + _i * 8192), 16, 0, 0); } while (0)
; #define PG8_LDA(dst, b, h) do { _Pragma("unroll") for (int m = 0; m < 4; ++m) _Pragma("unroll") for (int k = 0; k < 2; ++k) dst[m][k] = *(const PG8_LAS bf16x8*)(lds + PG8_SA(b, h) + aoff + m * 2048 + k * 1024); } while (0)
; #define PG8_MMA(ai, bj, At, Bt) do { __builtin_amdgcn_s_setprio(1); _Pragma("unroll") for (int m = 0; m < 4; ++m) _Pragma("unroll") for (int n = 0; n < 2; ++n) _Pragma("unroll") for (int k = 0; k < 2; ++k) \
;         acc[ai][bj][m][n] = __builtin_amdgcn_mfma_f32_16x16x32_bf16(Bt[n][k], At[m][k], acc[ai][bj][m][n], 0, 0, 0); __builtin_amdgcn_s_setprio(0); } while (0)
; #define PG8_WAIT_V(n) asm volatile("s_waitcnt vmcnt(" #n ")" ::: "memory")
; #define PG8_WAIT_L(n) asm volatile("s_waitcnt lgkmcnt(" #n ")" ::: "memory")
; #define PG8_BAR __builtin_amdgcn_s_barrier()
; #define PG8_SCHED __builtin_amdgcn_sched_barrier(0)
; template <class Epi, class Sched, bool ALIGN_EPI = false, bool SP2 = false>
; __device__ __forceinline__ void gemm_phase(PG8_LAS unsigned char* lds, const Gemm g, const Sched& S, const Epi& E) {
;     ...
;             PG8_WAIT_V(8); PG8_WAIT_L(0); PG8_BAR; PG8_MMA(0, 0, At, B0); PG8_MMA(0, 1, At, B1); PG8_BAR; PG8_SCHED;
;             PG8_LDA(At, 0, 1); PG8_STAGE(PG8_SB(0, 0), b2, voffB); PG8_STAGE(PG8_SB(0, 1), b2 + hstep, voffB); PG8_STAGE(PG8_SA(0, 0), a2, voffA);
;             PG8_WAIT_V(8); PG8_WAIT_L(0); PG8_BAR; PG8_MMA(1, 0, At, B0); PG8_MMA(1, 1, At, B1); PG8_BAR; PG8_SCHED;
	v_mfma_f32_16x16x32_bf16 v[124:127], v[146:149], v[184:187], v[124:127]
	v_mfma_f32_16x16x32_bf16 v[120:123], v[160:163], v[184:187], v[120:123]
	v_mfma_f32_16x16x32_bf16 v[108:111], v[146:149], v[192:195], v[108:111]
	v_mfma_f32_16x16x32_bf16 v[104:107], v[160:163], v[192:195], v[104:107]
	v_mfma_f32_16x16x32_bf16 v[92:95], v[146:149], v[200:203], v[92:95]
	v_mfma_f32_16x16x32_bf16 v[88:91], v[160:163], v[200:203], v[88:91]
	v_mfma_f32_16x16x32_bf16 v[76:79], v[146:149], v[210:213], v[76:79]
	v_mfma_f32_16x16x32_bf16 v[72:75], v[160:163], v[210:213], v[72:75]
	v_mfma_f32_16x16x32_bf16 v[124:127], v[156:159], v[188:191], v[124:127]
	v_mfma_f32_16x16x32_bf16 v[120:123], v[164:167], v[188:191], v[120:123]
	v_mfma_f32_16x16x32_bf16 v[108:111], v[156:159], v[196:199], v[108:111]
	v_mfma_f32_16x16x32_bf16 v[104:107], v[164:167], v[196:199], v[104:107]
	v_mfma_f32_16x16x32_bf16 v[92:95], v[156:159], v[206:209], v[92:95]
	v_mfma_f32_16x16x32_bf16 v[88:91], v[164:167], v[206:209], v[88:91]
	v_mfma_f32_16x16x32_bf16 v[76:79], v[156:159], v[214:217], v[76:79]
	v_mfma_f32_16x16x32_bf16 v[72:75], v[164:167], v[214:217], v[72:75]
	v_mfma_f32_16x16x32_bf16 v[116:119], v[168:171], v[184:187], v[116:119]
	v_mfma_f32_16x16x32_bf16 v[112:115], v[176:179], v[184:187], v[112:115]
	v_mfma_f32_16x16x32_bf16 v[100:103], v[168:171], v[192:195], v[100:103]
	v_mfma_f32_16x16x32_bf16 v[96:99], v[176:179], v[192:195], v[96:99]
	v_mfma_f32_16x16x32_bf16 v[84:87], v[168:171], v[200:203], v[84:87]
	v_mfma_f32_16x16x32_bf16 v[80:83], v[176:179], v[200:203], v[80:83]
	v_mfma_f32_16x16x32_bf16 v[68:71], v[168:171], v[210:213], v[68:71]
	v_mfma_f32_16x16x32_bf16 v[64:67], v[176:179], v[210:213], v[64:67]
	v_mfma_f32_16x16x32_bf16 v[116:119], v[172:175], v[188:191], v[116:119]
	v_mfma_f32_16x16x32_bf16 v[112:115], v[180:183], v[188:191], v[112:115]
	v_mfma_f32_16x16x32_bf16 v[100:103], v[172:175], v[196:199], v[100:103]
	v_mfma_f32_16x16x32_bf16 v[96:99], v[180:183], v[196:199], v[96:99]
	v_mfma_f32_16x16x32_bf16 v[84:87], v[172:175], v[206:209], v[84:87]
	v_mfma_f32_16x16x32_bf16 v[80:83], v[180:183], v[206:209], v[80:83]
	v_mfma_f32_16x16x32_bf16 v[68:71], v[172:175], v[214:217], v[68:71]
	v_mfma_f32_16x16x32_bf16 v[64:67], v[180:183], v[214:217], v[64:67]
	s_setprio 0
	s_barrier
	s_add_i32 s63, s55, s33
	s_mov_b32 m0, s63
	ds_read_b128 v[184:187], v153 offset:16384
	ds_read_b128 v[188:191], v153 offset:17408
	ds_read_b128 v[192:195], v153 offset:18432
	ds_read_b128 v[196:199], v153 offset:19456
	ds_read_b128 v[200:203], v153 offset:20480
	ds_read_b128 v[206:209], v153 offset:21504
	ds_read_b128 v[210:213], v153 offset:22528
	ds_read_b128 v[214:217], v153 offset:23552
	global_load_lds_dwordx4 v132, s[42:43]
	s_add_i32 m0, s63, 0x2000
	s_add_u32 s98, s42, 0x80
	s_addc_u32 s99, s43, 0
	s_add_u32 s64, s42, 0x40000
	s_addc_u32 s65, s43, 0
	s_add_i32 s63, s56, s33
	global_load_lds_dwordx4 v136, s[42:43]
	s_mov_b32 m0, s63
	s_nop 0
	global_load_lds_dwordx4 v132, s[64:65]
	s_add_i32 m0, s63, 0x2000
	s_nop 0
	global_load_lds_dwordx4 v136, s[64:65]
	s_mov_b32 m0, s46
	s_nop 0
	global_load_lds_dwordx4 v130, s[44:45]
	s_mov_b32 m0, s47
	s_nop 0
	global_load_lds_dwordx4 v134, s[44:45]
	s_waitcnt vmcnt(8)
	s_waitcnt lgkmcnt(0)
	s_setprio 1
	s_barrier
	v_mfma_f32_16x16x32_bf16 v[60:63], v[146:149], v[184:187], v[60:63]
	v_mfma_f32_16x16x32_bf16 v[56:59], v[160:163], v[184:187], v[56:59]
	v_mfma_f32_16x16x32_bf16 v[44:47], v[146:149], v[192:195], v[44:47]
	v_mfma_f32_16x16x32_bf16 v[40:43], v[160:163], v[192:195], v[40:43]
	v_mfma_f32_16x16x32_bf16 v[28:31], v[146:149], v[200:203], v[28:31]
	v_mfma_f32_16x16x32_bf16 v[24:27], v[160:163], v[200:203], v[24:27]
	v_mfma_f32_16x16x32_bf16 v[12:15], v[146:149], v[210:213], v[12:15]
	v_mfma_f32_16x16x32_bf16 v[8:11], v[160:163], v[210:213], v[8:11]
	v_mfma_f32_16x16x32_bf16 v[60:63], v[156:159], v[188:191], v[60:63]
	v_mfma_f32_16x16x32_bf16 v[56:59], v[164:167], v[188:191], v[56:59]
	v_mfma_f32_16x16x32_bf16 v[44:47], v[156:159], v[196:199], v[44:47]
	v_mfma_f32_16x16x32_bf16 v[40:43], v[164:167], v[196:199], v[40:43]
	v_mfma_f32_16x16x32_bf16 v[28:31], v[156:159], v[206:209], v[28:31]
	v_mfma_f32_16x16x32_bf16 v[24:27], v[164:167], v[206:209], v[24:27]
	v_mfma_f32_16x16x32_bf16 v[12:15], v[156:159], v[214:217], v[12:15]
	v_mfma_f32_16x16x32_bf16 v[8:11], v[164:167], v[214:217], v[8:11]
	v_mfma_f32_16x16x32_bf16 v[52:55], v[168:171], v[184:187], v[52:55]
	v_mfma_f32_16x16x32_bf16 v[48:51], v[176:179], v[184:187], v[48:51]
	v_mfma_f32_16x16x32_bf16 v[36:39], v[168:171], v[192:195], v[36:39]
	v_mfma_f32_16x16x32_bf16 v[32:35], v[176:179], v[192:195], v[32:35]
	v_mfma_f32_16x16x32_bf16 v[20:23], v[168:171], v[200:203], v[20:23]
	v_mfma_f32_16x16x32_bf16 v[16:19], v[176:179], v[200:203], v[16:19]
	v_mfma_f32_16x16x32_bf16 v[4:7], v[168:171], v[210:213], v[4:7]
	v_mfma_f32_16x16x32_bf16 v[0:3], v[176:179], v[210:213], v[0:3]
	v_mfma_f32_16x16x32_bf16 v[52:55], v[172:175], v[188:191], v[52:55]
	v_mfma_f32_16x16x32_bf16 v[48:51], v[180:183], v[188:191], v[48:51]
	v_mfma_f32_16x16x32_bf16 v[36:39], v[172:175], v[196:199], v[36:39]
	v_mfma_f32_16x16x32_bf16 v[32:35], v[180:183], v[196:199], v[32:35]
	v_mfma_f32_16x16x32_bf16 v[20:23], v[172:175], v[206:209], v[20:23]
	v_mfma_f32_16x16x32_bf16 v[16:19], v[180:183], v[206:209], v[16:19]
	v_mfma_f32_16x16x32_bf16 v[4:7], v[172:175], v[214:217], v[4:7]
	v_mfma_f32_16x16x32_bf16 v[0:3], v[180:183], v[214:217], v[0:3]
	s_setprio 0
	s_barrier
; #define PG8_STAGE(bufoff, gbase, voff) do { _Pragma("unroll") for (int _i = 0; _i < 2; ++_i) \
;         __builtin_amdgcn_global_load_lds((const unsigned*)((const char*)(gbase) + (voff)[_i]), (PG8_LAS unsigned*)(lds + (bufoff) + ldsw + _i * 8192), 16, 0, 0); } while (0)
; #define PG8_LDA(dst, b, h) do { _Pragma("unroll") for (int m = 0; m < 4; ++m) _Pragma("unroll") for (int k = 0; k < 2; ++k) dst[m][k] = *(const PG8_LAS bf16x8*)(lds + PG8_SA(b, h) + aoff + m * 2048 + k * 1024); } while (0)
; #define PG8_LDB(dst, b, h) do { _Pragma("unroll") for (int n = 0; n < 2; ++n) _Pragma("unroll") for (int k = 0; k < 2; ++k) dst[n][k] = *(const PG8_LAS bf16x8*)(lds + PG8_SB(b, h) + boff + n * 2048 + k * 1024); } while (0)
; #define PG8_MMA(ai, bj, At, Bt) do { __builtin_amdgcn_s_setprio(1); _Pragma("unroll") for (int m = 0; m < 4; ++m) _Pragma("unroll") for (int n = 0; n < 2; ++n) _Pragma("unroll") for (int k = 0; k < 2; ++k) \
;         acc[ai][bj][m][n] = __builtin_amdgcn_mfma_f32_16x16x32_bf16(Bt[n][k], At[m][k], acc[ai][bj][m][n], 0, 0, 0); __builtin_amdgcn_s_setprio(0); } while (0)
; #define PG8_WAIT_V(n) asm volatile("s_waitcnt vmcnt(" #n ")" ::: "memory")
; #define PG8_WAIT_L(n) asm volatile("s_waitcnt lgkmcnt(" #n ")" ::: "memory")
; #define PG8_BAR __builtin_amdgcn_s_barrier()
; #define PG8_SCHED __builtin_amdgcn_sched_barrier(0)
; template <class Epi, class Sched, bool ALIGN_EPI = false, bool SP2 = false>
; __device__ __forceinline__ void gemm_phase(PG8_LAS unsigned char* lds, const Gemm g, const Sched& S, const Epi& E) {
;     ...
;         for (int t = 0; t < nt; t += 2) {
;     ...
;             PG8_LDB(B0, 1, 0); PG8_LDB(B1, 1, 1); PG8_SCHED; PG8_LDA(At, 1, 0); PG8_STAGE(PG8_SA(0, 1), a2 + hstep, voffA);
;             PG8_WAIT_V(8); PG8_WAIT_L(0); PG8_BAR; PG8_MMA(0, 0, At, B0); PG8_MMA(0, 1, At, B1); PG8_BAR; PG8_SCHED;
;             PG8_LDA(At, 1, 1); PG8_STAGE(PG8_SB(1, 0), b3, voffB); PG8_STAGE(PG8_SB(1, 1), b3 + hstep, voffB); PG8_STAGE(PG8_SA(1, 0), a3, voffA);
;             PG8_WAIT_V(8); PG8_WAIT_L(0); PG8_BAR; PG8_MMA(1, 0, At, B0); PG8_MMA(1, 1, At, B1); PG8_BAR; PG8_SCHED;
	s_add_i32 s63, 0, 0x18000
	s_add_i32 s64, 0, 0x1c000
	ds_read_b128 v[146:149], v240
	ds_read_b128 v[156:159], v240 offset:1024
	ds_read_b128 v[160:163], v240 offset:2048
	ds_read_b128 v[164:167], v240 offset:3072
	ds_read_b128 v[168:171], v241
	ds_read_b128 v[172:175], v241 offset:1024
	ds_read_b128 v[176:179], v241 offset:2048
	ds_read_b128 v[180:183], v241 offset:3072
	s_add_u32 s100, s44, 0x80
	s_addc_u32 s101, s45, 0
	s_add_u32 s44, s44, 0x40000
	s_addc_u32 s45, s45, 0
	s_mov_b32 m0, s48
	ds_read_b128 v[184:187], v153 offset:32768
	ds_read_b128 v[188:191], v153 offset:33792
	ds_read_b128 v[192:195], v153 offset:34816
	ds_read_b128 v[196:199], v153 offset:35840
	ds_read_b128 v[200:203], v153 offset:36864
	ds_read_b128 v[206:209], v153 offset:37888
	ds_read_b128 v[210:213], v153 offset:38912
	ds_read_b128 v[214:217], v153 offset:39936
	global_load_lds_dwordx4 v130, s[44:45]
	s_mov_b32 m0, s49
	s_nop 0
	global_load_lds_dwordx4 v134, s[44:45]
	s_waitcnt vmcnt(8)
	s_waitcnt lgkmcnt(0)
	s_setprio 1
	s_barrier
	v_mfma_f32_16x16x32_bf16 v[124:127], v[146:149], v[184:187], v[124:127]
	v_mfma_f32_16x16x32_bf16 v[120:123], v[160:163], v[184:187], v[120:123]
	v_mfma_f32_16x16x32_bf16 v[108:111], v[146:149], v[192:195], v[108:111]
	v_mfma_f32_16x16x32_bf16 v[104:107], v[160:163], v[192:195], v[104:107]
	v_mfma_f32_16x16x32_bf16 v[92:95], v[146:149], v[200:203], v[92:95]
	v_mfma_f32_16x16x32_bf16 v[88:91], v[160:163], v[200:203], v[88:91]
	v_mfma_f32_16x16x32_bf16 v[76:79], v[146:149], v[210:213], v[76:79]
	v_mfma_f32_16x16x32_bf16 v[72:75], v[160:163], v[210:213], v[72:75]
	v_mfma_f32_16x16x32_bf16 v[124:127], v[156:159], v[188:191], v[124:127]
	v_mfma_f32_16x16x32_bf16 v[120:123], v[164:167], v[188:191], v[120:123]
	v_mfma_f32_16x16x32_bf16 v[108:111], v[156:159], v[196:199], v[108:111]
	v_mfma_f32_16x16x32_bf16 v[104:107], v[164:167], v[196:199], v[104:107]
	v_mfma_f32_16x16x32_bf16 v[92:95], v[156:159], v[206:209], v[92:95]
	v_mfma_f32_16x16x32_bf16 v[88:91], v[164:167], v[206:209], v[88:91]
	v_mfma_f32_16x16x32_bf16 v[76:79], v[156:159], v[214:217], v[76:79]
	v_mfma_f32_16x16x32_bf16 v[72:75], v[164:167], v[214:217], v[72:75]
	v_mfma_f32_16x16x32_bf16 v[116:119], v[168:171], v[184:187], v[116:119]
	v_mfma_f32_16x16x32_bf16 v[112:115], v[176:179], v[184:187], v[112:115]
	v_mfma_f32_16x16x32_bf16 v[100:103], v[168:171], v[192:195], v[100:103]
	v_mfma_f32_16x16x32_bf16 v[96:99], v[176:179], v[192:195], v[96:99]
	v_mfma_f32_16x16x32_bf16 v[84:87], v[168:171], v[200:203], v[84:87]
	v_mfma_f32_16x16x32_bf16 v[80:83], v[176:179], v[200:203], v[80:83]
	v_mfma_f32_16x16x32_bf16 v[68:71], v[168:171], v[210:213], v[68:71]
	v_mfma_f32_16x16x32_bf16 v[64:67], v[176:179], v[210:213], v[64:67]
	v_mfma_f32_16x16x32_bf16 v[116:119], v[172:175], v[188:191], v[116:119]
	v_mfma_f32_16x16x32_bf16 v[112:115], v[180:183], v[188:191], v[112:115]
	v_mfma_f32_16x16x32_bf16 v[100:103], v[172:175], v[196:199], v[100:103]
	v_mfma_f32_16x16x32_bf16 v[96:99], v[180:183], v[196:199], v[96:99]
	v_mfma_f32_16x16x32_bf16 v[84:87], v[172:175], v[206:209], v[84:87]
	v_mfma_f32_16x16x32_bf16 v[80:83], v[180:183], v[206:209], v[80:83]
	v_mfma_f32_16x16x32_bf16 v[68:71], v[172:175], v[214:217], v[68:71]
	v_mfma_f32_16x16x32_bf16 v[64:67], v[180:183], v[214:217], v[64:67]
	s_setprio 0
	s_barrier
	s_add_i32 s44, s63, s33
	s_mov_b32 m0, s44
	ds_read_b128 v[184:187], v153 offset:49152
	ds_read_b128 v[188:191], v153 offset:50176
	ds_read_b128 v[192:195], v153 offset:51200
	ds_read_b128 v[196:199], v153 offset:52224
	ds_read_b128 v[200:203], v153 offset:53248
	ds_read_b128 v[206:209], v153 offset:54272
	ds_read_b128 v[210:213], v153 offset:55296
	ds_read_b128 v[214:217], v153 offset:56320
	global_load_lds_dwordx4 v132, s[98:99]
	s_add_i32 m0, s44, 0x2000
	s_add_u32 s42, s42, 0x40080
	s_addc_u32 s43, s43, 0
	s_add_i32 s44, s64, s33
	global_load_lds_dwordx4 v136, s[98:99]
	s_mov_b32 m0, s44
	s_nop 0
	global_load_lds_dwordx4 v132, s[42:43]
	s_add_i32 m0, s44, 0x2000
	s_nop 0
	global_load_lds_dwordx4 v136, s[42:43]
	s_mov_b32 m0, s52
	s_nop 0
	global_load_lds_dwordx4 v130, s[100:101]
	s_mov_b32 m0, s53
	s_nop 0
	global_load_lds_dwordx4 v134, s[100:101]
	s_waitcnt vmcnt(8)
	s_waitcnt lgkmcnt(0)
	s_setprio 1
	s_barrier
	v_mfma_f32_16x16x32_bf16 v[60:63], v[146:149], v[184:187], v[60:63]
	v_mfma_f32_16x16x32_bf16 v[56:59], v[160:163], v[184:187], v[56:59]
	v_mfma_f32_16x16x32_bf16 v[44:47], v[146:149], v[192:195], v[44:47]
	v_mfma_f32_16x16x32_bf16 v[40:43], v[160:163], v[192:195], v[40:43]
	v_mfma_f32_16x16x32_bf16 v[28:31], v[146:149], v[200:203], v[28:31]
	v_mfma_f32_16x16x32_bf16 v[24:27], v[160:163], v[200:203], v[24:27]
	v_mfma_f32_16x16x32_bf16 v[12:15], v[146:149], v[210:213], v[12:15]
	v_mfma_f32_16x16x32_bf16 v[8:11], v[160:163], v[210:213], v[8:11]
	v_mfma_f32_16x16x32_bf16 v[60:63], v[156:159], v[188:191], v[60:63]
	v_mfma_f32_16x16x32_bf16 v[56:59], v[164:167], v[188:191], v[56:59]
	v_mfma_f32_16x16x32_bf16 v[44:47], v[156:159], v[196:199], v[44:47]
	v_mfma_f32_16x16x32_bf16 v[40:43], v[164:167], v[196:199], v[40:43]
	v_mfma_f32_16x16x32_bf16 v[28:31], v[156:159], v[206:209], v[28:31]
	v_mfma_f32_16x16x32_bf16 v[24:27], v[164:167], v[206:209], v[24:27]
	v_mfma_f32_16x16x32_bf16 v[12:15], v[156:159], v[214:217], v[12:15]
	v_mfma_f32_16x16x32_bf16 v[8:11], v[164:167], v[214:217], v[8:11]
	v_mfma_f32_16x16x32_bf16 v[52:55], v[168:171], v[184:187], v[52:55]
	v_mfma_f32_16x16x32_bf16 v[48:51], v[176:179], v[184:187], v[48:51]
	v_mfma_f32_16x16x32_bf16 v[36:39], v[168:171], v[192:195], v[36:39]
	v_mfma_f32_16x16x32_bf16 v[32:35], v[176:179], v[192:195], v[32:35]
	v_mfma_f32_16x16x32_bf16 v[20:23], v[168:171], v[200:203], v[20:23]
	v_mfma_f32_16x16x32_bf16 v[16:19], v[176:179], v[200:203], v[16:19]
	v_mfma_f32_16x16x32_bf16 v[4:7], v[168:171], v[210:213], v[4:7]
	v_mfma_f32_16x16x32_bf16 v[0:3], v[176:179], v[210:213], v[0:3]
	v_mfma_f32_16x16x32_bf16 v[52:55], v[172:175], v[188:191], v[52:55]
	v_mfma_f32_16x16x32_bf16 v[48:51], v[180:183], v[188:191], v[48:51]
	v_mfma_f32_16x16x32_bf16 v[36:39], v[172:175], v[196:199], v[36:39]
	v_mfma_f32_16x16x32_bf16 v[32:35], v[180:183], v[196:199], v[32:35]
	v_mfma_f32_16x16x32_bf16 v[20:23], v[172:175], v[206:209], v[20:23]
	v_mfma_f32_16x16x32_bf16 v[16:19], v[180:183], v[206:209], v[16:19]
	v_mfma_f32_16x16x32_bf16 v[4:7], v[172:175], v[214:217], v[4:7]
	v_mfma_f32_16x16x32_bf16 v[0:3], v[180:183], v[214:217], v[0:3]
	s_setprio 0
	s_barrier
	s_add_i32 s62, s62, 2
	s_add_u32 s40, s40, 0x100
	s_addc_u32 s41, s41, 0
	s_add_u32 s60, s60, 0x100
	s_addc_u32 s61, s61, 0
	s_cmp_gt_u32 s62, 13
	s_cbranch_scc0 .LBB0_905
	s_and_b64 vcc, exec, s[28:29]
	s_cbranch_vccz .LBB0_908
	s_barrier

; #define PG8_STAGE(bufoff, gbase, voff) do { _Pragma("unroll") for (int _i = 0; _i < 2; ++_i) \
;         __builtin_amdgcn_global_load_lds((const unsigned*)((const char*)(gbase) + (voff)[_i]), (PG8_LAS unsigned*)(lds + (bufoff) + ldsw + _i * 8192), 16, 0, 0); } while (0)
; #define PG8_LDA(dst, b, h) do { _Pragma("unroll") for (int m = 0; m < 4; ++m) _Pragma("unroll") for (int k = 0; k < 2; ++k) dst[m][k] = *(const PG8_LAS bf16x8*)(lds + PG8_SA(b, h) + aoff + m * 2048 + k * 1024); } while (0)
; #define PG8_LDB(dst, b, h) do { _Pragma("unroll") for (int n = 0; n < 2; ++n) _Pragma("unroll") for (int k = 0; k < 2; ++k) dst[n][k] = *(const PG8_LAS bf16x8*)(lds + PG8_SB(b, h) + boff + n * 2048 + k * 1024); } while (0)
; #define PG8_WAIT_V(n) asm volatile("s_waitcnt vmcnt(" #n ")" ::: "memory")
; #define PG8_WAIT_L(n) asm volatile("s_waitcnt lgkmcnt(" #n ")" ::: "memory")
; #define PG8_BAR __builtin_amdgcn_s_barrier()
; template <class Epi, class Sched, bool ALIGN_EPI = false, bool SP2 = false>
; __device__ __forceinline__ void gemm_phase(PG8_LAS unsigned char* lds, const Gemm g, const Sched& S, const Epi& E) {
;     ...
;         const bool has_next = S.next(ui + 1, nxt);
;         const char* nA = has_next ? (const char*)g.A + (size_t)nxt.pm * tstep : cA; const char* nB = has_next ? (const char*)g.Bt + (size_t)nxt.pn * tstep : cB;
;         for (int t = 0; t < nt; t += 2) {
;             const bool last = (t == nt - 2);
;             const char* a1 = cA + (size_t)(t + 1) * kstep;
;             const char* a2 = last ? nA : cA + (size_t)(t + 2) * kstep; const char* b2 = last ? nB : cB + (size_t)(t + 2) * kstep;
;             const char* a3 = a2 + kstep; const char* b3 = b2 + kstep;
;             if (last && has_next) S.a_ready(nxt);
;             if constexpr (SP2) {
;             PG8_LDB(B0, 0, 0); PG8_LDB(B1, 0, 1); PG8_SCHED; PG8_LDA(At, 0, 0); PG8_STAGE(PG8_SA(1, 1), a1 + hstep, voffA);
;             PG8_WAIT_V(8); PG8_WAIT_L(0); PG8_BAR; PG8_MMA(0, 0, At, B0); PG8_MMA(0, 1, At, B1); PG8_BAR; PG8_SCHED;
;     ...
; #pragma unroll
;         for (int a = 0; a < 2; ++a)
; #pragma unroll
;             for (int b = 0; b < 2; ++b)
; #pragma unroll
;                 for (int m = 0; m < 4; ++m)
; #pragma unroll
;                     for (int n = 0; n < 2; ++n) acc[a][b][m][n] = (f32x4){0.f, 0.f, 0.f, 0.f};
;         cur = nxt; cA = nA; cB = nB; ++ui;
.LBB0_1000:
	s_ashr_i32 s21, s20, 31
	s_lshl_b64 s[22:23], s[20:21], 21
	v_readlane_b32 s16, v255, 26
	v_readlane_b32 s17, v255, 27
	s_add_u32 s22, s16, s22
	s_addc_u32 s23, s17, s23
	s_and_b64 s[24:25], s[6:7], exec
	s_cselect_b32 s21, s23, s29
	s_cselect_b32 s47, s22, s28
	s_ashr_i32 s19, s18, 31
	s_lshl_b64 s[24:25], s[18:19], 21
	s_add_u32 s24, s66, s24
	s_addc_u32 s25, s67, s25
	s_and_b64 s[34:35], s[6:7], exec
	s_cselect_b32 s19, s25, s31
	s_cselect_b32 s48, s24, s30
	s_add_u32 s28, s28, 0x100080
	s_addc_u32 s29, s29, 0
	s_add_u32 s49, s30, 0x100
	v_mov_b32_e32 v0, 0
	s_addc_u32 s50, s31, 0
	s_mov_b32 s51, -2
	v_mov_b32_e32 v1, v0
	v_mov_b32_e32 v2, v0
	v_mov_b32_e32 v3, v0
	v_mov_b32_e32 v4, v0
	v_mov_b32_e32 v5, v0
	v_mov_b32_e32 v6, v0
	v_mov_b32_e32 v7, v0
	v_mov_b32_e32 v16, v0
	v_mov_b32_e32 v17, v0
	v_mov_b32_e32 v18, v0
	v_mov_b32_e32 v19, v0
	v_mov_b32_e32 v20, v0
	v_mov_b32_e32 v21, v0
	v_mov_b32_e32 v22, v0
	v_mov_b32_e32 v23, v0
	v_mov_b32_e32 v32, v0
	v_mov_b32_e32 v33, v0
	v_mov_b32_e32 v34, v0
	v_mov_b32_e32 v35, v0
	v_mov_b32_e32 v36, v0
	v_mov_b32_e32 v37, v0
	v_mov_b32_e32 v38, v0
	v_mov_b32_e32 v39, v0
	v_mov_b32_e32 v48, v0
	v_mov_b32_e32 v49, v0
	v_mov_b32_e32 v50, v0
	v_mov_b32_e32 v51, v0
	v_mov_b32_e32 v52, v0
	v_mov_b32_e32 v53, v0
	v_mov_b32_e32 v54, v0
	v_mov_b32_e32 v55, v0
	v_mov_b32_e32 v8, v0
	v_mov_b32_e32 v9, v0
	v_mov_b32_e32 v10, v0
	v_mov_b32_e32 v11, v0
	v_mov_b32_e32 v12, v0
	v_mov_b32_e32 v13, v0
	v_mov_b32_e32 v14, v0
	v_mov_b32_e32 v15, v0
	v_mov_b32_e32 v24, v0
	v_mov_b32_e32 v25, v0
	v_mov_b32_e32 v26, v0
	v_mov_b32_e32 v27, v0
	v_mov_b32_e32 v28, v0
	v_mov_b32_e32 v29, v0
	v_mov_b32_e32 v30, v0
	v_mov_b32_e32 v31, v0
	v_mov_b32_e32 v40, v0
	v_mov_b32_e32 v41, v0
	v_mov_b32_e32 v42, v0
	v_mov_b32_e32 v43, v0
	v_mov_b32_e32 v44, v0
	v_mov_b32_e32 v45, v0
	v_mov_b32_e32 v46, v0
	v_mov_b32_e32 v47, v0
	v_mov_b32_e32 v56, v0
	v_mov_b32_e32 v57, v0
	v_mov_b32_e32 v58, v0
	v_mov_b32_e32 v59, v0
	v_mov_b32_e32 v60, v0
	v_mov_b32_e32 v61, v0
	v_mov_b32_e32 v62, v0
	v_mov_b32_e32 v63, v0
	v_mov_b32_e32 v64, v0
	v_mov_b32_e32 v65, v0
	v_mov_b32_e32 v66, v0
	v_mov_b32_e32 v67, v0
	v_mov_b32_e32 v68, v0
	v_mov_b32_e32 v69, v0
	v_mov_b32_e32 v70, v0
	v_mov_b32_e32 v71, v0
	v_mov_b32_e32 v80, v0
	v_mov_b32_e32 v81, v0
	v_mov_b32_e32 v82, v0
	v_mov_b32_e32 v83, v0
	v_mov_b32_e32 v84, v0
	v_mov_b32_e32 v85, v0
	v_mov_b32_e32 v86, v0
	v_mov_b32_e32 v87, v0
	v_mov_b32_e32 v96, v0
	v_mov_b32_e32 v97, v0
	v_mov_b32_e32 v98, v0
	v_mov_b32_e32 v99, v0
	v_mov_b32_e32 v100, v0
	v_mov_b32_e32 v101, v0
	v_mov_b32_e32 v102, v0
	v_mov_b32_e32 v103, v0
	v_mov_b32_e32 v112, v0
	v_mov_b32_e32 v113, v0
	v_mov_b32_e32 v114, v0
	v_mov_b32_e32 v115, v0
	v_mov_b32_e32 v116, v0
	v_mov_b32_e32 v117, v0
	v_mov_b32_e32 v118, v0
	v_mov_b32_e32 v119, v0
	v_mov_b32_e32 v72, v0
	v_mov_b32_e32 v73, v0
	v_mov_b32_e32 v74, v0
	v_mov_b32_e32 v75, v0
	v_mov_b32_e32 v76, v0
	v_mov_b32_e32 v77, v0
	v_mov_b32_e32 v78, v0
	v_mov_b32_e32 v79, v0
	v_mov_b32_e32 v88, v0
	v_mov_b32_e32 v89, v0
	v_mov_b32_e32 v90, v0
	v_mov_b32_e32 v91, v0
	v_mov_b32_e32 v92, v0
	v_mov_b32_e32 v93, v0
	v_mov_b32_e32 v94, v0
	v_mov_b32_e32 v95, v0
	v_mov_b32_e32 v104, v0
	v_mov_b32_e32 v105, v0
	v_mov_b32_e32 v106, v0
	v_mov_b32_e32 v107, v0
	v_mov_b32_e32 v108, v0
	v_mov_b32_e32 v109, v0
	v_mov_b32_e32 v110, v0
	v_mov_b32_e32 v111, v0
	v_mov_b32_e32 v120, v0
	v_mov_b32_e32 v121, v0
	v_mov_b32_e32 v122, v0
	v_mov_b32_e32 v123, v0
	v_mov_b32_e32 v124, v0
	v_mov_b32_e32 v125, v0
	v_mov_b32_e32 v126, v0
	v_mov_b32_e32 v127, v0
	v_add_u32_e32 v240, 0x18000, v150
	v_add_u32_e32 v241, 0x1c000, v150
.LBB0_1001:
	ds_read_b128 v[146:149], v152
	ds_read_b128 v[156:159], v152 offset:1024
	ds_read_b128 v[160:163], v152 offset:2048
	ds_read_b128 v[164:167], v152 offset:3072
	ds_read_b128 v[168:171], v153
	ds_read_b128 v[172:175], v153 offset:1024
	ds_read_b128 v[176:179], v153 offset:2048
	ds_read_b128 v[180:183], v153 offset:3072
	s_add_u32 s30, s28, 0xfff00080
	s_addc_u32 s31, s29, -1
	s_cmp_eq_u32 s51, 60
	s_cselect_b32 s35, s21, s31
	s_cselect_b32 s34, s47, s30
	s_cselect_b32 s31, s19, s50
	s_cselect_b32 s30, s48, s49
	s_add_i32 m0, s27, 0xc000
	ds_read_b128 v[184:187], v154
	ds_read_b128 v[188:191], v154 offset:1024
	ds_read_b128 v[192:195], v154 offset:2048
	ds_read_b128 v[196:199], v154 offset:3072
	ds_read_b128 v[200:203], v154 offset:4096
	ds_read_b128 v[206:209], v154 offset:5120
	ds_read_b128 v[210:213], v154 offset:6144
	ds_read_b128 v[214:217], v154 offset:7168
	global_load_lds_dwordx4 v138, s[28:29]
	s_add_i32 m0, s27, 0xe000
	s_nop 0
	global_load_lds_dwordx4 v140, s[28:29]
	s_waitcnt vmcnt(8)
	s_waitcnt lgkmcnt(0)
	s_setprio 1
	s_barrier
; #define PG8_STAGE(bufoff, gbase, voff) do { _Pragma("unroll") for (int _i = 0; _i < 2; ++_i) \
;         __builtin_amdgcn_global_load_lds((const unsigned*)((const char*)(gbase) + (voff)[_i]), (PG8_LAS unsigned*)(lds + (bufoff) + ldsw + _i * 8192), 16, 0, 0); } while (0)
; #define PG8_LDA(dst, b, h) do { _Pragma("unroll") for (int m = 0; m < 4; ++m) _Pragma("unroll") for (int k = 0; k < 2; ++k) dst[m][k] = *(const PG8_LAS bf16x8*)(lds + PG8_SA(b, h) + aoff + m * 2048 + k * 1024); } while (0)
; #define PG8_MMA(ai, bj, At, Bt) do { __builtin_amdgcn_s_setprio(1); _Pragma("unroll") for (int m = 0; m < 4; ++m) _Pragma("unroll") for (int n = 0; n < 2; ++n) _Pragma("unroll") for (int k = 0; k < 2; ++k) \
;         acc[ai][bj][m][n] = __builtin_amdgcn_mfma_f32_16x16x32_bf16(Bt[n][k], At[m][k], acc[ai][bj][m][n], 0, 0, 0); __builtin_amdgcn_s_setprio(0); } while (0)
; #define PG8_WAIT_V(n) asm volatile("s_waitcnt vmcnt(" #n ")" ::: "memory")
; #define PG8_WAIT_L(n) asm volatile("s_waitcnt lgkmcnt(" #n ")" ::: "memory")
; #define PG8_BAR __builtin_amdgcn_s_barrier()
; #define PG8_SCHED __builtin_amdgcn_sched_barrier(0)
; template <class Epi, class Sched, bool ALIGN_EPI = false, bool SP2 = false>
; __device__ __forceinline__ void gemm_phase(PG8_LAS unsigned char* lds, const Gemm g, const Sched& S, const Epi& E) {
;     ...
;             PG8_WAIT_V(8); PG8_WAIT_L(0); PG8_BAR; PG8_MMA(0, 0, At, B0); PG8_MMA(0, 1, At, B1); PG8_BAR; PG8_SCHED;
;             PG8_LDA(At, 0, 1); PG8_STAGE(PG8_SB(0, 0), b2, voffB); PG8_STAGE(PG8_SB(0, 1), b2 + hstep, voffB); PG8_STAGE(PG8_SA(0, 0), a2, voffA);
;             PG8_WAIT_V(8); PG8_WAIT_L(0); PG8_BAR; PG8_MMA(1, 0, At, B0); PG8_MMA(1, 1, At, B1); PG8_BAR; PG8_SCHED;
	v_mfma_f32_16x16x32_bf16 v[124:127], v[146:149], v[184:187], v[124:127]
	v_mfma_f32_16x16x32_bf16 v[120:123], v[160:163], v[184:187], v[120:123]
	v_mfma_f32_16x16x32_bf16 v[108:111], v[146:149], v[192:195], v[108:111]
	v_mfma_f32_16x16x32_bf16 v[104:107], v[160:163], v[192:195], v[104:107]
	v_mfma_f32_16x16x32_bf16 v[92:95], v[146:149], v[200:203], v[92:95]
	v_mfma_f32_16x16x32_bf16 v[88:91], v[160:163], v[200:203], v[88:91]
	v_mfma_f32_16x16x32_bf16 v[76:79], v[146:149], v[210:213], v[76:79]
	v_mfma_f32_16x16x32_bf16 v[72:75], v[160:163], v[210:213], v[72:75]
	v_mfma_f32_16x16x32_bf16 v[124:127], v[156:159], v[188:191], v[124:127]
	v_mfma_f32_16x16x32_bf16 v[120:123], v[164:167], v[188:191], v[120:123]
	v_mfma_f32_16x16x32_bf16 v[108:111], v[156:159], v[196:199], v[108:111]
	v_mfma_f32_16x16x32_bf16 v[104:107], v[164:167], v[196:199], v[104:107]
	v_mfma_f32_16x16x32_bf16 v[92:95], v[156:159], v[206:209], v[92:95]
	v_mfma_f32_16x16x32_bf16 v[88:91], v[164:167], v[206:209], v[88:91]
	v_mfma_f32_16x16x32_bf16 v[76:79], v[156:159], v[214:217], v[76:79]
	v_mfma_f32_16x16x32_bf16 v[72:75], v[164:167], v[214:217], v[72:75]
	v_mfma_f32_16x16x32_bf16 v[116:119], v[168:171], v[184:187], v[116:119]
	v_mfma_f32_16x16x32_bf16 v[112:115], v[176:179], v[184:187], v[112:115]
	v_mfma_f32_16x16x32_bf16 v[100:103], v[168:171], v[192:195], v[100:103]
	v_mfma_f32_16x16x32_bf16 v[96:99], v[176:179], v[192:195], v[96:99]
	v_mfma_f32_16x16x32_bf16 v[84:87], v[168:171], v[200:203], v[84:87]
	v_mfma_f32_16x16x32_bf16 v[80:83], v[176:179], v[200:203], v[80:83]
	v_mfma_f32_16x16x32_bf16 v[68:71], v[168:171], v[210:213], v[68:71]
	v_mfma_f32_16x16x32_bf16 v[64:67], v[176:179], v[210:213], v[64:67]
	v_mfma_f32_16x16x32_bf16 v[116:119], v[172:175], v[188:191], v[116:119]
	v_mfma_f32_16x16x32_bf16 v[112:115], v[180:183], v[188:191], v[112:115]
	v_mfma_f32_16x16x32_bf16 v[100:103], v[172:175], v[196:199], v[100:103]
	v_mfma_f32_16x16x32_bf16 v[96:99], v[180:183], v[196:199], v[96:99]
	v_mfma_f32_16x16x32_bf16 v[84:87], v[172:175], v[206:209], v[84:87]
	v_mfma_f32_16x16x32_bf16 v[80:83], v[180:183], v[206:209], v[80:83]
	v_mfma_f32_16x16x32_bf16 v[68:71], v[172:175], v[214:217], v[68:71]
	v_mfma_f32_16x16x32_bf16 v[64:67], v[180:183], v[214:217], v[64:67]
	s_setprio 0
	s_barrier
	s_add_i32 s52, s44, s33
	s_mov_b32 m0, s52
	ds_read_b128 v[184:187], v154 offset:16384
	ds_read_b128 v[188:191], v154 offset:17408
	ds_read_b128 v[192:195], v154 offset:18432
	ds_read_b128 v[196:199], v154 offset:19456
	ds_read_b128 v[200:203], v154 offset:20480
	ds_read_b128 v[206:209], v154 offset:21504
	ds_read_b128 v[210:213], v154 offset:22528
	ds_read_b128 v[214:217], v154 offset:23552
	global_load_lds_dwordx4 v132, s[30:31]
	s_add_i32 m0, s52, 0x2000
	s_add_u32 s98, s30, 0x80
	s_addc_u32 s99, s31, 0
	s_add_u32 s52, s30, 0x100000
	s_addc_u32 s53, s31, 0
	s_add_i32 s54, s45, s33
	global_load_lds_dwordx4 v136, s[30:31]
	s_mov_b32 m0, s54
	s_nop 0
	global_load_lds_dwordx4 v132, s[52:53]
	s_add_i32 m0, s54, 0x2000
	s_nop 0
	global_load_lds_dwordx4 v136, s[52:53]
	s_mov_b32 m0, s27
	s_nop 0
	global_load_lds_dwordx4 v130, s[34:35]
	s_mov_b32 m0, s36
	s_nop 0
	global_load_lds_dwordx4 v134, s[34:35]
	s_waitcnt vmcnt(8)
	s_waitcnt lgkmcnt(0)
	s_setprio 1
	s_barrier
	v_mfma_f32_16x16x32_bf16 v[60:63], v[146:149], v[184:187], v[60:63]
	v_mfma_f32_16x16x32_bf16 v[56:59], v[160:163], v[184:187], v[56:59]
	v_mfma_f32_16x16x32_bf16 v[44:47], v[146:149], v[192:195], v[44:47]
	v_mfma_f32_16x16x32_bf16 v[40:43], v[160:163], v[192:195], v[40:43]
	v_mfma_f32_16x16x32_bf16 v[28:31], v[146:149], v[200:203], v[28:31]
	v_mfma_f32_16x16x32_bf16 v[24:27], v[160:163], v[200:203], v[24:27]
	v_mfma_f32_16x16x32_bf16 v[12:15], v[146:149], v[210:213], v[12:15]
	v_mfma_f32_16x16x32_bf16 v[8:11], v[160:163], v[210:213], v[8:11]
	v_mfma_f32_16x16x32_bf16 v[60:63], v[156:159], v[188:191], v[60:63]
	v_mfma_f32_16x16x32_bf16 v[56:59], v[164:167], v[188:191], v[56:59]
	v_mfma_f32_16x16x32_bf16 v[44:47], v[156:159], v[196:199], v[44:47]
	v_mfma_f32_16x16x32_bf16 v[40:43], v[164:167], v[196:199], v[40:43]
	v_mfma_f32_16x16x32_bf16 v[28:31], v[156:159], v[206:209], v[28:31]
	v_mfma_f32_16x16x32_bf16 v[24:27], v[164:167], v[206:209], v[24:27]
	v_mfma_f32_16x16x32_bf16 v[12:15], v[156:159], v[214:217], v[12:15]
	v_mfma_f32_16x16x32_bf16 v[8:11], v[164:167], v[214:217], v[8:11]
	v_mfma_f32_16x16x32_bf16 v[52:55], v[168:171], v[184:187], v[52:55]
	v_mfma_f32_16x16x32_bf16 v[48:51], v[176:179], v[184:187], v[48:51]
	v_mfma_f32_16x16x32_bf16 v[36:39], v[168:171], v[192:195], v[36:39]
	v_mfma_f32_16x16x32_bf16 v[32:35], v[176:179], v[192:195], v[32:35]
	v_mfma_f32_16x16x32_bf16 v[20:23], v[168:171], v[200:203], v[20:23]
	v_mfma_f32_16x16x32_bf16 v[16:19], v[176:179], v[200:203], v[16:19]
	v_mfma_f32_16x16x32_bf16 v[4:7], v[168:171], v[210:213], v[4:7]
	v_mfma_f32_16x16x32_bf16 v[0:3], v[176:179], v[210:213], v[0:3]
	v_mfma_f32_16x16x32_bf16 v[52:55], v[172:175], v[188:191], v[52:55]
	v_mfma_f32_16x16x32_bf16 v[48:51], v[180:183], v[188:191], v[48:51]
	v_mfma_f32_16x16x32_bf16 v[36:39], v[172:175], v[196:199], v[36:39]
	v_mfma_f32_16x16x32_bf16 v[32:35], v[180:183], v[196:199], v[32:35]
	v_mfma_f32_16x16x32_bf16 v[20:23], v[172:175], v[206:209], v[20:23]
	v_mfma_f32_16x16x32_bf16 v[16:19], v[180:183], v[206:209], v[16:19]
	v_mfma_f32_16x16x32_bf16 v[4:7], v[172:175], v[214:217], v[4:7]
	v_mfma_f32_16x16x32_bf16 v[0:3], v[180:183], v[214:217], v[0:3]
	s_setprio 0
	s_barrier
; #define PG8_STAGE(bufoff, gbase, voff) do { _Pragma("unroll") for (int _i = 0; _i < 2; ++_i) \
;         __builtin_amdgcn_global_load_lds((const unsigned*)((const char*)(gbase) + (voff)[_i]), (PG8_LAS unsigned*)(lds + (bufoff) + ldsw + _i * 8192), 16, 0, 0); } while (0)
; #define PG8_LDA(dst, b, h) do { _Pragma("unroll") for (int m = 0; m < 4; ++m) _Pragma("unroll") for (int k = 0; k < 2; ++k) dst[m][k] = *(const PG8_LAS bf16x8*)(lds + PG8_SA(b, h) + aoff + m * 2048 + k * 1024); } while (0)
; #define PG8_LDB(dst, b, h) do { _Pragma("unroll") for (int n = 0; n < 2; ++n) _Pragma("unroll") for (int k = 0; k < 2; ++k) dst[n][k] = *(const PG8_LAS bf16x8*)(lds + PG8_SB(b, h) + boff + n * 2048 + k * 1024); } while (0)
; #define PG8_MMA(ai, bj, At, Bt) do { __builtin_amdgcn_s_setprio(1); _Pragma("unroll") for (int m = 0; m < 4; ++m) _Pragma("unroll") for (int n = 0; n < 2; ++n) _Pragma("unroll") for (int k = 0; k < 2; ++k) \
;         acc[ai][bj][m][n] = __builtin_amdgcn_mfma_f32_16x16x32_bf16(Bt[n][k], At[m][k], acc[ai][bj][m][n], 0, 0, 0); __builtin_amdgcn_s_setprio(0); } while (0)
; #define PG8_WAIT_V(n) asm volatile("s_waitcnt vmcnt(" #n ")" ::: "memory")
; #define PG8_WAIT_L(n) asm volatile("s_waitcnt lgkmcnt(" #n ")" ::: "memory")
; #define PG8_BAR __builtin_amdgcn_s_barrier()
; #define PG8_SCHED __builtin_amdgcn_sched_barrier(0)
; template <class Epi, class Sched, bool ALIGN_EPI = false, bool SP2 = false>
; __device__ __forceinline__ void gemm_phase(PG8_LAS unsigned char* lds, const Gemm g, const Sched& S, const Epi& E) {
;     ...
;         for (int t = 0; t < nt; t += 2) {
;     ...
;             PG8_LDB(B0, 1, 0); PG8_LDB(B1, 1, 1); PG8_SCHED; PG8_LDA(At, 1, 0); PG8_STAGE(PG8_SA(0, 1), a2 + hstep, voffA);
;             PG8_WAIT_V(8); PG8_WAIT_L(0); PG8_BAR; PG8_MMA(0, 0, At, B0); PG8_MMA(0, 1, At, B1); PG8_BAR; PG8_SCHED;
;             PG8_LDA(At, 1, 1); PG8_STAGE(PG8_SB(1, 0), b3, voffB); PG8_STAGE(PG8_SB(1, 1), b3 + hstep, voffB); PG8_STAGE(PG8_SA(1, 0), a3, voffA);
;             PG8_WAIT_V(8); PG8_WAIT_L(0); PG8_BAR; PG8_MMA(1, 0, At, B0); PG8_MMA(1, 1, At, B1); PG8_BAR; PG8_SCHED;
	s_add_i32 s52, 0, 0x18000
	s_add_i32 s53, 0, 0x1c000
	ds_read_b128 v[146:149], v240
	ds_read_b128 v[156:159], v240 offset:1024
	ds_read_b128 v[160:163], v240 offset:2048
	ds_read_b128 v[164:167], v240 offset:3072
	ds_read_b128 v[168:171], v241
	ds_read_b128 v[172:175], v241 offset:1024
	ds_read_b128 v[176:179], v241 offset:2048
	ds_read_b128 v[180:183], v241 offset:3072
	s_add_u32 s100, s34, 0x80
	s_addc_u32 s101, s35, 0
	s_add_u32 s34, s34, 0x100000
	s_addc_u32 s35, s35, 0
	s_mov_b32 m0, s37
	ds_read_b128 v[184:187], v154 offset:32768
	ds_read_b128 v[188:191], v154 offset:33792
	ds_read_b128 v[192:195], v154 offset:34816
	ds_read_b128 v[196:199], v154 offset:35840
	ds_read_b128 v[200:203], v154 offset:36864
	ds_read_b128 v[206:209], v154 offset:37888
	ds_read_b128 v[210:213], v154 offset:38912
	ds_read_b128 v[214:217], v154 offset:39936
	global_load_lds_dwordx4 v130, s[34:35]
	s_mov_b32 m0, s38
	s_nop 0
	global_load_lds_dwordx4 v134, s[34:35]
	s_waitcnt vmcnt(8)
	s_waitcnt lgkmcnt(0)
	s_setprio 1
	s_barrier
	v_mfma_f32_16x16x32_bf16 v[124:127], v[146:149], v[184:187], v[124:127]
	v_mfma_f32_16x16x32_bf16 v[120:123], v[160:163], v[184:187], v[120:123]
	v_mfma_f32_16x16x32_bf16 v[108:111], v[146:149], v[192:195], v[108:111]
	v_mfma_f32_16x16x32_bf16 v[104:107], v[160:163], v[192:195], v[104:107]
	v_mfma_f32_16x16x32_bf16 v[92:95], v[146:149], v[200:203], v[92:95]
	v_mfma_f32_16x16x32_bf16 v[88:91], v[160:163], v[200:203], v[88:91]
	v_mfma_f32_16x16x32_bf16 v[76:79], v[146:149], v[210:213], v[76:79]
	v_mfma_f32_16x16x32_bf16 v[72:75], v[160:163], v[210:213], v[72:75]
	v_mfma_f32_16x16x32_bf16 v[124:127], v[156:159], v[188:191], v[124:127]
	v_mfma_f32_16x16x32_bf16 v[120:123], v[164:167], v[188:191], v[120:123]
	v_mfma_f32_16x16x32_bf16 v[108:111], v[156:159], v[196:199], v[108:111]
	v_mfma_f32_16x16x32_bf16 v[104:107], v[164:167], v[196:199], v[104:107]
	v_mfma_f32_16x16x32_bf16 v[92:95], v[156:159], v[206:209], v[92:95]
	v_mfma_f32_16x16x32_bf16 v[88:91], v[164:167], v[206:209], v[88:91]
	v_mfma_f32_16x16x32_bf16 v[76:79], v[156:159], v[214:217], v[76:79]
	v_mfma_f32_16x16x32_bf16 v[72:75], v[164:167], v[214:217], v[72:75]
	v_mfma_f32_16x16x32_bf16 v[116:119], v[168:171], v[184:187], v[116:119]
	v_mfma_f32_16x16x32_bf16 v[112:115], v[176:179], v[184:187], v[112:115]
	v_mfma_f32_16x16x32_bf16 v[100:103], v[168:171], v[192:195], v[100:103]
	v_mfma_f32_16x16x32_bf16 v[96:99], v[176:179], v[192:195], v[96:99]
	v_mfma_f32_16x16x32_bf16 v[84:87], v[168:171], v[200:203], v[84:87]
	v_mfma_f32_16x16x32_bf16 v[80:83], v[176:179], v[200:203], v[80:83]
	v_mfma_f32_16x16x32_bf16 v[68:71], v[168:171], v[210:213], v[68:71]
	v_mfma_f32_16x16x32_bf16 v[64:67], v[176:179], v[210:213], v[64:67]
	v_mfma_f32_16x16x32_bf16 v[116:119], v[172:175], v[188:191], v[116:119]
	v_mfma_f32_16x16x32_bf16 v[112:115], v[180:183], v[188:191], v[112:115]
	v_mfma_f32_16x16x32_bf16 v[100:103], v[172:175], v[196:199], v[100:103]
	v_mfma_f32_16x16x32_bf16 v[96:99], v[180:183], v[196:199], v[96:99]
	v_mfma_f32_16x16x32_bf16 v[84:87], v[172:175], v[206:209], v[84:87]
	v_mfma_f32_16x16x32_bf16 v[80:83], v[180:183], v[206:209], v[80:83]
	v_mfma_f32_16x16x32_bf16 v[68:71], v[172:175], v[214:217], v[68:71]
	v_mfma_f32_16x16x32_bf16 v[64:67], v[180:183], v[214:217], v[64:67]
	s_setprio 0
	s_barrier
	s_add_i32 s34, s52, s33
	s_mov_b32 m0, s34
	ds_read_b128 v[184:187], v154 offset:49152
	ds_read_b128 v[188:191], v154 offset:50176
	ds_read_b128 v[192:195], v154 offset:51200
	ds_read_b128 v[196:199], v154 offset:52224
	ds_read_b128 v[200:203], v154 offset:53248
	ds_read_b128 v[206:209], v154 offset:54272
	ds_read_b128 v[210:213], v154 offset:55296
	ds_read_b128 v[214:217], v154 offset:56320
	global_load_lds_dwordx4 v132, s[98:99]
	s_add_i32 m0, s34, 0x2000
	s_add_u32 s30, s30, 0x100080
	s_addc_u32 s31, s31, 0
	s_add_i32 s34, s53, s33
	global_load_lds_dwordx4 v136, s[98:99]
	s_mov_b32 m0, s34
	s_nop 0
	global_load_lds_dwordx4 v132, s[30:31]
	s_add_i32 m0, s34, 0x2000
	s_nop 0
	global_load_lds_dwordx4 v136, s[30:31]
	s_mov_b32 m0, s40
	s_nop 0
	global_load_lds_dwordx4 v130, s[100:101]
	s_mov_b32 m0, s41
	s_nop 0
	global_load_lds_dwordx4 v134, s[100:101]
	s_waitcnt vmcnt(8)
	s_waitcnt lgkmcnt(0)
	s_setprio 1
	s_barrier
	v_mfma_f32_16x16x32_bf16 v[60:63], v[146:149], v[184:187], v[60:63]
	v_mfma_f32_16x16x32_bf16 v[56:59], v[160:163], v[184:187], v[56:59]
	v_mfma_f32_16x16x32_bf16 v[44:47], v[146:149], v[192:195], v[44:47]
	v_mfma_f32_16x16x32_bf16 v[40:43], v[160:163], v[192:195], v[40:43]
	v_mfma_f32_16x16x32_bf16 v[28:31], v[146:149], v[200:203], v[28:31]
	v_mfma_f32_16x16x32_bf16 v[24:27], v[160:163], v[200:203], v[24:27]
	v_mfma_f32_16x16x32_bf16 v[12:15], v[146:149], v[210:213], v[12:15]
	v_mfma_f32_16x16x32_bf16 v[8:11], v[160:163], v[210:213], v[8:11]
	v_mfma_f32_16x16x32_bf16 v[60:63], v[156:159], v[188:191], v[60:63]
	v_mfma_f32_16x16x32_bf16 v[56:59], v[164:167], v[188:191], v[56:59]
	v_mfma_f32_16x16x32_bf16 v[44:47], v[156:159], v[196:199], v[44:47]
	v_mfma_f32_16x16x32_bf16 v[40:43], v[164:167], v[196:199], v[40:43]
	v_mfma_f32_16x16x32_bf16 v[28:31], v[156:159], v[206:209], v[28:31]
	v_mfma_f32_16x16x32_bf16 v[24:27], v[164:167], v[206:209], v[24:27]
	v_mfma_f32_16x16x32_bf16 v[12:15], v[156:159], v[214:217], v[12:15]
	v_mfma_f32_16x16x32_bf16 v[8:11], v[164:167], v[214:217], v[8:11]
	v_mfma_f32_16x16x32_bf16 v[52:55], v[168:171], v[184:187], v[52:55]
	v_mfma_f32_16x16x32_bf16 v[48:51], v[176:179], v[184:187], v[48:51]
	v_mfma_f32_16x16x32_bf16 v[36:39], v[168:171], v[192:195], v[36:39]
	v_mfma_f32_16x16x32_bf16 v[32:35], v[176:179], v[192:195], v[32:35]
	v_mfma_f32_16x16x32_bf16 v[20:23], v[168:171], v[200:203], v[20:23]
	v_mfma_f32_16x16x32_bf16 v[16:19], v[176:179], v[200:203], v[16:19]
	v_mfma_f32_16x16x32_bf16 v[4:7], v[168:171], v[210:213], v[4:7]
	v_mfma_f32_16x16x32_bf16 v[0:3], v[176:179], v[210:213], v[0:3]
	v_mfma_f32_16x16x32_bf16 v[52:55], v[172:175], v[188:191], v[52:55]
	v_mfma_f32_16x16x32_bf16 v[48:51], v[180:183], v[188:191], v[48:51]
	v_mfma_f32_16x16x32_bf16 v[36:39], v[172:175], v[196:199], v[36:39]
	v_mfma_f32_16x16x32_bf16 v[32:35], v[180:183], v[196:199], v[32:35]
	v_mfma_f32_16x16x32_bf16 v[20:23], v[172:175], v[206:209], v[20:23]
	v_mfma_f32_16x16x32_bf16 v[16:19], v[180:183], v[206:209], v[16:19]
	v_mfma_f32_16x16x32_bf16 v[4:7], v[172:175], v[214:217], v[4:7]
	v_mfma_f32_16x16x32_bf16 v[0:3], v[180:183], v[214:217], v[0:3]
	s_setprio 0
	s_barrier
	s_add_i32 s51, s51, 2
	s_add_u32 s28, s28, 0x100
	s_addc_u32 s29, s29, 0
	s_add_u32 s49, s49, 0x100
	s_addc_u32 s50, s50, 0
	s_cmp_gt_u32 s51, 61
	s_cbranch_scc0 .LBB0_1001
	s_and_b64 vcc, exec, s[14:15]
	s_cbranch_vccz .LBB0_1004
	s_barrier

; #define PG8_STAGE(bufoff, gbase, voff) do { _Pragma("unroll") for (int _i = 0; _i < 2; ++_i) \
;         __builtin_amdgcn_global_load_lds((const unsigned*)((const char*)(gbase) + (voff)[_i]), (PG8_LAS unsigned*)(lds + (bufoff) + ldsw + _i * 8192), 16, 0, 0); } while (0)
; #define PG8_LDA(dst, b, h) do { _Pragma("unroll") for (int m = 0; m < 4; ++m) _Pragma("unroll") for (int k = 0; k < 2; ++k) dst[m][k] = *(const PG8_LAS bf16x8*)(lds + PG8_SA(b, h) + aoff + m * 2048 + k * 1024); } while (0)
; #define PG8_WAIT_V(n) asm volatile("s_waitcnt vmcnt(" #n ")" ::: "memory")
; #define PG8_WAIT_L(n) asm volatile("s_waitcnt lgkmcnt(" #n ")" ::: "memory")
; template <class Epi, class Sched, bool ALIGN_EPI = false, bool SP2 = false>
; __device__ __forceinline__ void gemm_phase(PG8_LAS unsigned char* lds, const Gemm g, const Sched& S, const Epi& E) {
;     ...
;         const bool has_next = S.next(ui + 1, nxt);
;         const char* nA = has_next ? (const char*)g.A + (size_t)nxt.pm * tstep : cA; const char* nB = has_next ? (const char*)g.Bt + (size_t)nxt.pn * tstep : cB;
;         for (int t = 0; t < nt; t += 2) {
;             const bool last = (t == nt - 2);
;             const char* a1 = cA + (size_t)(t + 1) * kstep;
;             const char* a2 = last ? nA : cA + (size_t)(t + 2) * kstep; const char* b2 = last ? nB : cB + (size_t)(t + 2) * kstep;
;             const char* a3 = a2 + kstep; const char* b3 = b2 + kstep;
;             if (last && has_next) S.a_ready(nxt);
;             if constexpr (SP2) {
;             PG8_LDB(B0, 0, 0); PG8_LDB(B1, 0, 1); PG8_SCHED; PG8_LDA(At, 0, 0); PG8_STAGE(PG8_SA(1, 1), a1 + hstep, voffA);
;             PG8_WAIT_V(8); PG8_WAIT_L(0); PG8_BAR; PG8_MMA(0, 0, At, B0); PG8_MMA(0, 1, At, B1); PG8_BAR; PG8_SCHED;
;             PG8_LDA(At, 0, 1); PG8_STAGE(PG8_SB(0, 0), b2, voffB); PG8_STAGE(PG8_SB(0, 1), b2 + hstep, voffB); PG8_STAGE(PG8_SA(0, 0), a2, voffA);
;             PG8_WAIT_V(8); PG8_WAIT_L(0); PG8_BAR; PG8_MMA(1, 0, At, B0); PG8_MMA(1, 1, At, B1); PG8_BAR; PG8_SCHED;
;     ...
; #pragma unroll
;         for (int a = 0; a < 2; ++a)
; #pragma unroll
;             for (int b = 0; b < 2; ++b)
; #pragma unroll
;                 for (int m = 0; m < 4; ++m)
; #pragma unroll
;                     for (int n = 0; n < 2; ++n) acc[a][b][m][n] = (f32x4){0.f, 0.f, 0.f, 0.f};
;         cur = nxt; cA = nA; cB = nB; ++ui;
.LBB0_1024:
	s_add_u32 s25, s28, 0x100
	s_addc_u32 s48, s29, 0
	s_ashr_i32 s21, s20, 31
	s_lshl_b64 s[22:23], s[20:21], 21
	v_readlane_b32 s16, v255, 26
	v_readlane_b32 s17, v255, 27
	s_add_u32 s26, s16, s22
	s_addc_u32 s27, s17, s23
	s_and_b64 s[22:23], s[6:7], exec
	s_cselect_b32 s21, s27, s13
	s_cselect_b32 s49, s26, s12
	s_ashr_i32 s19, s18, 31
	s_lshl_b64 s[22:23], s[18:19], 21
	s_add_u32 s22, s66, s22
	s_addc_u32 s23, s67, s23
	s_and_b64 s[30:31], s[6:7], exec
	s_cselect_b32 s19, s23, s29
	s_cselect_b32 s50, s22, s28
	v_lshl_add_u64 v[140:141], s[12:13], 0, v[128:129]
	v_lshl_add_u64 v[142:143], s[12:13], 0, v[134:135]
	s_mov_b32 s51, -2
	s_mov_b64 s[28:29], 0
	v_add_u32_e32 v240, 0x10000, v146
	v_add_u32_e32 v241, 0x14000, v146
	v_add_u32_e32 v242, 0x18000, v146
	v_add_u32_e32 v243, 0x1c000, v146
.LBB0_1025:
	s_add_u32 s98, s12, s28
	s_addc_u32 s99, s13, s29
	s_add_u32 s30, s12, s28
	ds_read_b128 v[148:151], v240
	ds_read_b128 v[152:155], v240 offset:1024
	ds_read_b128 v[156:159], v240 offset:2048
	ds_read_b128 v[160:163], v240 offset:3072
	ds_read_b128 v[164:167], v241
	ds_read_b128 v[168:171], v241 offset:1024
	ds_read_b128 v[172:175], v241 offset:2048
	ds_read_b128 v[176:179], v241 offset:3072
	s_addc_u32 s31, s13, s29
	s_add_u32 s30, s30, 0x100
	s_addc_u32 s31, s31, 0
	s_add_u32 s52, s25, s28
	s_addc_u32 s53, s48, s29
	s_cmpk_eq_i32 s28, 0x1f00
	s_cselect_b32 s35, s21, s31
	s_cselect_b32 s34, s49, s30
	s_cselect_b32 s31, s19, s53
	s_cselect_b32 s30, s50, s52
	s_add_i32 m0, s11, 0xc000
	ds_read_b128 v[180:183], v147
	ds_read_b128 v[184:187], v147 offset:1024
	ds_read_b128 v[188:191], v147 offset:2048
	ds_read_b128 v[192:195], v147 offset:3072
	ds_read_b128 v[196:199], v147 offset:4096
	ds_read_b128 v[200:203], v147 offset:5120
	ds_read_b128 v[206:209], v147 offset:6144
	ds_read_b128 v[210:213], v147 offset:7168
	global_load_lds_dwordx4 v128, s[98:99]
	s_add_i32 m0, s11, 0xe000
	s_nop 0
	global_load_lds_dwordx4 v134, s[98:99]
	s_waitcnt vmcnt(8)
	s_waitcnt lgkmcnt(0)
	s_setprio 1
	s_barrier
	v_mfma_f32_16x16x32_bf16 v[124:127], v[148:151], v[180:183], v[124:127]
	v_mfma_f32_16x16x32_bf16 v[120:123], v[156:159], v[180:183], v[120:123]
	v_mfma_f32_16x16x32_bf16 v[108:111], v[148:151], v[188:191], v[108:111]
	v_mfma_f32_16x16x32_bf16 v[104:107], v[156:159], v[188:191], v[104:107]
	v_mfma_f32_16x16x32_bf16 v[92:95], v[148:151], v[196:199], v[92:95]
	v_mfma_f32_16x16x32_bf16 v[88:91], v[156:159], v[196:199], v[88:91]
	v_mfma_f32_16x16x32_bf16 v[76:79], v[148:151], v[206:209], v[76:79]
	v_mfma_f32_16x16x32_bf16 v[72:75], v[156:159], v[206:209], v[72:75]
	v_mfma_f32_16x16x32_bf16 v[124:127], v[152:155], v[184:187], v[124:127]
	v_mfma_f32_16x16x32_bf16 v[120:123], v[160:163], v[184:187], v[120:123]
	v_mfma_f32_16x16x32_bf16 v[108:111], v[152:155], v[192:195], v[108:111]
	v_mfma_f32_16x16x32_bf16 v[104:107], v[160:163], v[192:195], v[104:107]
	v_mfma_f32_16x16x32_bf16 v[92:95], v[152:155], v[200:203], v[92:95]
	v_mfma_f32_16x16x32_bf16 v[88:91], v[160:163], v[200:203], v[88:91]
	v_mfma_f32_16x16x32_bf16 v[76:79], v[152:155], v[210:213], v[76:79]
	v_mfma_f32_16x16x32_bf16 v[72:75], v[160:163], v[210:213], v[72:75]
	v_mfma_f32_16x16x32_bf16 v[116:119], v[164:167], v[180:183], v[116:119]
	v_mfma_f32_16x16x32_bf16 v[112:115], v[172:175], v[180:183], v[112:115]
	v_mfma_f32_16x16x32_bf16 v[100:103], v[164:167], v[188:191], v[100:103]
	v_mfma_f32_16x16x32_bf16 v[96:99], v[172:175], v[188:191], v[96:99]
	v_mfma_f32_16x16x32_bf16 v[84:87], v[164:167], v[196:199], v[84:87]
	v_mfma_f32_16x16x32_bf16 v[80:83], v[172:175], v[196:199], v[80:83]
	v_mfma_f32_16x16x32_bf16 v[68:71], v[164:167], v[206:209], v[68:71]
	v_mfma_f32_16x16x32_bf16 v[64:67], v[172:175], v[206:209], v[64:67]
	v_mfma_f32_16x16x32_bf16 v[116:119], v[168:171], v[184:187], v[116:119]
	v_mfma_f32_16x16x32_bf16 v[112:115], v[176:179], v[184:187], v[112:115]
	v_mfma_f32_16x16x32_bf16 v[100:103], v[168:171], v[192:195], v[100:103]
	v_mfma_f32_16x16x32_bf16 v[96:99], v[176:179], v[192:195], v[96:99]
	v_mfma_f32_16x16x32_bf16 v[84:87], v[168:171], v[200:203], v[84:87]
	v_mfma_f32_16x16x32_bf16 v[80:83], v[176:179], v[200:203], v[80:83]
	v_mfma_f32_16x16x32_bf16 v[68:71], v[168:171], v[210:213], v[68:71]
	v_mfma_f32_16x16x32_bf16 v[64:67], v[176:179], v[210:213], v[64:67]
	s_setprio 0
	s_barrier
	s_add_i32 s52, s46, s36
	s_mov_b32 m0, s52
	ds_read_b128 v[180:183], v147 offset:16384
	ds_read_b128 v[184:187], v147 offset:17408
	ds_read_b128 v[188:191], v147 offset:18432
	ds_read_b128 v[192:195], v147 offset:19456
	ds_read_b128 v[196:199], v147 offset:20480
	ds_read_b128 v[200:203], v147 offset:21504
	ds_read_b128 v[206:209], v147 offset:22528
	ds_read_b128 v[210:213], v147 offset:23552
	global_load_lds_dwordx4 v130, s[30:31]
	s_add_i32 m0, s52, 0x2000
	s_add_u32 s98, s30, 0x80
	s_addc_u32 s99, s31, 0
	s_add_u32 s52, s30, 0x100000
	s_addc_u32 s53, s31, 0
	s_add_i32 s54, s47, s36
	global_load_lds_dwordx4 v132, s[30:31]
	s_mov_b32 m0, s54
	s_nop 0
	global_load_lds_dwordx4 v130, s[52:53]
	s_add_i32 m0, s54, 0x2000
	s_nop 0
	global_load_lds_dwordx4 v132, s[52:53]
	s_mov_b32 m0, s11
	s_nop 0
	global_load_lds_dwordx4 v130, s[34:35]
	s_mov_b32 m0, s37
	s_nop 0
	global_load_lds_dwordx4 v132, s[34:35]
	s_waitcnt vmcnt(8)
	s_waitcnt lgkmcnt(0)
	s_setprio 1
	s_barrier
; #define PG8_STAGE(bufoff, gbase, voff) do { _Pragma("unroll") for (int _i = 0; _i < 2; ++_i) \
;         __builtin_amdgcn_global_load_lds((const unsigned*)((const char*)(gbase) + (voff)[_i]), (PG8_LAS unsigned*)(lds + (bufoff) + ldsw + _i * 8192), 16, 0, 0); } while (0)
; #define PG8_LDA(dst, b, h) do { _Pragma("unroll") for (int m = 0; m < 4; ++m) _Pragma("unroll") for (int k = 0; k < 2; ++k) dst[m][k] = *(const PG8_LAS bf16x8*)(lds + PG8_SA(b, h) + aoff + m * 2048 + k * 1024); } while (0)
; #define PG8_LDB(dst, b, h) do { _Pragma("unroll") for (int n = 0; n < 2; ++n) _Pragma("unroll") for (int k = 0; k < 2; ++k) dst[n][k] = *(const PG8_LAS bf16x8*)(lds + PG8_SB(b, h) + boff + n * 2048 + k * 1024); } while (0)
; #define PG8_MMA(ai, bj, At, Bt) do { __builtin_amdgcn_s_setprio(1); _Pragma("unroll") for (int m = 0; m < 4; ++m) _Pragma("unroll") for (int n = 0; n < 2; ++n) _Pragma("unroll") for (int k = 0; k < 2; ++k) \
;         acc[ai][bj][m][n] = __builtin_amdgcn_mfma_f32_16x16x32_bf16(Bt[n][k], At[m][k], acc[ai][bj][m][n], 0, 0, 0); __builtin_amdgcn_s_setprio(0); } while (0)
; #define PG8_WAIT_V(n) asm volatile("s_waitcnt vmcnt(" #n ")" ::: "memory")
; #define PG8_WAIT_L(n) asm volatile("s_waitcnt lgkmcnt(" #n ")" ::: "memory")
; #define PG8_BAR __builtin_amdgcn_s_barrier()
; #define PG8_SCHED __builtin_amdgcn_sched_barrier(0)
; template <class Epi, class Sched, bool ALIGN_EPI = false, bool SP2 = false>
; __device__ __forceinline__ void gemm_phase(PG8_LAS unsigned char* lds, const Gemm g, const Sched& S, const Epi& E) {
;     ...
;             PG8_LDA(At, 0, 1); PG8_STAGE(PG8_SB(0, 0), b2, voffB); PG8_STAGE(PG8_SB(0, 1), b2 + hstep, voffB); PG8_STAGE(PG8_SA(0, 0), a2, voffA);
;             PG8_WAIT_V(8); PG8_WAIT_L(0); PG8_BAR; PG8_MMA(1, 0, At, B0); PG8_MMA(1, 1, At, B1); PG8_BAR; PG8_SCHED;
;             PG8_LDB(B0, 1, 0); PG8_LDB(B1, 1, 1); PG8_SCHED; PG8_LDA(At, 1, 0); PG8_STAGE(PG8_SA(0, 1), a2 + hstep, voffA);
;             PG8_WAIT_V(8); PG8_WAIT_L(0); PG8_BAR; PG8_MMA(0, 0, At, B0); PG8_MMA(0, 1, At, B1); PG8_BAR; PG8_SCHED;
	v_mfma_f32_16x16x32_bf16 v[60:63], v[148:151], v[180:183], v[60:63]
	v_mfma_f32_16x16x32_bf16 v[56:59], v[156:159], v[180:183], v[56:59]
	v_mfma_f32_16x16x32_bf16 v[44:47], v[148:151], v[188:191], v[44:47]
	v_mfma_f32_16x16x32_bf16 v[40:43], v[156:159], v[188:191], v[40:43]
	v_mfma_f32_16x16x32_bf16 v[28:31], v[148:151], v[196:199], v[28:31]
	v_mfma_f32_16x16x32_bf16 v[24:27], v[156:159], v[196:199], v[24:27]
	v_mfma_f32_16x16x32_bf16 v[12:15], v[148:151], v[206:209], v[12:15]
	v_mfma_f32_16x16x32_bf16 v[8:11], v[156:159], v[206:209], v[8:11]
	v_mfma_f32_16x16x32_bf16 v[60:63], v[152:155], v[184:187], v[60:63]
	v_mfma_f32_16x16x32_bf16 v[56:59], v[160:163], v[184:187], v[56:59]
	v_mfma_f32_16x16x32_bf16 v[44:47], v[152:155], v[192:195], v[44:47]
	v_mfma_f32_16x16x32_bf16 v[40:43], v[160:163], v[192:195], v[40:43]
	v_mfma_f32_16x16x32_bf16 v[28:31], v[152:155], v[200:203], v[28:31]
	v_mfma_f32_16x16x32_bf16 v[24:27], v[160:163], v[200:203], v[24:27]
	v_mfma_f32_16x16x32_bf16 v[12:15], v[152:155], v[210:213], v[12:15]
	v_mfma_f32_16x16x32_bf16 v[8:11], v[160:163], v[210:213], v[8:11]
	v_mfma_f32_16x16x32_bf16 v[52:55], v[164:167], v[180:183], v[52:55]
	v_mfma_f32_16x16x32_bf16 v[48:51], v[172:175], v[180:183], v[48:51]
	v_mfma_f32_16x16x32_bf16 v[36:39], v[164:167], v[188:191], v[36:39]
	v_mfma_f32_16x16x32_bf16 v[32:35], v[172:175], v[188:191], v[32:35]
	v_mfma_f32_16x16x32_bf16 v[20:23], v[164:167], v[196:199], v[20:23]
	v_mfma_f32_16x16x32_bf16 v[16:19], v[172:175], v[196:199], v[16:19]
	v_mfma_f32_16x16x32_bf16 v[4:7], v[164:167], v[206:209], v[4:7]
	v_mfma_f32_16x16x32_bf16 v[0:3], v[172:175], v[206:209], v[0:3]
	v_mfma_f32_16x16x32_bf16 v[52:55], v[168:171], v[184:187], v[52:55]
	v_mfma_f32_16x16x32_bf16 v[48:51], v[176:179], v[184:187], v[48:51]
	v_mfma_f32_16x16x32_bf16 v[36:39], v[168:171], v[192:195], v[36:39]
	v_mfma_f32_16x16x32_bf16 v[32:35], v[176:179], v[192:195], v[32:35]
	v_mfma_f32_16x16x32_bf16 v[20:23], v[168:171], v[200:203], v[20:23]
	v_mfma_f32_16x16x32_bf16 v[16:19], v[176:179], v[200:203], v[16:19]
	v_mfma_f32_16x16x32_bf16 v[4:7], v[168:171], v[210:213], v[4:7]
	v_mfma_f32_16x16x32_bf16 v[0:3], v[176:179], v[210:213], v[0:3]
	s_setprio 0
	s_barrier
	s_add_i32 s52, 0, 0x18000
	s_add_i32 s53, 0, 0x1c000
	ds_read_b128 v[148:151], v242
	ds_read_b128 v[152:155], v242 offset:1024
	ds_read_b128 v[156:159], v242 offset:2048
	ds_read_b128 v[160:163], v242 offset:3072
	ds_read_b128 v[164:167], v243
	ds_read_b128 v[168:171], v243 offset:1024
	ds_read_b128 v[172:175], v243 offset:2048
	ds_read_b128 v[176:179], v243 offset:3072
	s_add_u32 s100, s34, 0x80
	s_addc_u32 s101, s35, 0
	s_add_u32 s34, s34, 0x100000
	s_addc_u32 s35, s35, 0
	s_mov_b32 m0, s38
	ds_read_b128 v[180:183], v147 offset:32768
	ds_read_b128 v[184:187], v147 offset:33792
	ds_read_b128 v[188:191], v147 offset:34816
	ds_read_b128 v[192:195], v147 offset:35840
	ds_read_b128 v[196:199], v147 offset:36864
	ds_read_b128 v[200:203], v147 offset:37888
	ds_read_b128 v[206:209], v147 offset:38912
	ds_read_b128 v[210:213], v147 offset:39936
	global_load_lds_dwordx4 v130, s[34:35]
	s_mov_b32 m0, s40
	s_nop 0
	global_load_lds_dwordx4 v132, s[34:35]
	s_waitcnt vmcnt(8)
	s_waitcnt lgkmcnt(0)
	s_setprio 1
	s_barrier
	v_mfma_f32_16x16x32_bf16 v[124:127], v[148:151], v[180:183], v[124:127]
	v_mfma_f32_16x16x32_bf16 v[120:123], v[156:159], v[180:183], v[120:123]
	v_mfma_f32_16x16x32_bf16 v[108:111], v[148:151], v[188:191], v[108:111]
	v_mfma_f32_16x16x32_bf16 v[104:107], v[156:159], v[188:191], v[104:107]
	v_mfma_f32_16x16x32_bf16 v[92:95], v[148:151], v[196:199], v[92:95]
	v_mfma_f32_16x16x32_bf16 v[88:91], v[156:159], v[196:199], v[88:91]
	v_mfma_f32_16x16x32_bf16 v[76:79], v[148:151], v[206:209], v[76:79]
	v_mfma_f32_16x16x32_bf16 v[72:75], v[156:159], v[206:209], v[72:75]
	v_mfma_f32_16x16x32_bf16 v[124:127], v[152:155], v[184:187], v[124:127]
	v_mfma_f32_16x16x32_bf16 v[120:123], v[160:163], v[184:187], v[120:123]
	v_mfma_f32_16x16x32_bf16 v[108:111], v[152:155], v[192:195], v[108:111]
	v_mfma_f32_16x16x32_bf16 v[104:107], v[160:163], v[192:195], v[104:107]
	v_mfma_f32_16x16x32_bf16 v[92:95], v[152:155], v[200:203], v[92:95]
	v_mfma_f32_16x16x32_bf16 v[88:91], v[160:163], v[200:203], v[88:91]
	v_mfma_f32_16x16x32_bf16 v[76:79], v[152:155], v[210:213], v[76:79]
	v_mfma_f32_16x16x32_bf16 v[72:75], v[160:163], v[210:213], v[72:75]
	v_mfma_f32_16x16x32_bf16 v[116:119], v[164:167], v[180:183], v[116:119]
	v_mfma_f32_16x16x32_bf16 v[112:115], v[172:175], v[180:183], v[112:115]
	v_mfma_f32_16x16x32_bf16 v[100:103], v[164:167], v[188:191], v[100:103]
	v_mfma_f32_16x16x32_bf16 v[96:99], v[172:175], v[188:191], v[96:99]
	v_mfma_f32_16x16x32_bf16 v[84:87], v[164:167], v[196:199], v[84:87]
	v_mfma_f32_16x16x32_bf16 v[80:83], v[172:175], v[196:199], v[80:83]
	v_mfma_f32_16x16x32_bf16 v[68:71], v[164:167], v[206:209], v[68:71]
	v_mfma_f32_16x16x32_bf16 v[64:67], v[172:175], v[206:209], v[64:67]
	v_mfma_f32_16x16x32_bf16 v[116:119], v[168:171], v[184:187], v[116:119]
	v_mfma_f32_16x16x32_bf16 v[112:115], v[176:179], v[184:187], v[112:115]
	v_mfma_f32_16x16x32_bf16 v[100:103], v[168:171], v[192:195], v[100:103]
	v_mfma_f32_16x16x32_bf16 v[96:99], v[176:179], v[192:195], v[96:99]
	v_mfma_f32_16x16x32_bf16 v[84:87], v[168:171], v[200:203], v[84:87]
	v_mfma_f32_16x16x32_bf16 v[80:83], v[176:179], v[200:203], v[80:83]
	v_mfma_f32_16x16x32_bf16 v[68:71], v[168:171], v[210:213], v[68:71]
	v_mfma_f32_16x16x32_bf16 v[64:67], v[176:179], v[210:213], v[64:67]
	s_setprio 0
	s_barrier
; #define PG8_STAGE(bufoff, gbase, voff) do { _Pragma("unroll") for (int _i = 0; _i < 2; ++_i) \
;         __builtin_amdgcn_global_load_lds((const unsigned*)((const char*)(gbase) + (voff)[_i]), (PG8_LAS unsigned*)(lds + (bufoff) + ldsw + _i * 8192), 16, 0, 0); } while (0)
; #define PG8_LDA(dst, b, h) do { _Pragma("unroll") for (int m = 0; m < 4; ++m) _Pragma("unroll") for (int k = 0; k < 2; ++k) dst[m][k] = *(const PG8_LAS bf16x8*)(lds + PG8_SA(b, h) + aoff + m * 2048 + k * 1024); } while (0)
; #define PG8_LDB(dst, b, h) do { _Pragma("unroll") for (int n = 0; n < 2; ++n) _Pragma("unroll") for (int k = 0; k < 2; ++k) dst[n][k] = *(const PG8_LAS bf16x8*)(lds + PG8_SB(b, h) + boff + n * 2048 + k * 1024); } while (0)
; #define PG8_MMA(ai, bj, At, Bt) do { __builtin_amdgcn_s_setprio(1); _Pragma("unroll") for (int m = 0; m < 4; ++m) _Pragma("unroll") for (int n = 0; n < 2; ++n) _Pragma("unroll") for (int k = 0; k < 2; ++k) \
;         acc[ai][bj][m][n] = __builtin_amdgcn_mfma_f32_16x16x32_bf16(Bt[n][k], At[m][k], acc[ai][bj][m][n], 0, 0, 0); __builtin_amdgcn_s_setprio(0); } while (0)
; #define PG8_WAIT_V(n) asm volatile("s_waitcnt vmcnt(" #n ")" ::: "memory")
; #define PG8_WAIT_L(n) asm volatile("s_waitcnt lgkmcnt(" #n ")" ::: "memory")
; #define PG8_BAR __builtin_amdgcn_s_barrier()
; #define PG8_SCHED __builtin_amdgcn_sched_barrier(0)
; template <class Epi, class Sched, bool ALIGN_EPI = false, bool SP2 = false>
; __device__ __forceinline__ void gemm_phase(PG8_LAS unsigned char* lds, const Gemm g, const Sched& S, const Epi& E) {
;     ...
;             PG8_LDB(B0, 1, 0); PG8_LDB(B1, 1, 1); PG8_SCHED; PG8_LDA(At, 1, 0); PG8_STAGE(PG8_SA(0, 1), a2 + hstep, voffA);
;             PG8_WAIT_V(8); PG8_WAIT_L(0); PG8_BAR; PG8_MMA(0, 0, At, B0); PG8_MMA(0, 1, At, B1); PG8_BAR; PG8_SCHED;
;             PG8_LDA(At, 1, 1); PG8_STAGE(PG8_SB(1, 0), b3, voffB); PG8_STAGE(PG8_SB(1, 1), b3 + hstep, voffB); PG8_STAGE(PG8_SA(1, 0), a3, voffA);
;             PG8_WAIT_V(8); PG8_WAIT_L(0); PG8_BAR; PG8_MMA(1, 0, At, B0); PG8_MMA(1, 1, At, B1); PG8_BAR; PG8_SCHED;
;     ...
; #pragma unroll
;         for (int a = 0; a < 2; ++a)
; #pragma unroll
;             for (int b = 0; b < 2; ++b)
; #pragma unroll
;                 for (int m = 0; m < 4; ++m)
; #pragma unroll
;                     for (int n = 0; n < 2; ++n) acc[a][b][m][n] = (f32x4){0.f, 0.f, 0.f, 0.f};
;         cur = nxt; cA = nA; cB = nB; ++ui;
	s_add_i32 s34, s52, s36
	s_mov_b32 m0, s34
	ds_read_b128 v[180:183], v147 offset:49152
	ds_read_b128 v[184:187], v147 offset:50176
	ds_read_b128 v[188:191], v147 offset:51200
	ds_read_b128 v[192:195], v147 offset:52224
	ds_read_b128 v[196:199], v147 offset:53248
	ds_read_b128 v[200:203], v147 offset:54272
	ds_read_b128 v[206:209], v147 offset:55296
	ds_read_b128 v[210:213], v147 offset:56320
	global_load_lds_dwordx4 v130, s[98:99]
	s_add_i32 m0, s34, 0x2000
	s_add_u32 s30, s30, 0x100080
	s_addc_u32 s31, s31, 0
	s_add_i32 s34, s53, s36
	global_load_lds_dwordx4 v132, s[98:99]
	s_mov_b32 m0, s34
	s_nop 0
	global_load_lds_dwordx4 v130, s[30:31]
	s_add_i32 m0, s34, 0x2000
	s_nop 0
	global_load_lds_dwordx4 v132, s[30:31]
	s_mov_b32 m0, s42
	s_nop 0
	global_load_lds_dwordx4 v130, s[100:101]
	s_mov_b32 m0, s43
	s_nop 0
	global_load_lds_dwordx4 v132, s[100:101]
	s_waitcnt vmcnt(8)
	s_waitcnt lgkmcnt(0)
	s_setprio 1
	s_barrier
	v_mfma_f32_16x16x32_bf16 v[60:63], v[148:151], v[180:183], v[60:63]
	v_mfma_f32_16x16x32_bf16 v[56:59], v[156:159], v[180:183], v[56:59]
	v_mfma_f32_16x16x32_bf16 v[44:47], v[148:151], v[188:191], v[44:47]
	v_mfma_f32_16x16x32_bf16 v[40:43], v[156:159], v[188:191], v[40:43]
	v_mfma_f32_16x16x32_bf16 v[28:31], v[148:151], v[196:199], v[28:31]
	v_mfma_f32_16x16x32_bf16 v[24:27], v[156:159], v[196:199], v[24:27]
	v_mfma_f32_16x16x32_bf16 v[12:15], v[148:151], v[206:209], v[12:15]
	v_mfma_f32_16x16x32_bf16 v[8:11], v[156:159], v[206:209], v[8:11]
	v_mfma_f32_16x16x32_bf16 v[60:63], v[152:155], v[184:187], v[60:63]
	v_mfma_f32_16x16x32_bf16 v[56:59], v[160:163], v[184:187], v[56:59]
	v_mfma_f32_16x16x32_bf16 v[44:47], v[152:155], v[192:195], v[44:47]
	v_mfma_f32_16x16x32_bf16 v[40:43], v[160:163], v[192:195], v[40:43]
	v_mfma_f32_16x16x32_bf16 v[28:31], v[152:155], v[200:203], v[28:31]
	v_mfma_f32_16x16x32_bf16 v[24:27], v[160:163], v[200:203], v[24:27]
	v_mfma_f32_16x16x32_bf16 v[12:15], v[152:155], v[210:213], v[12:15]
	v_mfma_f32_16x16x32_bf16 v[8:11], v[160:163], v[210:213], v[8:11]
	v_mfma_f32_16x16x32_bf16 v[52:55], v[164:167], v[180:183], v[52:55]
	v_mfma_f32_16x16x32_bf16 v[48:51], v[172:175], v[180:183], v[48:51]
	v_mfma_f32_16x16x32_bf16 v[36:39], v[164:167], v[188:191], v[36:39]
	v_mfma_f32_16x16x32_bf16 v[32:35], v[172:175], v[188:191], v[32:35]
	v_mfma_f32_16x16x32_bf16 v[20:23], v[164:167], v[196:199], v[20:23]
	v_mfma_f32_16x16x32_bf16 v[16:19], v[172:175], v[196:199], v[16:19]
	v_mfma_f32_16x16x32_bf16 v[4:7], v[164:167], v[206:209], v[4:7]
	v_mfma_f32_16x16x32_bf16 v[0:3], v[172:175], v[206:209], v[0:3]
	v_mfma_f32_16x16x32_bf16 v[52:55], v[168:171], v[184:187], v[52:55]
	v_mfma_f32_16x16x32_bf16 v[48:51], v[176:179], v[184:187], v[48:51]
	v_mfma_f32_16x16x32_bf16 v[36:39], v[168:171], v[192:195], v[36:39]
	v_mfma_f32_16x16x32_bf16 v[32:35], v[176:179], v[192:195], v[32:35]
	v_mfma_f32_16x16x32_bf16 v[20:23], v[168:171], v[200:203], v[20:23]
	v_mfma_f32_16x16x32_bf16 v[16:19], v[176:179], v[200:203], v[16:19]
	v_mfma_f32_16x16x32_bf16 v[4:7], v[168:171], v[210:213], v[4:7]
	v_mfma_f32_16x16x32_bf16 v[0:3], v[176:179], v[210:213], v[0:3]
	s_setprio 0
	s_barrier
	s_add_i32 s51, s51, 2
	s_add_u32 s28, s28, 0x100
	s_addc_u32 s29, s29, 0
	s_cmp_gt_u32 s51, 61
	s_cbranch_scc0 .LBB0_1025
	s_add_u32 s28, s25, 0xffffff00
	s_addc_u32 s29, s48, -1
	s_andn2_b64 vcc, exec, s[6:7]
	s_cbranch_vccnz .LBB0_1028
	v_mov_b32_e32 v0, 0
	s_mov_b32 s44, s18
	s_mov_b32 s10, s20
	s_mov_b64 s[12:13], s[26:27]
	s_mov_b32 s45, s24
	v_mov_b32_e32 v1, v0
	v_mov_b32_e32 v2, v0
	v_mov_b32_e32 v3, v0
	v_mov_b32_e32 v4, v0
	v_mov_b32_e32 v5, v0
	v_mov_b32_e32 v6, v0
	v_mov_b32_e32 v7, v0
	v_mov_b32_e32 v16, v0
	v_mov_b32_e32 v17, v0
	v_mov_b32_e32 v18, v0
	v_mov_b32_e32 v19, v0
	v_mov_b32_e32 v20, v0
	v_mov_b32_e32 v21, v0
	v_mov_b32_e32 v22, v0
	v_mov_b32_e32 v23, v0
	v_mov_b32_e32 v32, v0
	v_mov_b32_e32 v33, v0
	v_mov_b32_e32 v34, v0
	v_mov_b32_e32 v35, v0
	v_mov_b32_e32 v36, v0
	v_mov_b32_e32 v37, v0
	v_mov_b32_e32 v38, v0
	v_mov_b32_e32 v39, v0
	v_mov_b32_e32 v48, v0
	v_mov_b32_e32 v49, v0
	v_mov_b32_e32 v50, v0
	v_mov_b32_e32 v51, v0
	v_mov_b32_e32 v52, v0
	v_mov_b32_e32 v53, v0
	v_mov_b32_e32 v54, v0
	v_mov_b32_e32 v55, v0
	v_mov_b32_e32 v8, v0
	v_mov_b32_e32 v9, v0
	v_mov_b32_e32 v10, v0
	v_mov_b32_e32 v11, v0
	v_mov_b32_e32 v12, v0
	v_mov_b32_e32 v13, v0
	v_mov_b32_e32 v14, v0
	v_mov_b32_e32 v15, v0
	v_mov_b32_e32 v24, v0
	v_mov_b32_e32 v25, v0
	v_mov_b32_e32 v26, v0
	v_mov_b32_e32 v27, v0
	v_mov_b32_e32 v28, v0
	v_mov_b32_e32 v29, v0
	v_mov_b32_e32 v30, v0
	v_mov_b32_e32 v31, v0
	v_mov_b32_e32 v40, v0
	v_mov_b32_e32 v41, v0
	v_mov_b32_e32 v42, v0
	v_mov_b32_e32 v43, v0
	v_mov_b32_e32 v44, v0
	v_mov_b32_e32 v45, v0
	v_mov_b32_e32 v46, v0
	v_mov_b32_e32 v47, v0
	v_mov_b32_e32 v56, v0
	v_mov_b32_e32 v57, v0
	v_mov_b32_e32 v58, v0
	v_mov_b32_e32 v59, v0
	v_mov_b32_e32 v60, v0
	v_mov_b32_e32 v61, v0
	v_mov_b32_e32 v62, v0
	v_mov_b32_e32 v63, v0
	v_mov_b32_e32 v64, v0
	v_mov_b32_e32 v65, v0
	v_mov_b32_e32 v66, v0
	v_mov_b32_e32 v67, v0
	v_mov_b32_e32 v68, v0
	v_mov_b32_e32 v69, v0
	v_mov_b32_e32 v70, v0
	v_mov_b32_e32 v71, v0
	v_mov_b32_e32 v80, v0
	v_mov_b32_e32 v81, v0
	v_mov_b32_e32 v82, v0
	v_mov_b32_e32 v83, v0
	v_mov_b32_e32 v84, v0
	v_mov_b32_e32 v85, v0
	v_mov_b32_e32 v86, v0
	v_mov_b32_e32 v87, v0
	v_mov_b32_e32 v96, v0
	v_mov_b32_e32 v97, v0
	v_mov_b32_e32 v98, v0
	v_mov_b32_e32 v99, v0
	v_mov_b32_e32 v100, v0
	v_mov_b32_e32 v101, v0
	v_mov_b32_e32 v102, v0
	v_mov_b32_e32 v103, v0
	v_mov_b32_e32 v112, v0
	v_mov_b32_e32 v113, v0
	v_mov_b32_e32 v114, v0
	v_mov_b32_e32 v115, v0
	v_mov_b32_e32 v116, v0
	v_mov_b32_e32 v117, v0
	v_mov_b32_e32 v118, v0
	v_mov_b32_e32 v119, v0
	v_mov_b32_e32 v72, v0
	v_mov_b32_e32 v73, v0
	v_mov_b32_e32 v74, v0
	v_mov_b32_e32 v75, v0
	v_mov_b32_e32 v76, v0
	v_mov_b32_e32 v77, v0
	v_mov_b32_e32 v78, v0
	v_mov_b32_e32 v79, v0
	v_mov_b32_e32 v88, v0
	v_mov_b32_e32 v89, v0
	v_mov_b32_e32 v90, v0
	v_mov_b32_e32 v91, v0
	v_mov_b32_e32 v92, v0
	v_mov_b32_e32 v93, v0
	v_mov_b32_e32 v94, v0
	v_mov_b32_e32 v95, v0
	v_mov_b32_e32 v104, v0
	v_mov_b32_e32 v105, v0
	v_mov_b32_e32 v106, v0
	v_mov_b32_e32 v107, v0
	v_mov_b32_e32 v108, v0
	v_mov_b32_e32 v109, v0
	v_mov_b32_e32 v110, v0
	v_mov_b32_e32 v111, v0
	v_mov_b32_e32 v120, v0
	v_mov_b32_e32 v121, v0
	v_mov_b32_e32 v122, v0
	v_mov_b32_e32 v123, v0
	v_mov_b32_e32 v124, v0
	v_mov_b32_e32 v125, v0
	v_mov_b32_e32 v126, v0
	v_mov_b32_e32 v127, v0
	s_andn2_b64 vcc, exec, s[0:1]
	s_cbranch_vccnz .LBB0_1029
	s_branch .LBB0_1030

; #define LAS __attribute__((address_space(3)))
; __global__ void __launch_bounds__(512, 2) fwd_mega(Args a) {
;     extern __shared__ __attribute__((aligned(16))) unsigned char lds_raw[];
;     LAS unsigned char* lds = (LAS unsigned char*)lds_raw;
;     cg::grid_group grid = cg::this_grid();
;     const int tid = threadIdx.x, lane = tid & 63, wave = __builtin_amdgcn_readfirstlane(tid >> 6);
;     const int G = gridDim.x, bid = blockIdx.x;
;     const int lo = a.ph_lo, hi = a.ph_hi;
	.amdhsa_kernel _Z8fwd_mega4Args
		.amdhsa_group_segment_fixed_size 0
		.amdhsa_private_segment_fixed_size 0
		.amdhsa_kernarg_size 464
		.amdhsa_user_sgpr_count 2
		.amdhsa_user_sgpr_dispatch_ptr 0
		.amdhsa_user_sgpr_queue_ptr 0
		.amdhsa_user_sgpr_kernarg_segment_ptr 1
		.amdhsa_user_sgpr_dispatch_id 0
		.amdhsa_user_sgpr_kernarg_preload_length 0
		.amdhsa_user_sgpr_kernarg_preload_offset 0
		.amdhsa_user_sgpr_private_segment_size 0
		.amdhsa_uses_dynamic_stack 0
		.amdhsa_enable_private_segment 0
		.amdhsa_system_sgpr_workgroup_id_x 1
		.amdhsa_system_sgpr_workgroup_id_y 0
		.amdhsa_system_sgpr_workgroup_id_z 0
		.amdhsa_system_sgpr_workgroup_info 0
		.amdhsa_system_vgpr_workitem_id 2
		.amdhsa_next_free_vgpr 256
		.amdhsa_next_free_sgpr 102
		.amdhsa_accum_offset 256
		.amdhsa_reserve_vcc 1
		.amdhsa_float_round_mode_32 0
		.amdhsa_float_round_mode_16_64 0
		.amdhsa_float_denorm_mode_32 3
		.amdhsa_float_denorm_mode_16_64 3
		.amdhsa_dx10_clamp 1
		.amdhsa_ieee_mode 1
		.amdhsa_fp16_overflow 0
		.amdhsa_tg_split 0
		.amdhsa_exception_fp_ieee_invalid_op 0
		.amdhsa_exception_fp_denorm_src 0
		.amdhsa_exception_fp_ieee_div_zero 0
		.amdhsa_exception_fp_ieee_overflow 0
		.amdhsa_exception_fp_ieee_underflow 0
		.amdhsa_exception_fp_ieee_inexact 0
		.amdhsa_exception_int_div_zero 0
	.end_amdhsa_kernel

; #define LAS __attribute__((address_space(3)))
; __global__ void __launch_bounds__(512, 2) fwd_mega(Args a) {
;     extern __shared__ __attribute__((aligned(16))) unsigned char lds_raw[];
;     LAS unsigned char* lds = (LAS unsigned char*)lds_raw;
;     cg::grid_group grid = cg::this_grid();
;     const int tid = threadIdx.x, lane = tid & 63, wave = __builtin_amdgcn_readfirstlane(tid >> 6);
;     const int G = gridDim.x, bid = blockIdx.x;
;     const int lo = a.ph_lo, hi = a.ph_hi;
amdhsa.kernels:
  - .agpr_count:     0
    .args:
      - .offset:         0
        .size:           208
        .value_kind:     by_value
      - .offset:         208
        .size:           4
        .value_kind:     hidden_block_count_x
      - .offset:         212
        .size:           4
        .value_kind:     hidden_block_count_y
      - .offset:         216
        .size:           4
        .value_kind:     hidden_block_count_z
      - .offset:         220
        .size:           2
        .value_kind:     hidden_group_size_x
      - .offset:         222
        .size:           2
        .value_kind:     hidden_group_size_y
      - .offset:         224
        .size:           2
        .value_kind:     hidden_group_size_z
      - .offset:         226
        .size:           2
        .value_kind:     hidden_remainder_x
      - .offset:         228
        .size:           2
        .value_kind:     hidden_remainder_y
      - .offset:         230
        .size:           2
        .value_kind:     hidden_remainder_z
      - .offset:         248
        .size:           8
        .value_kind:     hidden_global_offset_x
      - .offset:         256
        .size:           8
        .value_kind:     hidden_global_offset_y
      - .offset:         264
        .size:           8
        .value_kind:     hidden_global_offset_z
      - .offset:         272
        .size:           2
        .value_kind:     hidden_grid_dims
      - .offset:         296
        .size:           8
        .value_kind:     hidden_multigrid_sync_arg
      - .offset:         328
        .size:           4
        .value_kind:     hidden_dynamic_lds_size
    .group_segment_fixed_size: 0
    .kernarg_segment_align: 8
    .kernarg_segment_size: 464
    .language:       OpenCL C
    .language_version:
      - 2
      - 0
    .max_flat_workgroup_size: 512
    .name:           _Z8fwd_mega4Args
    .private_segment_fixed_size: 0
    .sgpr_count:     108
    .sgpr_spill_count: 63
    .symbol:         _Z8fwd_mega4Args.kd
    .uniform_work_group_size: 1
    .uses_dynamic_stack: false
    .vgpr_count:     256
    .vgpr_spill_count: 0
    .wavefront_size: 64
